# GEMM-unit and score-loop accumulator clears: one v_mov_b64 per aligned register pair instead of two v_mov_b32
# baseline (speedup 1.0000x reference)
; template <class Epi, class Sched, bool ALIGN_EPI = false, bool SP2 = false, bool F8 = false>
; __device__ __forceinline__ void gemm_phase(PG8_LAS unsigned char* lds, const Gemm g, const Sched& S, const Epi& E, int wv) {
;     ...
;     for (;;) {
;         const bool has_next = S.next(ui + 1, nxt);
;         const char* nA = has_next ? (const char*)g.A + (size_t)nxt.pm * tstepA : cA; const char* nB = has_next ? (const char*)g.Bt + (size_t)nxt.pn * tstepB : cB;
;         for (int t = 0; t < nt; t += 2) {
;             if constexpr (Epi::MIDK) { if (t == nt / 2) { if constexpr (F8) asm volatile("s_nop 15\n\ts_nop 15" ::: "memory"); E.mid(acc, cur, wr, wc, fr, fq); } }
;             const bool last = (t == nt - 2);
;             const char* a1 = cA + (size_t)(t + 1) * kstep;
;             const char* a2 = last ? nA : cA + (size_t)(t + 2) * kstep; const char* b2 = last ? nB : cB + (size_t)(t + 2) * kstep;
;     ...
; #pragma unroll
;         for (int a = 0; a < 2; ++a)
; #pragma unroll
;             for (int b = 0; b < 2; ++b)
; #pragma unroll
;                 for (int m = 0; m < 4; ++m)
; #pragma unroll
;                     for (int n = 0; n < 2; ++n) acc[a][b][m][n] = (f32x4){0.f, 0.f, 0.f, 0.f};
.LBB0_238:
	s_ashr_i32 s15, s14, 31
	s_lshl_b64 s[16:17], s[14:15], 20
	s_add_u32 s16, s3, s16
	s_addc_u32 s17, s26, s17
	s_and_b64 s[18:19], s[0:1], exec
	s_cselect_b32 s15, s17, s21
	s_cselect_b32 s57, s16, s20
	s_ashr_i32 s13, s12, 31
	s_lshl_b64 s[18:19], s[12:13], 20
	s_add_u32 s18, s27, s18
	s_addc_u32 s19, s28, s19
	s_and_b64 s[24:25], s[0:1], exec
	s_cselect_b32 s13, s19, s23
	s_cselect_b32 s58, s18, s22
	s_add_u32 s20, s20, 0x80080
	s_addc_u32 s21, s21, 0
	s_add_u32 s59, s22, 0x100
	v_mov_b64_e32 v[0:1], 0
	s_addc_u32 s60, s23, 0
	s_mov_b32 s61, -2
	v_mov_b64_e32 v[2:3], 0
	v_mov_b64_e32 v[4:5], 0
	v_mov_b64_e32 v[6:7], 0
	v_mov_b64_e32 v[8:9], 0
	v_mov_b64_e32 v[10:11], 0
	v_mov_b64_e32 v[16:17], 0
	v_mov_b64_e32 v[18:19], 0
	v_mov_b64_e32 v[24:25], 0
	v_mov_b64_e32 v[26:27], 0
	v_mov_b64_e32 v[32:33], 0
	v_mov_b64_e32 v[34:35], 0
	v_mov_b64_e32 v[40:41], 0
	v_mov_b64_e32 v[42:43], 0
	v_mov_b64_e32 v[48:49], 0
	v_mov_b64_e32 v[50:51], 0
	v_mov_b64_e32 v[12:13], 0
	v_mov_b64_e32 v[14:15], 0
	v_mov_b64_e32 v[20:21], 0
	v_mov_b64_e32 v[22:23], 0
	v_mov_b64_e32 v[28:29], 0
	v_mov_b64_e32 v[30:31], 0
	v_mov_b64_e32 v[36:37], 0
	v_mov_b64_e32 v[38:39], 0
	v_mov_b64_e32 v[44:45], 0
	v_mov_b64_e32 v[46:47], 0
	v_mov_b64_e32 v[52:53], 0
	v_mov_b64_e32 v[54:55], 0
	v_mov_b64_e32 v[56:57], 0
	v_mov_b64_e32 v[58:59], 0
	v_mov_b64_e32 v[60:61], 0
	v_mov_b64_e32 v[62:63], 0
	v_mov_b64_e32 v[64:65], 0
	v_mov_b64_e32 v[66:67], 0
	v_mov_b64_e32 v[68:69], 0
	v_mov_b64_e32 v[70:71], 0
	v_mov_b64_e32 v[72:73], 0
	v_mov_b64_e32 v[74:75], 0
	v_mov_b64_e32 v[80:81], 0
	v_mov_b64_e32 v[82:83], 0
	v_mov_b64_e32 v[88:89], 0
	v_mov_b64_e32 v[90:91], 0
	v_mov_b64_e32 v[96:97], 0
	v_mov_b64_e32 v[98:99], 0
	v_mov_b64_e32 v[104:105], 0
	v_mov_b64_e32 v[106:107], 0
	v_mov_b64_e32 v[112:113], 0
	v_mov_b64_e32 v[114:115], 0
	v_mov_b64_e32 v[76:77], 0
	v_mov_b64_e32 v[78:79], 0
	v_mov_b64_e32 v[84:85], 0
	v_mov_b64_e32 v[86:87], 0
	v_mov_b64_e32 v[92:93], 0
	v_mov_b64_e32 v[94:95], 0
	v_mov_b64_e32 v[100:101], 0
	v_mov_b64_e32 v[102:103], 0
	v_mov_b64_e32 v[108:109], 0
	v_mov_b64_e32 v[110:111], 0
	v_mov_b64_e32 v[116:117], 0
	v_mov_b64_e32 v[118:119], 0
	v_mov_b64_e32 v[120:121], 0
	v_mov_b64_e32 v[122:123], 0
	v_mov_b64_e32 v[124:125], 0
	v_mov_b64_e32 v[126:127], 0

; template <class Epi, class Sched, bool ALIGN_EPI = false, bool SP2 = false, bool F8 = false>
; __device__ __forceinline__ void gemm_phase(PG8_LAS unsigned char* lds, const Gemm g, const Sched& S, const Epi& E, int wv) {
;     ...
;     for (;;) {
;         const bool has_next = S.next(ui + 1, nxt);
;         const char* nA = has_next ? (const char*)g.A + (size_t)nxt.pm * tstepA : cA; const char* nB = has_next ? (const char*)g.Bt + (size_t)nxt.pn * tstepB : cB;
;         for (int t = 0; t < nt; t += 2) {
;             if constexpr (Epi::MIDK) { if (t == nt / 2) { if constexpr (F8) asm volatile("s_nop 15\n\ts_nop 15" ::: "memory"); E.mid(acc, cur, wr, wc, fr, fq); } }
;             const bool last = (t == nt - 2);
;             const char* a1 = cA + (size_t)(t + 1) * kstep;
;             const char* a2 = last ? nA : cA + (size_t)(t + 2) * kstep; const char* b2 = last ? nB : cB + (size_t)(t + 2) * kstep;
;     ...
; #pragma unroll
;         for (int a = 0; a < 2; ++a)
; #pragma unroll
;             for (int b = 0; b < 2; ++b)
; #pragma unroll
;                 for (int m = 0; m < 4; ++m)
; #pragma unroll
;                     for (int n = 0; n < 2; ++n) acc[a][b][m][n] = (f32x4){0.f, 0.f, 0.f, 0.f};
.LBB0_285:
	s_mov_b32 s16, s13
	s_ashr_i32 s17, s13, 31
	s_lshl_b64 s[22:23], s[16:17], 19
	s_add_u32 s22, s36, s22
	s_addc_u32 s23, s37, s23
	s_and_b64 s[24:25], s[20:21], exec
	s_mov_b32 s14, s15
	s_cselect_b32 s13, s23, s27
	s_cselect_b32 s17, s22, s26
	s_ashr_i32 s15, s15, 31
	s_lshl_b64 s[24:25], s[14:15], 19
	s_add_u32 s24, s38, s24
	s_addc_u32 s25, s39, s25
	s_and_b64 s[30:31], s[20:21], exec
	s_cselect_b32 s15, s25, s29
	s_cselect_b32 s67, s24, s28
	s_add_u32 s26, s26, 0x40080
	s_addc_u32 s27, s27, 0
	s_add_u32 s69, s28, 0x100
	v_mov_b64_e32 v[32:33], 0
	s_addc_u32 s70, s29, 0
	s_mov_b32 s71, -2
	v_mov_b64_e32 v[34:35], 0
	v_mov_b64_e32 v[36:37], 0
	v_mov_b64_e32 v[38:39], 0
	v_mov_b64_e32 v[44:45], 0
	v_mov_b64_e32 v[46:47], 0
	v_mov_b64_e32 v[52:53], 0
	v_mov_b64_e32 v[54:55], 0
	v_mov_b64_e32 v[60:61], 0
	v_mov_b64_e32 v[62:63], 0
	v_mov_b64_e32 v[68:69], 0
	v_mov_b64_e32 v[70:71], 0
	v_mov_b64_e32 v[76:77], 0
	v_mov_b64_e32 v[78:79], 0
	v_mov_b64_e32 v[84:85], 0
	v_mov_b64_e32 v[86:87], 0
	v_mov_b64_e32 v[40:41], 0
	v_mov_b64_e32 v[42:43], 0
	v_mov_b64_e32 v[48:49], 0
	v_mov_b64_e32 v[50:51], 0
	v_mov_b64_e32 v[56:57], 0
	v_mov_b64_e32 v[58:59], 0
	v_mov_b64_e32 v[64:65], 0
	v_mov_b64_e32 v[66:67], 0
	v_mov_b64_e32 v[72:73], 0
	v_mov_b64_e32 v[74:75], 0
	v_mov_b64_e32 v[80:81], 0
	v_mov_b64_e32 v[82:83], 0
	v_mov_b64_e32 v[88:89], 0
	v_mov_b64_e32 v[90:91], 0
	v_mov_b64_e32 v[92:93], 0
	v_mov_b64_e32 v[94:95], 0
	v_mov_b64_e32 v[96:97], 0
	v_mov_b64_e32 v[98:99], 0
	v_mov_b64_e32 v[100:101], 0
	v_mov_b64_e32 v[102:103], 0
	v_mov_b64_e32 v[108:109], 0
	v_mov_b64_e32 v[110:111], 0
	v_mov_b64_e32 v[116:117], 0
	v_mov_b64_e32 v[118:119], 0
	v_mov_b64_e32 v[124:125], 0
	v_mov_b64_e32 v[126:127], 0
	v_mov_b64_e32 v[134:135], 0
	v_mov_b64_e32 v[136:137], 0
	v_mov_b64_e32 v[142:143], 0
	v_mov_b64_e32 v[144:145], 0
	v_mov_b64_e32 v[150:151], 0
	v_mov_b64_e32 v[152:153], 0
	v_mov_b64_e32 v[104:105], 0
	v_mov_b64_e32 v[106:107], 0
	v_mov_b64_e32 v[112:113], 0
	v_mov_b64_e32 v[114:115], 0
	v_mov_b64_e32 v[120:121], 0
	v_mov_b64_e32 v[122:123], 0
	v_mov_b64_e32 v[130:131], 0
	v_mov_b64_e32 v[132:133], 0
	v_mov_b64_e32 v[138:139], 0
	v_mov_b64_e32 v[140:141], 0
	v_mov_b64_e32 v[146:147], 0
	v_mov_b64_e32 v[148:149], 0
	v_mov_b64_e32 v[154:155], 0
	v_mov_b64_e32 v[156:157], 0
	v_mov_b64_e32 v[158:159], 0
	v_mov_b64_e32 v[160:161], 0

; template <class Epi, class Sched, bool ALIGN_EPI = false, bool SP2 = false, bool F8 = false>
; __device__ __forceinline__ void gemm_phase(PG8_LAS unsigned char* lds, const Gemm g, const Sched& S, const Epi& E, int wv) {
;     ...
;     for (;;) {
;         const bool has_next = S.next(ui + 1, nxt);
;         const char* nA = has_next ? (const char*)g.A + (size_t)nxt.pm * tstepA : cA; const char* nB = has_next ? (const char*)g.Bt + (size_t)nxt.pn * tstepB : cB;
;         for (int t = 0; t < nt; t += 2) {
;             if constexpr (Epi::MIDK) { if (t == nt / 2) { if constexpr (F8) asm volatile("s_nop 15\n\ts_nop 15" ::: "memory"); E.mid(acc, cur, wr, wc, fr, fq); } }
;             const bool last = (t == nt - 2);
;             const char* a1 = cA + (size_t)(t + 1) * kstep;
;             const char* a2 = last ? nA : cA + (size_t)(t + 2) * kstep; const char* b2 = last ? nB : cB + (size_t)(t + 2) * kstep;
;     ...
; #pragma unroll
;         for (int a = 0; a < 2; ++a)
; #pragma unroll
;             for (int b = 0; b < 2; ++b)
; #pragma unroll
;                 for (int m = 0; m < 4; ++m)
; #pragma unroll
;                     for (int n = 0; n < 2; ++n) acc[a][b][m][n] = (f32x4){0.f, 0.f, 0.f, 0.f};
.LBB0_710:
	s_ashr_i32 s9, s8, 31
	s_lshl_b64 s[10:11], s[8:9], 19
	s_add_u32 s10, s24, s10
	s_addc_u32 s11, s25, s11
	s_and_b64 s[12:13], s[36:37], exec
	s_cselect_b32 s9, s11, s19
	s_cselect_b32 s15, s10, s18
	s_ashr_i32 s7, s6, 31
	s_lshl_b64 s[12:13], s[6:7], 19
	s_add_u32 s12, s26, s12
	s_addc_u32 s13, s27, s13
	s_and_b64 s[22:23], s[36:37], exec
	s_cselect_b32 s7, s13, s21
	s_cselect_b32 s58, s12, s20
	s_add_u32 s18, s18, 0x40080
	s_addc_u32 s19, s19, 0
	s_add_u32 s59, s20, 0x100
	v_mov_b64_e32 v[32:33], 0
	s_addc_u32 s60, s21, 0
	s_mov_b32 s61, -2
	v_mov_b64_e32 v[34:35], 0
	v_mov_b64_e32 v[36:37], 0
	v_mov_b64_e32 v[38:39], 0
	v_mov_b64_e32 v[44:45], 0
	v_mov_b64_e32 v[46:47], 0
	v_mov_b64_e32 v[52:53], 0
	v_mov_b64_e32 v[54:55], 0
	v_mov_b64_e32 v[60:61], 0
	v_mov_b64_e32 v[62:63], 0
	v_mov_b64_e32 v[68:69], 0
	v_mov_b64_e32 v[70:71], 0
	v_mov_b64_e32 v[76:77], 0
	v_mov_b64_e32 v[78:79], 0
	v_mov_b64_e32 v[84:85], 0
	v_mov_b64_e32 v[86:87], 0
	v_mov_b64_e32 v[40:41], 0
	v_mov_b64_e32 v[42:43], 0
	v_mov_b64_e32 v[48:49], 0
	v_mov_b64_e32 v[50:51], 0
	v_mov_b64_e32 v[56:57], 0
	v_mov_b64_e32 v[58:59], 0
	v_mov_b64_e32 v[64:65], 0
	v_mov_b64_e32 v[66:67], 0
	v_mov_b64_e32 v[72:73], 0
	v_mov_b64_e32 v[74:75], 0
	v_mov_b64_e32 v[80:81], 0
	v_mov_b64_e32 v[82:83], 0
	v_mov_b64_e32 v[88:89], 0
	v_mov_b64_e32 v[90:91], 0
	v_mov_b64_e32 v[92:93], 0
	v_mov_b64_e32 v[94:95], 0
	v_mov_b64_e32 v[96:97], 0
	v_mov_b64_e32 v[98:99], 0
	v_mov_b64_e32 v[100:101], 0
	v_mov_b64_e32 v[102:103], 0
	v_mov_b64_e32 v[108:109], 0
	v_mov_b64_e32 v[110:111], 0
	v_mov_b64_e32 v[116:117], 0
	v_mov_b64_e32 v[118:119], 0
	v_mov_b64_e32 v[124:125], 0
	v_mov_b64_e32 v[126:127], 0
	v_mov_b64_e32 v[134:135], 0
	v_mov_b64_e32 v[136:137], 0
	v_mov_b64_e32 v[142:143], 0
	v_mov_b64_e32 v[144:145], 0
	v_mov_b64_e32 v[150:151], 0
	v_mov_b64_e32 v[152:153], 0
	v_mov_b64_e32 v[104:105], 0
	v_mov_b64_e32 v[106:107], 0
	v_mov_b64_e32 v[112:113], 0
	v_mov_b64_e32 v[114:115], 0
	v_mov_b64_e32 v[120:121], 0
	v_mov_b64_e32 v[122:123], 0
	v_mov_b64_e32 v[130:131], 0
	v_mov_b64_e32 v[132:133], 0
	v_mov_b64_e32 v[138:139], 0
	v_mov_b64_e32 v[140:141], 0
	v_mov_b64_e32 v[146:147], 0
	v_mov_b64_e32 v[148:149], 0
	v_mov_b64_e32 v[154:155], 0
	v_mov_b64_e32 v[156:157], 0
	v_mov_b64_e32 v[158:159], 0
	v_mov_b64_e32 v[160:161], 0

; template <class Epi, class Sched, bool ALIGN_EPI = false, bool SP2 = false, bool F8 = false>
; __device__ __forceinline__ void gemm_phase(PG8_LAS unsigned char* lds, const Gemm g, const Sched& S, const Epi& E, int wv) {
;     ...
;         const bool has_next = S.next(ui + 1, nxt);
;         const char* nA = has_next ? (const char*)g.A + (size_t)nxt.pm * tstepA : cA; const char* nB = has_next ? (const char*)g.Bt + (size_t)nxt.pn * tstepB : cB;
;     ...
; #pragma unroll
;         for (int a = 0; a < 2; ++a)
; #pragma unroll
;             for (int b = 0; b < 2; ++b)
; #pragma unroll
;                 for (int m = 0; m < 4; ++m)
; #pragma unroll
;                     for (int n = 0; n < 2; ++n) acc[a][b][m][n] = (f32x4){0.f, 0.f, 0.f, 0.f};
;         cur = nxt; cA = nA; cB = nB; ++ui;
.LBB0_845:
	s_ashr_i32 s11, s10, 31
	s_lshl_b64 s[16:17], s[10:11], 20
	s_add_u32 s16, s26, s16
	s_addc_u32 s17, s27, s17
	s_and_b64 s[18:19], s[0:1], exec
	s_cselect_b32 s11, s17, s21
	s_cselect_b32 s57, s16, s20
	s_ashr_i32 s9, s8, 31
	s_lshl_b64 s[18:19], s[8:9], 20
	s_add_u32 s18, s28, s18
	s_addc_u32 s19, s29, s19
	s_and_b64 s[24:25], s[0:1], exec
	s_cselect_b32 s9, s19, s23
	s_cselect_b32 s58, s18, s22
	s_add_u32 s20, s20, 0x80080
	s_addc_u32 s21, s21, 0
	s_add_u32 s59, s22, 0x100
	v_mov_b64_e32 v[0:1], 0
	s_addc_u32 s60, s23, 0
	s_mov_b32 s61, -2
	v_mov_b64_e32 v[2:3], 0
	v_mov_b64_e32 v[4:5], 0
	v_mov_b64_e32 v[6:7], 0
	v_mov_b64_e32 v[8:9], 0
	v_mov_b64_e32 v[10:11], 0
	v_mov_b64_e32 v[16:17], 0
	v_mov_b64_e32 v[18:19], 0
	v_mov_b64_e32 v[24:25], 0
	v_mov_b64_e32 v[26:27], 0
	v_mov_b64_e32 v[32:33], 0
	v_mov_b64_e32 v[34:35], 0
	v_mov_b64_e32 v[40:41], 0
	v_mov_b64_e32 v[42:43], 0
	v_mov_b64_e32 v[48:49], 0
	v_mov_b64_e32 v[50:51], 0
	v_mov_b64_e32 v[12:13], 0
	v_mov_b64_e32 v[14:15], 0
	v_mov_b64_e32 v[20:21], 0
	v_mov_b64_e32 v[22:23], 0
	v_mov_b64_e32 v[28:29], 0
	v_mov_b64_e32 v[30:31], 0
	v_mov_b64_e32 v[36:37], 0
	v_mov_b64_e32 v[38:39], 0
	v_mov_b64_e32 v[44:45], 0
	v_mov_b64_e32 v[46:47], 0
	v_mov_b64_e32 v[52:53], 0
	v_mov_b64_e32 v[54:55], 0
	v_mov_b64_e32 v[56:57], 0
	v_mov_b64_e32 v[58:59], 0
	v_mov_b64_e32 v[60:61], 0
	v_mov_b64_e32 v[62:63], 0
	v_mov_b64_e32 v[64:65], 0
	v_mov_b64_e32 v[66:67], 0
	v_mov_b64_e32 v[68:69], 0
	v_mov_b64_e32 v[70:71], 0
	v_mov_b64_e32 v[72:73], 0
	v_mov_b64_e32 v[74:75], 0
	v_mov_b64_e32 v[80:81], 0
	v_mov_b64_e32 v[82:83], 0
	v_mov_b64_e32 v[88:89], 0
	v_mov_b64_e32 v[90:91], 0
	v_mov_b64_e32 v[96:97], 0
	v_mov_b64_e32 v[98:99], 0
	v_mov_b64_e32 v[104:105], 0
	v_mov_b64_e32 v[106:107], 0
	v_mov_b64_e32 v[112:113], 0
	v_mov_b64_e32 v[114:115], 0
	v_mov_b64_e32 v[76:77], 0
	v_mov_b64_e32 v[78:79], 0
	v_mov_b64_e32 v[84:85], 0
	v_mov_b64_e32 v[86:87], 0
	v_mov_b64_e32 v[92:93], 0
	v_mov_b64_e32 v[94:95], 0
	v_mov_b64_e32 v[100:101], 0
	v_mov_b64_e32 v[102:103], 0
	v_mov_b64_e32 v[108:109], 0
	v_mov_b64_e32 v[110:111], 0
	v_mov_b64_e32 v[116:117], 0
	v_mov_b64_e32 v[118:119], 0
	v_mov_b64_e32 v[120:121], 0
	v_mov_b64_e32 v[122:123], 0
	v_mov_b64_e32 v[124:125], 0
	v_mov_b64_e32 v[126:127], 0

; DI void route_block(const Frame& F, int t0, int t1) {
;     ...
;     for (int item = F.wave; item < ntile * NH; item += NWAVES) {
;         const int tile = item >> 3, h = item & 7;
;         const int tl = tile * 32 + r32; const bool valid = t0 + tl < t1;
;         const int tok = valid ? t0 + tl : t1 - 1;
;         float tv[2][16];
; #pragma unroll
;         for (int p = 0; p < 2; ++p) {
;             f32x16 acc[4];
; #pragma unroll
;             for (int kb = 0; kb < 4; ++kb)
; #pragma unroll
;                 for (int i = 0; i < 16; ++i) acc[kb][i] = 0.f;
;             const bf16* qp = F.Y + (size_t)tok * D + (h * 2 + p) * 128 + 8 * hh;
;             const bf16* kp = F.Keys + ((size_t)((h * 2 + p) * 128) + r32) * 128 + 8 * hh;
; #pragma unroll 4
;             for (int ks = 0; ks < 8; ++ks) {
;                 const bf16x8v bq = *(const bf16x8v*)(qp + ks * 16);
; #pragma unroll
;                 for (int kb = 0; kb < 4; ++kb) { const bf16x8v ak = *(const bf16x8v*)(kp + (size_t)kb * 32 * 128 + ks * 16);
;                     acc[kb] = __builtin_amdgcn_mfma_f32_32x32x16_bf16(ak, bq, acc[kb], 0, 0, 0); }
;             }
.LBB0_912:
	s_and_b32 s8, s1, 0xffffffe0
	v_add_u32_e32 v0, s8, v145
	v_ashrrev_i32_e32 v1, 31, v0
	v_mov_b32_e32 v2, s3
	v_cmp_gt_i64_e32 vcc, s[2:3], v[0:1]
	s_mov_b64 s[8:9], 0
	s_mov_b32 s10, 0x4a06000
	v_cndmask_b32_e32 v1, v2, v1, vcc
	v_mov_b32_e32 v2, s2
	v_cndmask_b32_e32 v0, v2, v0, vcc
	v_lshlrev_b64 v[72:73], 12, v[0:1]
	v_mov_b64_e32 v[0:1], 0
	v_lshl_add_u64 v[74:75], v[66:67], 0, v[72:73]
	v_mov_b64_e32 v[2:3], 0
	v_mov_b64_e32 v[4:5], 0
	v_mov_b64_e32 v[6:7], 0
	v_mov_b64_e32 v[8:9], 0
	v_mov_b64_e32 v[10:11], 0
	v_mov_b64_e32 v[12:13], 0
	v_mov_b64_e32 v[14:15], 0
	v_mov_b64_e32 v[32:33], 0
	v_mov_b64_e32 v[34:35], 0
	v_mov_b64_e32 v[36:37], 0
	v_mov_b64_e32 v[38:39], 0
	v_mov_b64_e32 v[40:41], 0
	v_mov_b64_e32 v[42:43], 0
	v_mov_b64_e32 v[44:45], 0
	v_mov_b64_e32 v[46:47], 0
	v_mov_b64_e32 v[48:49], 0
	v_mov_b64_e32 v[50:51], 0
	v_mov_b64_e32 v[52:53], 0
	v_mov_b64_e32 v[54:55], 0
	v_mov_b64_e32 v[56:57], 0
	v_mov_b64_e32 v[58:59], 0
	v_mov_b64_e32 v[60:61], 0
	v_mov_b64_e32 v[62:63], 0
	v_mov_b64_e32 v[16:17], 0
	v_mov_b64_e32 v[18:19], 0
	v_mov_b64_e32 v[20:21], 0
	v_mov_b64_e32 v[22:23], 0
	v_mov_b64_e32 v[24:25], 0
	v_mov_b64_e32 v[26:27], 0
	v_mov_b64_e32 v[28:29], 0
	v_mov_b64_e32 v[30:31], 0
	v_add_co_u32_e32 v158, vcc, s15, v64
	s_nop 1
	v_addc_co_u32_e32 v159, vcc, 0, v65, vcc
	v_add_co_u32_e32 v160, vcc, s16, v64
	s_nop 1
	v_addc_co_u32_e32 v161, vcc, 0, v65, vcc
	v_add_co_u32_e32 v162, vcc, s17, v64
	s_nop 1
	v_addc_co_u32_e32 v163, vcc, 0, v65, vcc
	v_add_co_u32_e32 v156, vcc, s10, v64
	s_nop 1
	v_addc_co_u32_e32 v157, vcc, 0, v65, vcc
	global_load_dwordx4 v[146:149], v[74:75], off offset:-64
	global_load_dwordx4 v[194:197], v[158:159], off offset:-4096
	global_load_dwordx4 v[198:201], v[160:161], off offset:-4096
	global_load_dwordx4 v[202:205], v[162:163], off offset:-4096
	global_load_dwordx4 v[208:211], v[156:157], off offset:-4096
	global_load_dwordx4 v[150:153], v[74:75], off offset:-32
	global_load_dwordx4 v[214:217], v[158:159], off offset:-3072
	global_load_dwordx4 v[218:221], v[160:161], off offset:-3072
	global_load_dwordx4 v[222:225], v[162:163], off offset:-3072
	global_load_dwordx4 v[226:229], v[156:157], off offset:-3072
	global_load_dwordx4 v[164:167], v[74:75], off offset:0
	global_load_dwordx4 v[168:171], v[74:75], off offset:32
	s_waitcnt vmcnt(10)
	v_mfma_f32_32x32x16_bf16 v[0:15], v[194:197], v[146:149], v[0:15]
	global_load_dwordx4 v[194:197], v[158:159], off offset:-2048
	s_waitcnt vmcnt(10)
	v_mfma_f32_32x32x16_bf16 v[32:47], v[198:201], v[146:149], v[32:47]
	global_load_dwordx4 v[198:201], v[160:161], off offset:-2048
	s_waitcnt vmcnt(10)
	v_mfma_f32_32x32x16_bf16 v[48:63], v[202:205], v[146:149], v[48:63]
	global_load_dwordx4 v[202:205], v[162:163], off offset:-2048
	s_waitcnt vmcnt(10)
	v_mfma_f32_32x32x16_bf16 v[16:31], v[208:211], v[146:149], v[16:31]
	global_load_dwordx4 v[208:211], v[156:157], off offset:-2048
	global_load_dwordx4 v[146:149], v[74:75], off offset:64
	s_waitcnt vmcnt(10)
	v_mfma_f32_32x32x16_bf16 v[0:15], v[214:217], v[150:153], v[0:15]
	global_load_dwordx4 v[214:217], v[158:159], off offset:-1024
	s_waitcnt vmcnt(10)
	v_mfma_f32_32x32x16_bf16 v[32:47], v[218:221], v[150:153], v[32:47]
	global_load_dwordx4 v[218:221], v[160:161], off offset:-1024
	s_waitcnt vmcnt(10)
	v_mfma_f32_32x32x16_bf16 v[48:63], v[222:225], v[150:153], v[48:63]
	global_load_dwordx4 v[222:225], v[162:163], off offset:-1024
	s_waitcnt vmcnt(10)
	v_mfma_f32_32x32x16_bf16 v[16:31], v[226:229], v[150:153], v[16:31]
	global_load_dwordx4 v[226:229], v[156:157], off offset:-1024
	global_load_dwordx4 v[150:153], v[74:75], off offset:96
	s_waitcnt vmcnt(9)
	v_mfma_f32_32x32x16_bf16 v[0:15], v[194:197], v[164:167], v[0:15]
	global_load_dwordx4 v[194:197], v[158:159], off
	s_waitcnt vmcnt(9)
	v_mfma_f32_32x32x16_bf16 v[32:47], v[198:201], v[164:167], v[32:47]
	global_load_dwordx4 v[198:201], v[160:161], off
	s_waitcnt vmcnt(9)
	v_mfma_f32_32x32x16_bf16 v[48:63], v[202:205], v[164:167], v[48:63]
	global_load_dwordx4 v[202:205], v[162:163], off
	s_waitcnt vmcnt(9)
	v_mfma_f32_32x32x16_bf16 v[16:31], v[208:211], v[164:167], v[16:31]
	global_load_dwordx4 v[208:211], v[156:157], off
	global_load_dwordx4 v[164:167], v[74:75], off offset:128
	s_waitcnt vmcnt(9)
	v_mfma_f32_32x32x16_bf16 v[0:15], v[214:217], v[168:171], v[0:15]
	global_load_dwordx4 v[214:217], v[158:159], off offset:1024
	s_waitcnt vmcnt(9)
	v_mfma_f32_32x32x16_bf16 v[32:47], v[218:221], v[168:171], v[32:47]
	global_load_dwordx4 v[218:221], v[160:161], off offset:1024
	s_waitcnt vmcnt(9)
	v_mfma_f32_32x32x16_bf16 v[48:63], v[222:225], v[168:171], v[48:63]
	global_load_dwordx4 v[222:225], v[162:163], off offset:1024
	s_waitcnt vmcnt(9)
	v_mfma_f32_32x32x16_bf16 v[16:31], v[226:229], v[168:171], v[16:31]
	global_load_dwordx4 v[226:229], v[156:157], off offset:1024
	global_load_dwordx4 v[168:171], v[74:75], off offset:160
	s_waitcnt vmcnt(9)
	v_mfma_f32_32x32x16_bf16 v[0:15], v[194:197], v[146:149], v[0:15]
	global_load_dwordx4 v[194:197], v[158:159], off offset:2048
	s_waitcnt vmcnt(9)
	v_mfma_f32_32x32x16_bf16 v[32:47], v[198:201], v[146:149], v[32:47]
	global_load_dwordx4 v[198:201], v[160:161], off offset:2048
	s_waitcnt vmcnt(9)
	v_mfma_f32_32x32x16_bf16 v[48:63], v[202:205], v[146:149], v[48:63]
	global_load_dwordx4 v[202:205], v[162:163], off offset:2048
	s_waitcnt vmcnt(9)
	v_mfma_f32_32x32x16_bf16 v[16:31], v[208:211], v[146:149], v[16:31]
	global_load_dwordx4 v[208:211], v[156:157], off offset:2048
	s_waitcnt vmcnt(8)
	v_mfma_f32_32x32x16_bf16 v[0:15], v[214:217], v[150:153], v[0:15]
	global_load_dwordx4 v[214:217], v[158:159], off offset:3072
	s_waitcnt vmcnt(8)
; #define CE_DESC(a, b) do { const float _x = (a), _y = (b); (a) = fmaxf(_x, _y); (b) = fminf(_x, _y); } while (0)
; #define CE_ASC(a, b) do { const float _x = (a), _y = (b); (a) = fminf(_x, _y); (b) = fmaxf(_x, _y); } while (0)
; DI void sort16_desc(float (&x)[16]) {
; #pragma unroll
;     for (int k = 2; k <= 16; k <<= 1)
; #pragma unroll
;         for (int j = k >> 1; j > 0; j >>= 1)
; #pragma unroll
;             for (int i = 0; i < 16; ++i) { const int l = i ^ j; if (l > i) { if ((i & k) == 0) CE_DESC(x[i], x[l]); else CE_ASC(x[i], x[l]); } }
; }
; DI void route_block(const Frame& F, int t0, int t1) {
;     ...
;             float x[64];
; #pragma unroll
;             for (int kb = 0; kb < 4; ++kb)
; #pragma unroll
;                 for (int i = 0; i < 16; ++i) { const unsigned key = (unsigned)(kb * 32 + (i & 3) + 8 * (i >> 2)) + 4u * (unsigned)hh;
;                     x[kb * 16 + i] = __uint_as_float((__float_as_uint(acc[kb][i]) & ~127u) | key); }
	v_mfma_f32_32x32x16_bf16 v[32:47], v[218:221], v[150:153], v[32:47]
	global_load_dwordx4 v[218:221], v[160:161], off offset:3072
	s_waitcnt vmcnt(8)
	v_mfma_f32_32x32x16_bf16 v[48:63], v[222:225], v[150:153], v[48:63]
	global_load_dwordx4 v[222:225], v[162:163], off offset:3072
	s_waitcnt vmcnt(8)
	v_mfma_f32_32x32x16_bf16 v[16:31], v[226:229], v[150:153], v[16:31]
	global_load_dwordx4 v[226:229], v[156:157], off offset:3072
	s_waitcnt vmcnt(7)
	v_mfma_f32_32x32x16_bf16 v[0:15], v[194:197], v[164:167], v[0:15]
	s_waitcnt vmcnt(6)
	v_mfma_f32_32x32x16_bf16 v[32:47], v[198:201], v[164:167], v[32:47]
	s_waitcnt vmcnt(5)
	v_mfma_f32_32x32x16_bf16 v[48:63], v[202:205], v[164:167], v[48:63]
	s_waitcnt vmcnt(4)
	v_mfma_f32_32x32x16_bf16 v[16:31], v[208:211], v[164:167], v[16:31]
	s_waitcnt vmcnt(3)
	v_mfma_f32_32x32x16_bf16 v[0:15], v[214:217], v[168:171], v[0:15]
	s_waitcnt vmcnt(2)
	v_mfma_f32_32x32x16_bf16 v[32:47], v[218:221], v[168:171], v[32:47]
	s_waitcnt vmcnt(1)
	v_mfma_f32_32x32x16_bf16 v[48:63], v[222:225], v[168:171], v[48:63]
	s_waitcnt vmcnt(0)
	v_mfma_f32_32x32x16_bf16 v[16:31], v[226:229], v[168:171], v[16:31]
	s_nop 7
	s_nop 3
	s_movk_i32 s8, 0xff80
	s_nop 0
	v_and_or_b32 v74, v0, s8, v77
	v_and_or_b32 v75, v1, s8, v80
	s_nop 0
	v_and_or_b32 v152, v32, s8, v95
	v_and_or_b32 v153, v33, s8, v96
	v_and_or_b32 v128, v2, s8, v81
	v_and_or_b32 v146, v3, s8, v82
	v_and_or_b32 v154, v34, s8, v97
	v_and_or_b32 v155, v35, s8, v98
	v_and_or_b32 v157, v37, s8, v100
	v_and_or_b32 v35, v16, s8, v127
	v_and_or_b32 v37, v17, s8, v130
	v_max_f32_e32 v16, v75, v75
	v_max_f32_e32 v17, v74, v74
	v_max_f32_e32 v74, v153, v153
	v_max_f32_e32 v75, v152, v152
	v_and_or_b32 v147, v4, s8, v83
	v_and_or_b32 v148, v5, s8, v84
	v_and_or_b32 v156, v36, s8, v99
	v_and_or_b32 v48, v48, s8, v111
	v_and_or_b32 v49, v49, s8, v112
	v_and_or_b32 v33, v18, s8, v131
	v_and_or_b32 v36, v19, s8, v132
	v_max_f32_e32 v18, v17, v16
	v_min_f32_e32 v16, v17, v16
	v_max_f32_e32 v17, v146, v146
	v_max_f32_e32 v19, v128, v128
	v_max_f32_e32 v128, v75, v74
	v_min_f32_e32 v74, v75, v74
	v_max_f32_e32 v75, v155, v155
	v_max_f32_e32 v146, v154, v154
	v_and_or_b32 v149, v6, s8, v85
	v_and_or_b32 v150, v11, s8, v90
	v_and_or_b32 v159, v39, s8, v102
	v_and_or_b32 v50, v50, s8, v113
	v_and_or_b32 v51, v51, s8, v114
	v_and_or_b32 v32, v20, s8, v133
	v_and_or_b32 v11, v22, s8, v135
	v_min_f32_e32 v20, v19, v17
	v_max_f32_e32 v17, v19, v17
	v_max_f32_e32 v19, v148, v148
	v_max_f32_e32 v22, v147, v147
	v_min_f32_e32 v147, v146, v75
	v_max_f32_e32 v75, v146, v75
	v_max_f32_e32 v146, v157, v157
	v_max_f32_e32 v148, v156, v156
	v_max_f32_e32 v49, v49, v49
	v_max_f32_e32 v48, v48, v48
	v_and_or_b32 v52, v52, s8, v115
	v_and_or_b32 v53, v53, s8, v116
	v_and_or_b32 v34, v21, s8, v134
	v_and_or_b32 v21, v23, s8, v136
	v_max_f32_e32 v23, v22, v19
	v_min_f32_e32 v19, v22, v19
	v_max_f32_e32 v22, v149, v149
	v_max_f32_e32 v149, v148, v146
	v_min_f32_e32 v146, v148, v146
	v_max_f32_e32 v148, v159, v159
	v_max_f32_e32 v159, v48, v49
	v_min_f32_e32 v48, v48, v49
	v_max_f32_e32 v49, v51, v51
	v_max_f32_e32 v50, v50, v50
	v_and_or_b32 v7, v7, s8, v86
	v_and_or_b32 v8, v8, s8, v87
	v_and_or_b32 v9, v9, s8, v88
	v_and_or_b32 v54, v54, s8, v117
	v_and_or_b32 v55, v55, s8, v118
	v_min_f32_e32 v51, v50, v49
	v_max_f32_e32 v49, v50, v49
	v_max_f32_e32 v50, v53, v53
	v_max_f32_e32 v52, v52, v52
	v_and_or_b32 v10, v10, s8, v89
	v_and_or_b32 v158, v38, s8, v101
	v_and_or_b32 v40, v40, s8, v103
	v_and_or_b32 v41, v41, s8, v104
	v_and_or_b32 v56, v56, s8, v119
	v_and_or_b32 v57, v57, s8, v120
	v_max_f32_e32 v7, v7, v7
	v_max_f32_e32 v9, v9, v9
	v_max_f32_e32 v8, v8, v8
	v_max_f32_e32 v53, v52, v50
	v_min_f32_e32 v50, v52, v50
	v_max_f32_e32 v52, v55, v55
	v_max_f32_e32 v54, v54, v54
	v_and_or_b32 v151, v12, s8, v91
	v_and_or_b32 v13, v13, s8, v92
	v_and_or_b32 v42, v42, s8, v105
	v_and_or_b32 v43, v43, s8, v106
	v_and_or_b32 v58, v58, s8, v121
	v_and_or_b32 v59, v59, s8, v122
	v_and_or_b32 v5, v24, s8, v137
	v_min_f32_e32 v24, v22, v7
	v_max_f32_e32 v7, v22, v7
	v_max_f32_e32 v22, v8, v9
	v_min_f32_e32 v8, v8, v9
	v_max_f32_e32 v9, v150, v150
	v_max_f32_e32 v10, v10, v10
	v_max_f32_e32 v150, v158, v158
	v_max_f32_e32 v41, v41, v41
	v_max_f32_e32 v40, v40, v40
	v_min_f32_e32 v55, v54, v52
	v_max_f32_e32 v52, v54, v52
	v_max_f32_e32 v54, v57, v57
	v_max_f32_e32 v56, v56, v56
	v_and_or_b32 v44, v44, s8, v107
	v_and_or_b32 v45, v45, s8, v108
	v_and_or_b32 v60, v60, s8, v123
	v_and_or_b32 v61, v61, s8, v124
	v_and_or_b32 v12, v25, s8, v138
	v_min_f32_e32 v25, v10, v9
	v_max_f32_e32 v9, v10, v9
	v_max_f32_e32 v10, v13, v13
	v_max_f32_e32 v13, v151, v151
	v_min_f32_e32 v151, v150, v148
	v_max_f32_e32 v148, v150, v148
	v_max_f32_e32 v150, v40, v41
	v_min_f32_e32 v40, v40, v41
	v_max_f32_e32 v41, v43, v43
	v_max_f32_e32 v42, v42, v42
	v_max_f32_e32 v57, v56, v54
	v_min_f32_e32 v54, v56, v54
	v_max_f32_e32 v56, v59, v59
	v_max_f32_e32 v58, v58, v58
	v_and_or_b32 v14, v14, s8, v93
	v_and_or_b32 v15, v15, s8, v94
	v_and_or_b32 v46, v46, s8, v109
	v_and_or_b32 v47, v47, s8, v110
	v_and_or_b32 v62, v62, s8, v125
	v_and_or_b32 v63, v63, s8, v126
	v_and_or_b32 v3, v26, s8, v139
	v_and_or_b32 v6, v27, s8, v140
	v_and_or_b32 v1, v28, s8, v141
	v_and_or_b32 v4, v29, s8, v142
	v_and_or_b32 v0, v30, s8, v143
	v_and_or_b32 v2, v31, s8, v144
	v_min_f32_e32 v43, v42, v41
	v_max_f32_e32 v41, v42, v41
	v_max_f32_e32 v42, v45, v45
	v_max_f32_e32 v44, v44, v44
	v_min_f32_e32 v59, v58, v56
	v_max_f32_e32 v56, v58, v56
	v_max_f32_e32 v58, v61, v61
	v_max_f32_e32 v60, v60, v60
	v_max_f32_e32 v26, v13, v10
	v_min_f32_e32 v10, v13, v10
; #define CE_DESC(a, b) do { const float _x = (a), _y = (b); (a) = fmaxf(_x, _y); (b) = fminf(_x, _y); } while (0)
; #define CE_ASC(a, b) do { const float _x = (a), _y = (b); (a) = fminf(_x, _y); (b) = fmaxf(_x, _y); } while (0)
; DI void sort16_desc(float (&x)[16]) {
; #pragma unroll
;     for (int k = 2; k <= 16; k <<= 1)
; #pragma unroll
;         for (int j = k >> 1; j > 0; j >>= 1)
; #pragma unroll
;             for (int i = 0; i < 16; ++i) { const int l = i ^ j; if (l > i) { if ((i & k) == 0) CE_DESC(x[i], x[l]); else CE_ASC(x[i], x[l]); } }
; }
; DI void merge_top16(float (&a)[16], const float (&b)[16]) {
; #pragma unroll
;     for (int i = 0; i < 16; ++i) a[i] = fmaxf(a[i], b[15 - i]);
; #pragma unroll
;     for (int j = 8; j > 0; j >>= 1)
; #pragma unroll
;         for (int i = 0; i < 16; ++i) { const int l = i ^ j; if (l > i) CE_DESC(a[i], a[l]); }
; }
; DI void top16_of64(float (&x)[64], float (&t)[16]) {
;     float g[4][16];
; #pragma unroll
;     for (int q = 0; q < 4; ++q) {
; #pragma unroll
;         for (int i = 0; i < 16; ++i) g[q][i] = x[q * 16 + i];
;         sort16_desc(g[q]); }
;     merge_top16(g[0], g[1]); merge_top16(g[2], g[3]); merge_top16(g[0], g[2]);
; #pragma unroll
;     for (int i = 0; i < 16; ++i) t[i] = g[0][i];
; }
	v_max_f32_e32 v13, v15, v15
	v_max_f32_e32 v14, v14, v14
	v_max_f32_e32 v45, v44, v42
	v_min_f32_e32 v42, v44, v42
	v_max_f32_e32 v44, v47, v47
	v_max_f32_e32 v46, v46, v46
	v_max_f32_e32 v61, v60, v58
	v_min_f32_e32 v58, v60, v58
	v_max_f32_e32 v60, v63, v63
	v_max_f32_e32 v62, v62, v62
	v_max_f32_e32 v37, v37, v37
	v_max_f32_e32 v35, v35, v35
	v_max_f32_e32 v36, v36, v36
	v_max_f32_e32 v33, v33, v33
	v_max_f32_e32 v34, v34, v34
	v_max_f32_e32 v32, v32, v32
	v_max_f32_e32 v21, v21, v21
	v_max_f32_e32 v11, v11, v11
	v_max_f32_e32 v12, v12, v12
	v_max_f32_e32 v5, v5, v5
	v_max_f32_e32 v6, v6, v6
	v_max_f32_e32 v3, v3, v3
	v_max_f32_e32 v4, v4, v4
	v_max_f32_e32 v1, v1, v1
	v_max_f32_e32 v2, v2, v2
	v_max_f32_e32 v0, v0, v0
	v_min_f32_e32 v15, v14, v13
	v_max_f32_e32 v13, v14, v13
	v_min_f32_e32 v47, v46, v44
	v_max_f32_e32 v44, v46, v44
	v_min_f32_e32 v63, v62, v60
	v_max_f32_e32 v60, v62, v60
	v_max_f32_e32 v167, v35, v37
	v_min_f32_e32 v35, v35, v37
	v_min_f32_e32 v37, v33, v36
	v_max_f32_e32 v33, v33, v36
	v_max_f32_e32 v36, v32, v34
	v_min_f32_e32 v32, v32, v34
	v_min_f32_e32 v34, v11, v21
	v_max_f32_e32 v11, v11, v21
	v_max_f32_e32 v21, v5, v12
	v_min_f32_e32 v5, v5, v12
	v_min_f32_e32 v12, v3, v6
	v_max_f32_e32 v3, v3, v6
	v_max_f32_e32 v6, v1, v4
	v_min_f32_e32 v1, v1, v4
	v_min_f32_e32 v4, v0, v2
	v_max_f32_e32 v0, v0, v2
	v_max_f32_e32 v14, v18, v20
	v_min_f32_e32 v18, v18, v20
	v_max_f32_e32 v20, v16, v17
	v_min_f32_e32 v16, v16, v17
	v_min_f32_e32 v17, v23, v24
	v_max_f32_e32 v23, v23, v24
	v_min_f32_e32 v24, v19, v7
	v_max_f32_e32 v7, v19, v7
	v_max_f32_e32 v19, v22, v25
	v_min_f32_e32 v22, v22, v25
	v_max_f32_e32 v25, v8, v9
	v_min_f32_e32 v8, v8, v9
	v_min_f32_e32 v9, v26, v15
	v_max_f32_e32 v15, v26, v15
	v_min_f32_e32 v26, v10, v13
	v_max_f32_e32 v10, v10, v13
	v_max_f32_e32 v46, v128, v147
	v_min_f32_e32 v128, v128, v147
	v_max_f32_e32 v147, v74, v75
	v_min_f32_e32 v74, v74, v75
	v_min_f32_e32 v75, v149, v151
	v_max_f32_e32 v149, v149, v151
	v_min_f32_e32 v151, v146, v148
	v_max_f32_e32 v146, v146, v148
	v_max_f32_e32 v148, v150, v43
	v_min_f32_e32 v43, v150, v43
	v_max_f32_e32 v150, v40, v41
	v_min_f32_e32 v40, v40, v41
	v_min_f32_e32 v41, v45, v47
	v_max_f32_e32 v45, v45, v47
	v_min_f32_e32 v47, v42, v44
	v_max_f32_e32 v42, v42, v44
	v_max_f32_e32 v62, v159, v51
	v_min_f32_e32 v51, v159, v51
	v_max_f32_e32 v159, v48, v49
	v_min_f32_e32 v48, v48, v49
	v_min_f32_e32 v49, v53, v55
	v_max_f32_e32 v53, v53, v55
	v_min_f32_e32 v55, v50, v52
	v_max_f32_e32 v50, v50, v52
	v_max_f32_e32 v52, v57, v59
	v_min_f32_e32 v57, v57, v59
	v_max_f32_e32 v59, v54, v56
	v_min_f32_e32 v54, v54, v56
	v_min_f32_e32 v56, v61, v63
	v_max_f32_e32 v61, v61, v63
	v_min_f32_e32 v63, v58, v60
	v_max_f32_e32 v58, v58, v60
	v_max_f32_e32 v2, v167, v37
	v_min_f32_e32 v37, v167, v37
	v_max_f32_e32 v167, v35, v33
	v_min_f32_e32 v33, v35, v33
	v_min_f32_e32 v35, v36, v34
	v_max_f32_e32 v34, v36, v34
	v_min_f32_e32 v36, v32, v11
	v_max_f32_e32 v11, v32, v11
	v_max_f32_e32 v32, v21, v12
	v_min_f32_e32 v12, v21, v12
	v_max_f32_e32 v21, v5, v3
	v_min_f32_e32 v3, v5, v3
	v_min_f32_e32 v5, v6, v4
	v_max_f32_e32 v4, v6, v4
	v_min_f32_e32 v6, v1, v0
	v_max_f32_e32 v0, v1, v0
	v_max_f32_e32 v13, v14, v20
	v_min_f32_e32 v14, v14, v20
	v_max_f32_e32 v20, v18, v16
	v_min_f32_e32 v16, v18, v16
	v_min_f32_e32 v18, v17, v24
	v_max_f32_e32 v17, v17, v24
	v_min_f32_e32 v24, v23, v7
	v_max_f32_e32 v7, v23, v7
	v_max_f32_e32 v23, v19, v25
	v_min_f32_e32 v19, v19, v25
	v_max_f32_e32 v25, v22, v8
	v_min_f32_e32 v8, v22, v8
	v_min_f32_e32 v22, v9, v26
	v_max_f32_e32 v9, v9, v26
	v_min_f32_e32 v26, v15, v10
	v_max_f32_e32 v10, v15, v10
	v_max_f32_e32 v44, v46, v147
	v_min_f32_e32 v46, v46, v147
	v_max_f32_e32 v147, v128, v74
	v_min_f32_e32 v74, v128, v74
	v_min_f32_e32 v128, v75, v151
	v_max_f32_e32 v75, v75, v151
	v_min_f32_e32 v151, v149, v146
	v_max_f32_e32 v146, v149, v146
	v_max_f32_e32 v149, v148, v150
	v_min_f32_e32 v148, v148, v150
	v_max_f32_e32 v150, v43, v40
	v_min_f32_e32 v40, v43, v40
	v_min_f32_e32 v43, v41, v47
	v_max_f32_e32 v41, v41, v47
	v_min_f32_e32 v47, v45, v42
	v_max_f32_e32 v42, v45, v42
	v_max_f32_e32 v60, v62, v159
	v_min_f32_e32 v62, v62, v159
	v_max_f32_e32 v159, v51, v48
	v_min_f32_e32 v48, v51, v48
	v_min_f32_e32 v51, v49, v55
	v_max_f32_e32 v49, v49, v55
	v_min_f32_e32 v55, v53, v50
	v_max_f32_e32 v50, v53, v50
	v_max_f32_e32 v53, v52, v59
	v_min_f32_e32 v52, v52, v59
	v_max_f32_e32 v59, v57, v54
	v_min_f32_e32 v54, v57, v54
	v_min_f32_e32 v57, v56, v63
	v_max_f32_e32 v56, v56, v63
	v_min_f32_e32 v63, v61, v58
	v_max_f32_e32 v58, v61, v58
	v_max_f32_e32 v1, v2, v167
	v_min_f32_e32 v2, v2, v167
	v_max_f32_e32 v167, v37, v33
	v_min_f32_e32 v33, v37, v33
	v_min_f32_e32 v37, v35, v36
	v_max_f32_e32 v35, v35, v36
	v_min_f32_e32 v36, v34, v11
	v_max_f32_e32 v11, v34, v11
	v_max_f32_e32 v34, v32, v21
	v_min_f32_e32 v21, v32, v21
	v_max_f32_e32 v32, v12, v3
	v_min_f32_e32 v3, v12, v3
	v_min_f32_e32 v12, v5, v6
	v_max_f32_e32 v5, v5, v6
	v_min_f32_e32 v6, v4, v0
	v_max_f32_e32 v0, v4, v0
	v_max_f32_e32 v15, v13, v18
	v_min_f32_e32 v13, v13, v18
	v_max_f32_e32 v18, v14, v17
	v_min_f32_e32 v14, v14, v17
	v_max_f32_e32 v17, v20, v24
	v_min_f32_e32 v20, v20, v24
	v_max_f32_e32 v24, v16, v7
	v_min_f32_e32 v7, v16, v7
	v_min_f32_e32 v16, v23, v22
	v_max_f32_e32 v22, v23, v22
	v_min_f32_e32 v23, v19, v9
	v_max_f32_e32 v9, v19, v9
	v_min_f32_e32 v19, v25, v26
	v_max_f32_e32 v25, v25, v26
	v_min_f32_e32 v26, v8, v10
	v_max_f32_e32 v8, v8, v10
	v_max_f32_e32 v45, v44, v128
	v_min_f32_e32 v44, v44, v128
	v_max_f32_e32 v128, v46, v75
	v_min_f32_e32 v46, v46, v75
; #define CE_DESC(a, b) do { const float _x = (a), _y = (b); (a) = fmaxf(_x, _y); (b) = fminf(_x, _y); } while (0)
; #define CE_ASC(a, b) do { const float _x = (a), _y = (b); (a) = fminf(_x, _y); (b) = fmaxf(_x, _y); } while (0)
; DI void sort16_desc(float (&x)[16]) {
; #pragma unroll
;     for (int k = 2; k <= 16; k <<= 1)
; #pragma unroll
;         for (int j = k >> 1; j > 0; j >>= 1)
; #pragma unroll
;             for (int i = 0; i < 16; ++i) { const int l = i ^ j; if (l > i) { if ((i & k) == 0) CE_DESC(x[i], x[l]); else CE_ASC(x[i], x[l]); } }
; }
; DI void merge_top16(float (&a)[16], const float (&b)[16]) {
; #pragma unroll
;     for (int i = 0; i < 16; ++i) a[i] = fmaxf(a[i], b[15 - i]);
; #pragma unroll
;     for (int j = 8; j > 0; j >>= 1)
; #pragma unroll
;         for (int i = 0; i < 16; ++i) { const int l = i ^ j; if (l > i) CE_DESC(a[i], a[l]); }
; }
; DI void top16_of64(float (&x)[64], float (&t)[16]) {
;     float g[4][16];
; #pragma unroll
;     for (int q = 0; q < 4; ++q) {
; #pragma unroll
;         for (int i = 0; i < 16; ++i) g[q][i] = x[q * 16 + i];
;         sort16_desc(g[q]); }
;     merge_top16(g[0], g[1]); merge_top16(g[2], g[3]); merge_top16(g[0], g[2]);
; #pragma unroll
;     for (int i = 0; i < 16; ++i) t[i] = g[0][i];
; }
	v_max_f32_e32 v75, v147, v151
	v_min_f32_e32 v147, v147, v151
	v_max_f32_e32 v151, v74, v146
	v_min_f32_e32 v74, v74, v146
	v_min_f32_e32 v146, v149, v43
	v_max_f32_e32 v43, v149, v43
	v_min_f32_e32 v149, v148, v41
	v_max_f32_e32 v41, v148, v41
	v_min_f32_e32 v148, v150, v47
	v_max_f32_e32 v47, v150, v47
	v_min_f32_e32 v150, v40, v42
	v_max_f32_e32 v40, v40, v42
	v_max_f32_e32 v61, v60, v51
	v_min_f32_e32 v51, v60, v51
	v_max_f32_e32 v60, v62, v49
	v_min_f32_e32 v49, v62, v49
	v_max_f32_e32 v62, v159, v55
	v_min_f32_e32 v55, v159, v55
	v_max_f32_e32 v159, v48, v50
	v_min_f32_e32 v48, v48, v50
	v_min_f32_e32 v50, v53, v57
	v_max_f32_e32 v53, v53, v57
	v_min_f32_e32 v57, v52, v56
	v_max_f32_e32 v52, v52, v56
	v_min_f32_e32 v56, v59, v63
	v_max_f32_e32 v59, v59, v63
	v_min_f32_e32 v63, v54, v58
	v_max_f32_e32 v54, v54, v58
	v_max_f32_e32 v4, v1, v37
	v_min_f32_e32 v1, v1, v37
	v_max_f32_e32 v37, v2, v35
	v_min_f32_e32 v2, v2, v35
	v_max_f32_e32 v35, v167, v36
	v_min_f32_e32 v36, v167, v36
	v_max_f32_e32 v167, v33, v11
	v_min_f32_e32 v11, v33, v11
	v_min_f32_e32 v33, v34, v12
	v_max_f32_e32 v12, v34, v12
	v_min_f32_e32 v34, v21, v5
	v_max_f32_e32 v5, v21, v5
	v_min_f32_e32 v21, v32, v6
	v_max_f32_e32 v6, v32, v6
	v_min_f32_e32 v32, v3, v0
	v_max_f32_e32 v0, v3, v0
	v_max_f32_e32 v10, v15, v17
	v_min_f32_e32 v15, v15, v17
	v_max_f32_e32 v17, v18, v24
	v_min_f32_e32 v18, v18, v24
	v_max_f32_e32 v24, v13, v20
	v_min_f32_e32 v13, v13, v20
	v_max_f32_e32 v20, v14, v7
	v_min_f32_e32 v7, v14, v7
	v_min_f32_e32 v14, v16, v19
	v_max_f32_e32 v16, v16, v19
	v_min_f32_e32 v19, v23, v26
	v_max_f32_e32 v23, v23, v26
	v_min_f32_e32 v26, v22, v25
	v_max_f32_e32 v22, v22, v25
	v_min_f32_e32 v25, v9, v8
	v_max_f32_e32 v8, v9, v8
	v_max_f32_e32 v42, v45, v75
	v_min_f32_e32 v45, v45, v75
	v_max_f32_e32 v75, v128, v151
	v_min_f32_e32 v128, v128, v151
	v_max_f32_e32 v151, v44, v147
	v_min_f32_e32 v44, v44, v147
	v_max_f32_e32 v147, v46, v74
	v_min_f32_e32 v46, v46, v74
	v_min_f32_e32 v74, v146, v148
	v_max_f32_e32 v146, v146, v148
	v_min_f32_e32 v148, v149, v150
	v_max_f32_e32 v149, v149, v150
	v_min_f32_e32 v150, v43, v47
	v_max_f32_e32 v43, v43, v47
	v_min_f32_e32 v47, v41, v40
	v_max_f32_e32 v40, v41, v40
	v_max_f32_e32 v58, v61, v62
	v_min_f32_e32 v61, v61, v62
	v_max_f32_e32 v62, v60, v159
	v_min_f32_e32 v60, v60, v159
	v_max_f32_e32 v159, v51, v55
	v_min_f32_e32 v51, v51, v55
	v_max_f32_e32 v55, v49, v48
	v_min_f32_e32 v48, v49, v48
	v_min_f32_e32 v49, v50, v56
	v_max_f32_e32 v50, v50, v56
	v_min_f32_e32 v56, v57, v63
	v_max_f32_e32 v57, v57, v63
	v_min_f32_e32 v63, v53, v59
	v_max_f32_e32 v53, v53, v59
	v_min_f32_e32 v59, v52, v54
	v_max_f32_e32 v52, v52, v54
	v_max_f32_e32 v3, v4, v35
	v_min_f32_e32 v4, v4, v35
	v_max_f32_e32 v35, v37, v167
	v_min_f32_e32 v37, v37, v167
	v_max_f32_e32 v167, v1, v36
	v_min_f32_e32 v1, v1, v36
	v_max_f32_e32 v36, v2, v11
	v_min_f32_e32 v2, v2, v11
	v_min_f32_e32 v11, v33, v21
	v_max_f32_e32 v21, v33, v21
	v_min_f32_e32 v33, v34, v32
	v_max_f32_e32 v32, v34, v32
	v_min_f32_e32 v34, v12, v6
	v_max_f32_e32 v6, v12, v6
	v_min_f32_e32 v12, v5, v0
	v_max_f32_e32 v0, v5, v0
	v_max_f32_e32 v9, v10, v17
	v_min_f32_e32 v10, v10, v17
	v_max_f32_e32 v17, v15, v18
	v_min_f32_e32 v15, v15, v18
	v_max_f32_e32 v18, v24, v20
	v_min_f32_e32 v20, v24, v20
	v_max_f32_e32 v24, v13, v7
	v_min_f32_e32 v7, v13, v7
	v_min_f32_e32 v13, v14, v19
	v_max_f32_e32 v14, v14, v19
	v_min_f32_e32 v19, v16, v23
	v_max_f32_e32 v16, v16, v23
	v_min_f32_e32 v23, v26, v25
	v_max_f32_e32 v25, v26, v25
	v_min_f32_e32 v26, v22, v8
	v_max_f32_e32 v8, v22, v8
	v_max_f32_e32 v41, v42, v75
	v_min_f32_e32 v42, v42, v75
	v_max_f32_e32 v75, v45, v128
	v_min_f32_e32 v45, v45, v128
	v_max_f32_e32 v128, v151, v147
	v_min_f32_e32 v147, v151, v147
	v_max_f32_e32 v151, v44, v46
	v_min_f32_e32 v44, v44, v46
	v_min_f32_e32 v46, v74, v148
	v_max_f32_e32 v74, v74, v148
	v_min_f32_e32 v148, v146, v149
	v_max_f32_e32 v146, v146, v149
	v_min_f32_e32 v149, v150, v47
	v_max_f32_e32 v47, v150, v47
	v_min_f32_e32 v150, v43, v40
	v_max_f32_e32 v40, v43, v40
	v_max_f32_e32 v54, v58, v62
	v_min_f32_e32 v58, v58, v62
	v_max_f32_e32 v62, v61, v60
	v_min_f32_e32 v60, v61, v60
	v_max_f32_e32 v61, v159, v55
	v_min_f32_e32 v55, v159, v55
	v_max_f32_e32 v159, v51, v48
	v_min_f32_e32 v48, v51, v48
	v_min_f32_e32 v51, v49, v56
	v_max_f32_e32 v49, v49, v56
	v_min_f32_e32 v56, v50, v57
	v_max_f32_e32 v50, v50, v57
	v_min_f32_e32 v57, v63, v59
	v_max_f32_e32 v59, v63, v59
	v_min_f32_e32 v63, v53, v52
	v_max_f32_e32 v52, v53, v52
	v_max_f32_e32 v5, v3, v35
	v_min_f32_e32 v3, v3, v35
	v_max_f32_e32 v35, v4, v37
	v_min_f32_e32 v4, v4, v37
	v_max_f32_e32 v37, v167, v36
	v_min_f32_e32 v36, v167, v36
	v_max_f32_e32 v167, v1, v2
	v_min_f32_e32 v1, v1, v2
	v_min_f32_e32 v2, v11, v33
	v_max_f32_e32 v11, v11, v33
	v_min_f32_e32 v33, v21, v32
	v_max_f32_e32 v21, v21, v32
	v_min_f32_e32 v32, v34, v12
	v_max_f32_e32 v12, v34, v12
	v_min_f32_e32 v34, v6, v0
	v_max_f32_e32 v0, v6, v0
	v_max_f32_e32 v22, v9, v13
	v_min_f32_e32 v9, v9, v13
	v_max_f32_e32 v13, v10, v14
	v_min_f32_e32 v10, v10, v14
	v_max_f32_e32 v14, v17, v19
	v_min_f32_e32 v17, v17, v19
	v_max_f32_e32 v19, v15, v16
	v_min_f32_e32 v15, v15, v16
	v_max_f32_e32 v16, v18, v23
	v_min_f32_e32 v18, v18, v23
	v_max_f32_e32 v23, v20, v25
	v_min_f32_e32 v20, v20, v25
	v_max_f32_e32 v25, v24, v26
	v_min_f32_e32 v24, v24, v26
	v_max_f32_e32 v26, v7, v8
	v_min_f32_e32 v7, v7, v8
	v_max_f32_e32 v43, v41, v46
	v_min_f32_e32 v41, v41, v46
	v_max_f32_e32 v46, v42, v74
	v_min_f32_e32 v42, v42, v74
	v_max_f32_e32 v74, v75, v148
	v_min_f32_e32 v75, v75, v148
; #define CE_DESC(a, b) do { const float _x = (a), _y = (b); (a) = fmaxf(_x, _y); (b) = fminf(_x, _y); } while (0)
; #define CE_ASC(a, b) do { const float _x = (a), _y = (b); (a) = fminf(_x, _y); (b) = fmaxf(_x, _y); } while (0)
; DI void sort16_desc(float (&x)[16]) {
; #pragma unroll
;     for (int k = 2; k <= 16; k <<= 1)
; #pragma unroll
;         for (int j = k >> 1; j > 0; j >>= 1)
; #pragma unroll
;             for (int i = 0; i < 16; ++i) { const int l = i ^ j; if (l > i) { if ((i & k) == 0) CE_DESC(x[i], x[l]); else CE_ASC(x[i], x[l]); } }
; }
; DI void merge_top16(float (&a)[16], const float (&b)[16]) {
; #pragma unroll
;     for (int i = 0; i < 16; ++i) a[i] = fmaxf(a[i], b[15 - i]);
; #pragma unroll
;     for (int j = 8; j > 0; j >>= 1)
; #pragma unroll
;         for (int i = 0; i < 16; ++i) { const int l = i ^ j; if (l > i) CE_DESC(a[i], a[l]); }
; }
; DI void top16_of64(float (&x)[64], float (&t)[16]) {
;     float g[4][16];
; #pragma unroll
;     for (int q = 0; q < 4; ++q) {
; #pragma unroll
;         for (int i = 0; i < 16; ++i) g[q][i] = x[q * 16 + i];
;         sort16_desc(g[q]); }
;     merge_top16(g[0], g[1]); merge_top16(g[2], g[3]); merge_top16(g[0], g[2]);
; #pragma unroll
;     for (int i = 0; i < 16; ++i) t[i] = g[0][i];
; }
	v_max_f32_e32 v148, v45, v146
	v_min_f32_e32 v45, v45, v146
	v_max_f32_e32 v146, v128, v149
	v_min_f32_e32 v128, v128, v149
	v_max_f32_e32 v149, v147, v47
	v_min_f32_e32 v47, v147, v47
	v_max_f32_e32 v147, v151, v150
	v_min_f32_e32 v150, v151, v150
	v_max_f32_e32 v151, v44, v40
	v_min_f32_e32 v40, v44, v40
	v_max_f32_e32 v53, v54, v51
	v_min_f32_e32 v51, v54, v51
	v_max_f32_e32 v54, v58, v49
	v_min_f32_e32 v49, v58, v49
	v_max_f32_e32 v58, v62, v56
	v_min_f32_e32 v56, v62, v56
	v_max_f32_e32 v62, v60, v50
	v_min_f32_e32 v50, v60, v50
	v_max_f32_e32 v60, v61, v57
	v_min_f32_e32 v57, v61, v57
	v_max_f32_e32 v61, v55, v59
	v_min_f32_e32 v55, v55, v59
	v_max_f32_e32 v59, v159, v63
	v_min_f32_e32 v63, v159, v63
	v_max_f32_e32 v159, v48, v52
	v_min_f32_e32 v48, v48, v52
	v_max_f32_e32 v6, v5, v2
	v_min_f32_e32 v2, v5, v2
	v_max_f32_e32 v5, v3, v11
	v_min_f32_e32 v3, v3, v11
	v_max_f32_e32 v11, v35, v33
	v_min_f32_e32 v33, v35, v33
	v_max_f32_e32 v35, v4, v21
	v_min_f32_e32 v4, v4, v21
	v_max_f32_e32 v21, v37, v32
	v_min_f32_e32 v32, v37, v32
	v_max_f32_e32 v37, v36, v12
	v_min_f32_e32 v12, v36, v12
	v_max_f32_e32 v36, v167, v34
	v_min_f32_e32 v34, v167, v34
	v_max_f32_e32 v167, v1, v0
	v_min_f32_e32 v0, v1, v0
	v_max_f32_e32 v8, v22, v16
	v_min_f32_e32 v16, v22, v16
	v_max_f32_e32 v27, v13, v23
	v_min_f32_e32 v28, v13, v23
	v_max_f32_e32 v22, v14, v25
	v_min_f32_e32 v23, v14, v25
	v_max_f32_e32 v14, v19, v26
	v_min_f32_e32 v19, v19, v26
	v_max_f32_e32 v25, v9, v18
	v_min_f32_e32 v26, v9, v18
	v_max_f32_e32 v29, v10, v20
	v_min_f32_e32 v20, v10, v20
	v_max_f32_e32 v9, v17, v24
	v_min_f32_e32 v10, v17, v24
	v_max_f32_e32 v30, v15, v7
	v_min_f32_e32 v31, v15, v7
	v_max_f32_e32 v44, v43, v146
	v_min_f32_e32 v43, v43, v146
	v_max_f32_e32 v146, v46, v149
	v_min_f32_e32 v46, v46, v149
	v_max_f32_e32 v149, v74, v147
	v_min_f32_e32 v74, v74, v147
	v_max_f32_e32 v147, v148, v151
	v_min_f32_e32 v148, v148, v151
	v_max_f32_e32 v151, v41, v128
	v_min_f32_e32 v41, v41, v128
	v_max_f32_e32 v128, v42, v47
	v_min_f32_e32 v42, v42, v47
	v_max_f32_e32 v47, v75, v150
	v_min_f32_e32 v75, v75, v150
	v_max_f32_e32 v150, v45, v40
	v_min_f32_e32 v40, v45, v40
	v_max_f32_e32 v52, v53, v60
	v_min_f32_e32 v53, v53, v60
	v_max_f32_e32 v60, v54, v61
	v_min_f32_e32 v54, v54, v61
	v_max_f32_e32 v61, v58, v59
	v_min_f32_e32 v58, v58, v59
	v_max_f32_e32 v59, v62, v159
	v_min_f32_e32 v62, v62, v159
	v_max_f32_e32 v159, v51, v57
	v_min_f32_e32 v51, v51, v57
	v_max_f32_e32 v57, v49, v55
	v_min_f32_e32 v49, v49, v55
	v_max_f32_e32 v55, v56, v63
	v_min_f32_e32 v56, v56, v63
	v_max_f32_e32 v63, v50, v48
	v_min_f32_e32 v48, v50, v48
	v_max_f32_e32 v1, v6, v21
	v_min_f32_e32 v6, v6, v21
	v_max_f32_e32 v21, v5, v37
	v_min_f32_e32 v5, v5, v37
	v_max_f32_e32 v37, v11, v36
	v_min_f32_e32 v11, v11, v36
	v_max_f32_e32 v36, v35, v167
	v_min_f32_e32 v35, v35, v167
	v_max_f32_e32 v167, v2, v32
	v_min_f32_e32 v2, v2, v32
	v_max_f32_e32 v32, v3, v12
	v_min_f32_e32 v3, v3, v12
	v_max_f32_e32 v12, v33, v34
	v_min_f32_e32 v33, v33, v34
	v_max_f32_e32 v34, v4, v0
	v_min_f32_e32 v0, v4, v0
	v_max_f32_e32 v13, v8, v22
	v_min_f32_e32 v7, v8, v22
	v_max_f32_e32 v22, v27, v14
	v_min_f32_e32 v17, v27, v14
	v_max_f32_e32 v14, v16, v23
	v_min_f32_e32 v8, v16, v23
	v_max_f32_e32 v23, v28, v19
	v_min_f32_e32 v18, v28, v19
	v_max_f32_e32 v15, v25, v9
	v_min_f32_e32 v9, v25, v9
	v_max_f32_e32 v24, v29, v30
	v_min_f32_e32 v19, v29, v30
	v_max_f32_e32 v16, v26, v10
	v_min_f32_e32 v10, v26, v10
	v_max_f32_e32 v25, v20, v31
	v_min_f32_e32 v20, v20, v31
	v_max_f32_e32 v45, v44, v149
	v_min_f32_e32 v44, v44, v149
	v_max_f32_e32 v149, v146, v147
	v_min_f32_e32 v146, v146, v147
	v_max_f32_e32 v147, v43, v74
	v_min_f32_e32 v43, v43, v74
	v_max_f32_e32 v74, v46, v148
	v_min_f32_e32 v46, v46, v148
	v_max_f32_e32 v148, v151, v47
	v_min_f32_e32 v47, v151, v47
	v_max_f32_e32 v151, v128, v150
	v_min_f32_e32 v128, v128, v150
	v_max_f32_e32 v150, v41, v75
	v_min_f32_e32 v41, v41, v75
	v_max_f32_e32 v75, v42, v40
	v_min_f32_e32 v40, v42, v40
	v_max_f32_e32 v50, v52, v61
	v_min_f32_e32 v52, v52, v61
	v_max_f32_e32 v61, v60, v59
	v_min_f32_e32 v59, v60, v59
	v_max_f32_e32 v60, v53, v58
	v_min_f32_e32 v53, v53, v58
	v_max_f32_e32 v58, v54, v62
	v_min_f32_e32 v54, v54, v62
	v_max_f32_e32 v62, v159, v55
	v_min_f32_e32 v55, v159, v55
	v_max_f32_e32 v159, v57, v63
	v_min_f32_e32 v57, v57, v63
	v_max_f32_e32 v63, v51, v56
	v_min_f32_e32 v51, v51, v56
	v_max_f32_e32 v56, v49, v48
	v_min_f32_e32 v48, v49, v48
	v_max_f32_e32 v4, v1, v37
	v_min_f32_e32 v1, v1, v37
	v_max_f32_e32 v37, v21, v36
	v_min_f32_e32 v21, v21, v36
	v_max_f32_e32 v36, v6, v11
	v_min_f32_e32 v6, v6, v11
	v_max_f32_e32 v11, v5, v35
	v_min_f32_e32 v5, v5, v35
	v_max_f32_e32 v35, v167, v12
	v_min_f32_e32 v12, v167, v12
	v_max_f32_e32 v167, v32, v34
	v_min_f32_e32 v32, v32, v34
	v_max_f32_e32 v34, v2, v33
	v_min_f32_e32 v2, v2, v33
	v_max_f32_e32 v33, v3, v0
	v_min_f32_e32 v0, v3, v0
	v_min_f32_e32 v39, v13, v22
	v_min_f32_e32 v38, v7, v17
	v_min_f32_e32 v31, v14, v23
	v_min_f32_e32 v30, v8, v18
	v_min_f32_e32 v29, v15, v24
	v_min_f32_e32 v28, v9, v19
	v_min_f32_e32 v27, v16, v25
	v_min_f32_e32 v26, v10, v20
	v_min_f32_e32 v42, v45, v149
	v_min_f32_e32 v152, v44, v146
	v_min_f32_e32 v153, v147, v74
	v_min_f32_e32 v154, v43, v46
	v_min_f32_e32 v155, v148, v151
	v_min_f32_e32 v156, v47, v128
	v_min_f32_e32 v157, v150, v75
	v_min_f32_e32 v158, v41, v40
	v_min_f32_e32 v49, v50, v61
	v_min_f32_e32 v160, v52, v59
	v_min_f32_e32 v161, v60, v58
	v_min_f32_e32 v162, v53, v54
	v_min_f32_e32 v163, v62, v159
	v_min_f32_e32 v164, v55, v57
	v_min_f32_e32 v165, v63, v56
; #define CE_DESC(a, b) do { const float _x = (a), _y = (b); (a) = fmaxf(_x, _y); (b) = fminf(_x, _y); } while (0)
; DI void merge_top16(float (&a)[16], const float (&b)[16]) {
; #pragma unroll
;     for (int i = 0; i < 16; ++i) a[i] = fmaxf(a[i], b[15 - i]);
; #pragma unroll
;     for (int j = 8; j > 0; j >>= 1)
; #pragma unroll
;         for (int i = 0; i < 16; ++i) { const int l = i ^ j; if (l > i) CE_DESC(a[i], a[l]); }
; }
; DI void top16_of64(float (&x)[64], float (&t)[16]) {
;     float g[4][16];
; #pragma unroll
;     for (int q = 0; q < 4; ++q) {
; #pragma unroll
;         for (int i = 0; i < 16; ++i) g[q][i] = x[q * 16 + i];
;         sort16_desc(g[q]); }
;     merge_top16(g[0], g[1]); merge_top16(g[2], g[3]); merge_top16(g[0], g[2]);
; #pragma unroll
;     for (int i = 0; i < 16; ++i) t[i] = g[0][i];
; }
	v_min_f32_e32 v166, v51, v48
	v_min_f32_e32 v3, v4, v37
	v_min_f32_e32 v168, v1, v21
	v_min_f32_e32 v169, v36, v11
	v_min_f32_e32 v170, v6, v5
	v_min_f32_e32 v171, v35, v167
	v_min_f32_e32 v172, v12, v32
	v_min_f32_e32 v173, v34, v33
	v_min_f32_e32 v174, v2, v0
	v_max3_f32 v13, v13, v22, v158
	v_max3_f32 v22, v39, v41, v40
	v_max3_f32 v7, v7, v17, v157
	v_max3_f32 v17, v38, v150, v75
	v_max3_f32 v14, v14, v23, v156
	v_max3_f32 v23, v31, v47, v128
	v_max3_f32 v8, v8, v18, v155
	v_max3_f32 v18, v30, v148, v151
	v_max3_f32 v15, v15, v24, v154
	v_max3_f32 v24, v29, v43, v46
	v_max3_f32 v9, v9, v19, v153
	v_max3_f32 v19, v28, v147, v74
	v_max3_f32 v16, v16, v25, v152
	v_max3_f32 v25, v27, v44, v146
	v_max3_f32 v10, v10, v20, v42
	v_max3_f32 v20, v26, v45, v149
	v_max3_f32 v40, v50, v61, v174
	v_max3_f32 v0, v49, v2, v0
	v_max3_f32 v2, v52, v59, v173
	v_max3_f32 v33, v160, v34, v33
	v_max3_f32 v34, v60, v58, v172
	v_max3_f32 v12, v161, v12, v32
	v_max3_f32 v32, v53, v54, v171
	v_max3_f32 v35, v162, v35, v167
	v_max3_f32 v41, v62, v159, v170
	v_max3_f32 v5, v163, v6, v5
	v_max3_f32 v6, v55, v57, v169
	v_max3_f32 v11, v164, v36, v11
	v_max3_f32 v36, v63, v56, v168
	v_max3_f32 v1, v165, v1, v21
	v_max3_f32 v3, v51, v48, v3
	v_max3_f32 v4, v166, v4, v37
	v_max_f32_e32 v26, v13, v15
	v_min_f32_e32 v13, v13, v15
	v_max_f32_e32 v15, v22, v24
	v_min_f32_e32 v22, v22, v24
	v_max_f32_e32 v24, v7, v9
	v_min_f32_e32 v7, v7, v9
	v_max_f32_e32 v9, v17, v19
	v_min_f32_e32 v17, v17, v19
	v_max_f32_e32 v19, v14, v16
	v_min_f32_e32 v14, v14, v16
	v_max_f32_e32 v16, v23, v25
	v_min_f32_e32 v23, v23, v25
	v_max_f32_e32 v25, v8, v10
	v_min_f32_e32 v8, v8, v10
	v_max_f32_e32 v10, v18, v20
	v_min_f32_e32 v18, v18, v20
	v_max_f32_e32 v21, v40, v41
	v_min_f32_e32 v37, v40, v41
	v_max_f32_e32 v40, v0, v5
	v_min_f32_e32 v0, v0, v5
	v_max_f32_e32 v5, v2, v6
	v_min_f32_e32 v2, v2, v6
	v_max_f32_e32 v6, v33, v11
	v_min_f32_e32 v11, v33, v11
	v_max_f32_e32 v33, v34, v36
	v_min_f32_e32 v34, v34, v36
	v_max_f32_e32 v36, v12, v1
	v_min_f32_e32 v1, v12, v1
	v_max_f32_e32 v12, v32, v3
	v_min_f32_e32 v3, v32, v3
	v_max_f32_e32 v32, v35, v4
	v_min_f32_e32 v4, v35, v4
	v_max_f32_e32 v20, v26, v19
	v_min_f32_e32 v19, v26, v19
	v_max_f32_e32 v26, v15, v16
	v_min_f32_e32 v15, v15, v16
	v_max_f32_e32 v16, v24, v25
	v_min_f32_e32 v24, v24, v25
	v_max_f32_e32 v25, v9, v10
	v_min_f32_e32 v9, v9, v10
	v_max_f32_e32 v10, v13, v14
	v_min_f32_e32 v13, v13, v14
	v_max_f32_e32 v14, v22, v23
	v_min_f32_e32 v22, v22, v23
	v_max_f32_e32 v23, v7, v8
	v_min_f32_e32 v7, v7, v8
	v_max_f32_e32 v8, v17, v18
	v_min_f32_e32 v17, v17, v18
	v_max_f32_e32 v35, v21, v33
	v_min_f32_e32 v21, v21, v33
	v_max_f32_e32 v33, v40, v36
	v_min_f32_e32 v36, v40, v36
	v_max_f32_e32 v40, v5, v12
	v_min_f32_e32 v5, v5, v12
	v_max_f32_e32 v12, v6, v32
	v_min_f32_e32 v6, v6, v32
	v_max_f32_e32 v32, v37, v34
	v_min_f32_e32 v34, v37, v34
	v_max_f32_e32 v37, v0, v1
	v_min_f32_e32 v0, v0, v1
	v_max_f32_e32 v1, v2, v3
	v_min_f32_e32 v2, v2, v3
	v_max_f32_e32 v3, v11, v4
	v_min_f32_e32 v4, v11, v4
	v_max_f32_e32 v18, v20, v16
	v_min_f32_e32 v16, v20, v16
	v_max_f32_e32 v20, v26, v25
	v_min_f32_e32 v25, v26, v25
	v_max_f32_e32 v26, v19, v24
	v_min_f32_e32 v19, v19, v24
	v_max_f32_e32 v24, v15, v9
	v_min_f32_e32 v9, v15, v9
	v_max_f32_e32 v15, v10, v23
	v_min_f32_e32 v10, v10, v23
	v_max_f32_e32 v23, v14, v8
	v_min_f32_e32 v8, v14, v8
	v_max_f32_e32 v14, v13, v7
	v_min_f32_e32 v7, v13, v7
	v_max_f32_e32 v13, v22, v17
	v_min_f32_e32 v17, v22, v17
	v_max_f32_e32 v11, v35, v40
	v_min_f32_e32 v35, v35, v40
	v_max_f32_e32 v40, v33, v12
	v_min_f32_e32 v12, v33, v12
	v_max_f32_e32 v33, v21, v5
	v_min_f32_e32 v5, v21, v5
	v_max_f32_e32 v21, v36, v6
	v_min_f32_e32 v6, v36, v6
	v_max_f32_e32 v36, v32, v1
	v_min_f32_e32 v1, v32, v1
	v_max_f32_e32 v32, v37, v3
	v_min_f32_e32 v3, v37, v3
	v_max_f32_e32 v37, v34, v2
	v_min_f32_e32 v2, v34, v2
	v_max_f32_e32 v34, v0, v4
	v_min_f32_e32 v0, v0, v4
	v_min_f32_e32 v22, v18, v20
	v_min_f32_e32 v27, v16, v25
	v_min_f32_e32 v28, v26, v24
	v_min_f32_e32 v29, v19, v9
	v_min_f32_e32 v30, v15, v23
	v_min_f32_e32 v31, v10, v8
	v_min_f32_e32 v38, v14, v13
	v_min_f32_e32 v39, v7, v17
	v_min_f32_e32 v4, v11, v40
	v_min_f32_e32 v41, v35, v12
	v_min_f32_e32 v42, v33, v21
	v_min_f32_e32 v43, v5, v6
	v_min_f32_e32 v44, v36, v32
	v_min_f32_e32 v45, v1, v3
	v_min_f32_e32 v46, v37, v34
	v_min_f32_e32 v47, v2, v0
	v_max3_f32 v18, v18, v20, v47
	v_max3_f32 v0, v22, v2, v0
	v_max3_f32 v2, v16, v25, v46
	v_max3_f32 v16, v27, v37, v34
	v_max3_f32 v20, v26, v24, v45
	v_max3_f32 v1, v28, v1, v3
	v_max3_f32 v3, v19, v9, v44
	v_max3_f32 v9, v29, v36, v32
	v_max3_f32 v15, v15, v23, v43
	v_max3_f32 v5, v30, v5, v6
	v_max3_f32 v6, v10, v8, v42
	v_max3_f32 v8, v31, v33, v21
	v_max3_f32 v10, v14, v13, v41
	v_max3_f32 v12, v38, v35, v12
	v_max3_f32 v4, v7, v17, v4
	v_max3_f32 v7, v39, v11, v40
	v_max_f32_e32 v11, v18, v15
	v_min_f32_e32 v13, v18, v15
	v_max_f32_e32 v14, v0, v5
	v_min_f32_e32 v0, v0, v5
	v_max_f32_e32 v5, v2, v6
	v_min_f32_e32 v2, v2, v6
	v_max_f32_e32 v6, v16, v8
	v_min_f32_e32 v8, v16, v8
	v_max_f32_e32 v15, v20, v10
	v_min_f32_e32 v10, v20, v10
	v_max_f32_e32 v16, v1, v12
	v_min_f32_e32 v1, v1, v12
	v_max_f32_e32 v12, v3, v4
	v_min_f32_e32 v3, v3, v4
	v_max_f32_e32 v4, v9, v7
	v_min_f32_e32 v7, v9, v7
	v_max_f32_e32 v9, v11, v15
	v_min_f32_e32 v11, v11, v15
	v_max_f32_e32 v15, v14, v16
	v_min_f32_e32 v14, v14, v16
	v_max_f32_e32 v16, v5, v12
	v_min_f32_e32 v5, v5, v12
	v_max_f32_e32 v12, v6, v4
	v_min_f32_e32 v4, v6, v4
	v_max_f32_e32 v6, v13, v10
	v_min_f32_e32 v10, v13, v10
	v_max_f32_e32 v13, v0, v1
; DI void route_block(const Frame& F, int t0, int t1) {
;     ...
;             f32x16 acc[4];
; #pragma unroll
;             for (int kb = 0; kb < 4; ++kb)
; #pragma unroll
;                 for (int i = 0; i < 16; ++i) acc[kb][i] = 0.f;
;             const bf16* qp = F.Y + (size_t)tok * D + (h * 2 + p) * 128 + 8 * hh;
;             const bf16* kp = F.Keys + ((size_t)((h * 2 + p) * 128) + r32) * 128 + 8 * hh;
; #pragma unroll 4
;             for (int ks = 0; ks < 8; ++ks) {
;                 const bf16x8v bq = *(const bf16x8v*)(qp + ks * 16);
; #pragma unroll
;                 for (int kb = 0; kb < 4; ++kb) { const bf16x8v ak = *(const bf16x8v*)(kp + (size_t)kb * 32 * 128 + ks * 16);
;                     acc[kb] = __builtin_amdgcn_mfma_f32_32x32x16_bf16(ak, bq, acc[kb], 0, 0, 0); }
;             }
;     ...
;             float t[16], pb[16];
;             top16_of64(x, t);
; #pragma unroll
;             for (int i = 0; i < 16; ++i) pb[i] = __shfl_xor(t[i], 32);
;             merge_top16(t, pb);
	v_min_f32_e32 v0, v0, v1
	v_max_f32_e32 v1, v2, v3
	v_min_f32_e32 v2, v2, v3
	v_max_f32_e32 v3, v8, v7
	v_min_f32_e32 v7, v8, v7
	v_max_f32_e32 v8, v9, v16
	v_min_f32_e32 v9, v9, v16
	v_max_f32_e32 v16, v15, v12
	v_min_f32_e32 v12, v15, v12
	v_max_f32_e32 v15, v11, v5
	v_min_f32_e32 v5, v11, v5
	v_max_f32_e32 v11, v14, v4
	v_min_f32_e32 v4, v14, v4
	v_max_f32_e32 v14, v6, v1
	v_min_f32_e32 v1, v6, v1
	v_max_f32_e32 v6, v13, v3
	v_min_f32_e32 v3, v13, v3
	v_max_f32_e32 v13, v10, v2
	v_min_f32_e32 v2, v10, v2
	v_max_f32_e32 v10, v0, v7
	v_min_f32_e32 v0, v0, v7
	v_max_f32_e32 v165, v8, v16
	v_min_f32_e32 v164, v8, v16
	v_max_f32_e32 v162, v9, v12
	v_min_f32_e32 v161, v9, v12
	v_max_f32_e32 v159, v15, v11
	v_min_f32_e32 v158, v15, v11
	v_max_f32_e32 v156, v5, v4
	v_min_f32_e32 v155, v5, v4
	v_max_f32_e32 v153, v14, v6
	v_min_f32_e32 v152, v14, v6
	v_max_f32_e32 v150, v1, v3
	v_min_f32_e32 v149, v1, v3
	v_max_f32_e32 v147, v13, v10
	v_min_f32_e32 v146, v13, v10
	v_max_f32_e32 v75, v2, v0
	v_min_f32_e32 v74, v2, v0
	ds_bpermute_b32 v128, v78, v165
	ds_bpermute_b32 v148, v78, v164
	ds_bpermute_b32 v151, v78, v162
	ds_bpermute_b32 v154, v78, v161
	ds_bpermute_b32 v157, v78, v159
	ds_bpermute_b32 v160, v78, v158
	ds_bpermute_b32 v163, v78, v156
	ds_bpermute_b32 v166, v78, v155
	ds_bpermute_b32 v167, v78, v153
	ds_bpermute_b32 v168, v78, v152
	ds_bpermute_b32 v169, v78, v150
	ds_bpermute_b32 v170, v78, v149
	ds_bpermute_b32 v171, v78, v147
	ds_bpermute_b32 v172, v78, v146
	ds_bpermute_b32 v173, v78, v75
	ds_bpermute_b32 v174, v78, v74
	v_mov_b64_e32 v[0:1], 0
	v_lshl_add_u64 v[72:73], v[70:71], 0, v[72:73]
	s_mov_b64 s[8:9], 0
	v_mov_b64_e32 v[2:3], 0
	v_mov_b64_e32 v[4:5], 0
	v_mov_b64_e32 v[6:7], 0
	v_mov_b64_e32 v[8:9], 0
	v_mov_b64_e32 v[10:11], 0
	v_mov_b64_e32 v[12:13], 0
	v_mov_b64_e32 v[14:15], 0
	v_mov_b64_e32 v[32:33], 0
	v_mov_b64_e32 v[34:35], 0
	v_mov_b64_e32 v[36:37], 0
	v_mov_b64_e32 v[38:39], 0
	v_mov_b64_e32 v[40:41], 0
	v_mov_b64_e32 v[42:43], 0
	v_mov_b64_e32 v[44:45], 0
	v_mov_b64_e32 v[46:47], 0
	v_mov_b64_e32 v[48:49], 0
	v_mov_b64_e32 v[50:51], 0
	v_mov_b64_e32 v[52:53], 0
	v_mov_b64_e32 v[54:55], 0
	v_mov_b64_e32 v[56:57], 0
	v_mov_b64_e32 v[58:59], 0
	v_mov_b64_e32 v[60:61], 0
	v_mov_b64_e32 v[62:63], 0
	v_mov_b64_e32 v[16:17], 0
	v_mov_b64_e32 v[18:19], 0
	v_mov_b64_e32 v[20:21], 0
	v_mov_b64_e32 v[22:23], 0
	v_mov_b64_e32 v[24:25], 0
	v_mov_b64_e32 v[26:27], 0
	v_mov_b64_e32 v[28:29], 0
	v_mov_b64_e32 v[30:31], 0
	v_add_co_u32_e32 v188, vcc, s15, v68
	s_nop 1
	v_addc_co_u32_e32 v189, vcc, 0, v69, vcc
	v_add_co_u32_e32 v190, vcc, s16, v68
	s_nop 1
	v_addc_co_u32_e32 v191, vcc, 0, v69, vcc
	v_add_co_u32_e32 v192, vcc, s17, v68
	s_nop 1
	v_addc_co_u32_e32 v193, vcc, 0, v69, vcc
	v_add_co_u32_e32 v186, vcc, s10, v68
	s_nop 1
	v_addc_co_u32_e32 v187, vcc, 0, v69, vcc
	global_load_dwordx4 v[176:179], v[72:73], off offset:-64
	global_load_dwordx4 v[194:197], v[188:189], off offset:-4096
	global_load_dwordx4 v[198:201], v[190:191], off offset:-4096
	global_load_dwordx4 v[202:205], v[192:193], off offset:-4096
	global_load_dwordx4 v[208:211], v[186:187], off offset:-4096
	global_load_dwordx4 v[180:183], v[72:73], off offset:-32
	global_load_dwordx4 v[214:217], v[188:189], off offset:-3072
	global_load_dwordx4 v[218:221], v[190:191], off offset:-3072
	global_load_dwordx4 v[222:225], v[192:193], off offset:-3072
	global_load_dwordx4 v[226:229], v[186:187], off offset:-3072
	global_load_dwordx4 v[230:233], v[72:73], off offset:0
	global_load_dwordx4 v[234:237], v[72:73], off offset:32
	s_waitcnt vmcnt(10)
	v_mfma_f32_32x32x16_bf16 v[0:15], v[194:197], v[176:179], v[0:15]
	global_load_dwordx4 v[194:197], v[188:189], off offset:-2048
	s_waitcnt vmcnt(10)
	v_mfma_f32_32x32x16_bf16 v[32:47], v[198:201], v[176:179], v[32:47]
	global_load_dwordx4 v[198:201], v[190:191], off offset:-2048
	s_waitcnt vmcnt(10)
	v_mfma_f32_32x32x16_bf16 v[48:63], v[202:205], v[176:179], v[48:63]
	global_load_dwordx4 v[202:205], v[192:193], off offset:-2048
	s_waitcnt vmcnt(10)
	v_mfma_f32_32x32x16_bf16 v[16:31], v[208:211], v[176:179], v[16:31]
	global_load_dwordx4 v[208:211], v[186:187], off offset:-2048
	global_load_dwordx4 v[176:179], v[72:73], off offset:64
	s_waitcnt vmcnt(10)
	v_mfma_f32_32x32x16_bf16 v[0:15], v[214:217], v[180:183], v[0:15]
	global_load_dwordx4 v[214:217], v[188:189], off offset:-1024
	s_waitcnt vmcnt(10)
	v_mfma_f32_32x32x16_bf16 v[32:47], v[218:221], v[180:183], v[32:47]
	global_load_dwordx4 v[218:221], v[190:191], off offset:-1024
	s_waitcnt vmcnt(10)
	v_mfma_f32_32x32x16_bf16 v[48:63], v[222:225], v[180:183], v[48:63]
	global_load_dwordx4 v[222:225], v[192:193], off offset:-1024
	s_waitcnt vmcnt(10)
	v_mfma_f32_32x32x16_bf16 v[16:31], v[226:229], v[180:183], v[16:31]
	global_load_dwordx4 v[226:229], v[186:187], off offset:-1024
	global_load_dwordx4 v[180:183], v[72:73], off offset:96
	s_waitcnt vmcnt(9)
	v_mfma_f32_32x32x16_bf16 v[0:15], v[194:197], v[230:233], v[0:15]
	global_load_dwordx4 v[194:197], v[188:189], off
	s_waitcnt vmcnt(9)
	v_mfma_f32_32x32x16_bf16 v[32:47], v[198:201], v[230:233], v[32:47]
	global_load_dwordx4 v[198:201], v[190:191], off
	s_waitcnt vmcnt(9)
	v_mfma_f32_32x32x16_bf16 v[48:63], v[202:205], v[230:233], v[48:63]
	global_load_dwordx4 v[202:205], v[192:193], off
	s_waitcnt vmcnt(9)
	v_mfma_f32_32x32x16_bf16 v[16:31], v[208:211], v[230:233], v[16:31]
	global_load_dwordx4 v[208:211], v[186:187], off
	global_load_dwordx4 v[230:233], v[72:73], off offset:128
	s_waitcnt vmcnt(9)
	v_mfma_f32_32x32x16_bf16 v[0:15], v[214:217], v[234:237], v[0:15]
	global_load_dwordx4 v[214:217], v[188:189], off offset:1024
	s_waitcnt vmcnt(9)
; DI void route_block(const Frame& F, int t0, int t1) {
;     ...
;             for (int ks = 0; ks < 8; ++ks) {
;                 const bf16x8v bq = *(const bf16x8v*)(qp + ks * 16);
; #pragma unroll
;                 for (int kb = 0; kb < 4; ++kb) { const bf16x8v ak = *(const bf16x8v*)(kp + (size_t)kb * 32 * 128 + ks * 16);
;                     acc[kb] = __builtin_amdgcn_mfma_f32_32x32x16_bf16(ak, bq, acc[kb], 0, 0, 0); }
;             }
;             float x[64];
; #pragma unroll
;             for (int kb = 0; kb < 4; ++kb)
; #pragma unroll
;                 for (int i = 0; i < 16; ++i) { const unsigned key = (unsigned)(kb * 32 + (i & 3) + 8 * (i >> 2)) + 4u * (unsigned)hh;
;                     x[kb * 16 + i] = __uint_as_float((__float_as_uint(acc[kb][i]) & ~127u) | key); }
;             float t[16], pb[16];
;             top16_of64(x, t);
; #pragma unroll
;             for (int i = 0; i < 16; ++i) pb[i] = __shfl_xor(t[i], 32);
;             merge_top16(t, pb);
	v_mfma_f32_32x32x16_bf16 v[32:47], v[218:221], v[234:237], v[32:47]
	global_load_dwordx4 v[218:221], v[190:191], off offset:1024
	s_waitcnt vmcnt(9)
	v_mfma_f32_32x32x16_bf16 v[48:63], v[222:225], v[234:237], v[48:63]
	global_load_dwordx4 v[222:225], v[192:193], off offset:1024
	s_waitcnt vmcnt(9)
	v_mfma_f32_32x32x16_bf16 v[16:31], v[226:229], v[234:237], v[16:31]
	global_load_dwordx4 v[226:229], v[186:187], off offset:1024
	global_load_dwordx4 v[234:237], v[72:73], off offset:160
	s_waitcnt vmcnt(9)
	v_mfma_f32_32x32x16_bf16 v[0:15], v[194:197], v[176:179], v[0:15]
	global_load_dwordx4 v[194:197], v[188:189], off offset:2048
	s_waitcnt vmcnt(9)
	v_mfma_f32_32x32x16_bf16 v[32:47], v[198:201], v[176:179], v[32:47]
	global_load_dwordx4 v[198:201], v[190:191], off offset:2048
	s_waitcnt vmcnt(9)
	v_mfma_f32_32x32x16_bf16 v[48:63], v[202:205], v[176:179], v[48:63]
	global_load_dwordx4 v[202:205], v[192:193], off offset:2048
	s_waitcnt vmcnt(9)
	v_mfma_f32_32x32x16_bf16 v[16:31], v[208:211], v[176:179], v[16:31]
	global_load_dwordx4 v[208:211], v[186:187], off offset:2048
	s_waitcnt vmcnt(8)
	v_mfma_f32_32x32x16_bf16 v[0:15], v[214:217], v[180:183], v[0:15]
	global_load_dwordx4 v[214:217], v[188:189], off offset:3072
	s_waitcnt vmcnt(8)
	v_mfma_f32_32x32x16_bf16 v[32:47], v[218:221], v[180:183], v[32:47]
	global_load_dwordx4 v[218:221], v[190:191], off offset:3072
	s_waitcnt vmcnt(8)
	v_mfma_f32_32x32x16_bf16 v[48:63], v[222:225], v[180:183], v[48:63]
	global_load_dwordx4 v[222:225], v[192:193], off offset:3072
	s_waitcnt vmcnt(8)
	v_mfma_f32_32x32x16_bf16 v[16:31], v[226:229], v[180:183], v[16:31]
	global_load_dwordx4 v[226:229], v[186:187], off offset:3072
	s_waitcnt vmcnt(7)
	v_mfma_f32_32x32x16_bf16 v[0:15], v[194:197], v[230:233], v[0:15]
	s_waitcnt vmcnt(6)
	v_mfma_f32_32x32x16_bf16 v[32:47], v[198:201], v[230:233], v[32:47]
	s_waitcnt vmcnt(5)
	v_mfma_f32_32x32x16_bf16 v[48:63], v[202:205], v[230:233], v[48:63]
	s_waitcnt vmcnt(4)
	v_mfma_f32_32x32x16_bf16 v[16:31], v[208:211], v[230:233], v[16:31]
	s_waitcnt vmcnt(3)
	v_mfma_f32_32x32x16_bf16 v[0:15], v[214:217], v[234:237], v[0:15]
	s_waitcnt vmcnt(2)
	v_mfma_f32_32x32x16_bf16 v[32:47], v[218:221], v[234:237], v[32:47]
	s_waitcnt vmcnt(1)
	v_mfma_f32_32x32x16_bf16 v[48:63], v[222:225], v[234:237], v[48:63]
	s_waitcnt vmcnt(0)
	v_mfma_f32_32x32x16_bf16 v[16:31], v[226:229], v[234:237], v[16:31]
	s_nop 7
	s_nop 3
	s_waitcnt lgkmcnt(0)
	v_max_f32_e32 v72, v174, v174
	v_max_f32_e32 v73, v165, v165
	v_max_f32_e32 v72, v73, v72
	v_max_f32_e32 v73, v173, v173
	v_max_f32_e32 v164, v164, v164
	v_max_f32_e32 v73, v164, v73
	v_max_f32_e32 v164, v172, v172
	v_max_f32_e32 v162, v162, v162
	v_max_f32_e32 v162, v162, v164
	v_max_f32_e32 v164, v171, v171
	v_max_f32_e32 v161, v161, v161
	v_max_f32_e32 v161, v161, v164
	v_max_f32_e32 v164, v170, v170
	v_max_f32_e32 v159, v159, v159
	v_max_f32_e32 v159, v159, v164
	v_max_f32_e32 v164, v169, v169
	v_max_f32_e32 v158, v158, v158
	v_max_f32_e32 v158, v158, v164
	v_max_f32_e32 v164, v168, v168
	v_max_f32_e32 v156, v156, v156
	v_max_f32_e32 v156, v156, v164
	v_max_f32_e32 v164, v167, v167
	v_max_f32_e32 v155, v155, v155
	v_max_f32_e32 v155, v155, v164
	v_max_f32_e32 v164, v166, v166
	v_max_f32_e32 v153, v153, v153
	v_max_f32_e32 v163, v163, v163
	v_max_f32_e32 v152, v152, v152
	v_max_f32_e32 v160, v160, v160
	v_max_f32_e32 v150, v150, v150
	v_max_f32_e32 v157, v157, v157
	v_max_f32_e32 v149, v149, v149
	v_max_f32_e32 v154, v154, v154
	v_max_f32_e32 v147, v147, v147
	v_max_f32_e32 v151, v151, v151
	v_max_f32_e32 v146, v146, v146
	v_max_f32_e32 v148, v148, v148
	v_max_f32_e32 v75, v75, v75
	v_max_f32_e32 v128, v128, v128
	v_max_f32_e32 v74, v74, v74
	v_max_f32_e32 v153, v153, v164
	v_max_f32_e32 v152, v152, v163
	v_max_f32_e32 v150, v150, v160
	v_max_f32_e32 v149, v149, v157
	v_max_f32_e32 v147, v147, v154
	v_max_f32_e32 v146, v146, v151
	v_max_f32_e32 v75, v75, v148
	v_max_f32_e32 v74, v74, v128
	v_max_f32_e32 v128, v72, v153
	v_min_f32_e32 v72, v72, v153
	v_max_f32_e32 v148, v73, v152
	v_min_f32_e32 v73, v73, v152
	v_max_f32_e32 v151, v162, v150
	v_min_f32_e32 v150, v162, v150
	v_max_f32_e32 v152, v161, v149
	v_min_f32_e32 v149, v161, v149
	v_max_f32_e32 v153, v159, v147
	v_min_f32_e32 v147, v159, v147
	v_max_f32_e32 v154, v158, v146
	v_min_f32_e32 v146, v158, v146
	v_max_f32_e32 v157, v156, v75
	v_min_f32_e32 v75, v156, v75
	v_max_f32_e32 v156, v155, v74
	v_min_f32_e32 v74, v155, v74
	s_lshl_b32 s8, s12, 2
	v_max_f32_e32 v155, v128, v153
	v_min_f32_e32 v153, v128, v153
	v_max_f32_e32 v159, v148, v154
	v_min_f32_e32 v148, v148, v154
	v_max_f32_e32 v154, v151, v157
	v_min_f32_e32 v151, v151, v157
	v_max_f32_e32 v160, v152, v156
	v_min_f32_e32 v156, v152, v156
	v_max_f32_e32 v161, v72, v147
	v_min_f32_e32 v147, v72, v147
	v_max_f32_e32 v162, v73, v146
	v_min_f32_e32 v146, v73, v146
	v_max_f32_e32 v163, v150, v75
	v_min_f32_e32 v75, v150, v75
	v_max_f32_e32 v150, v149, v74
	v_min_f32_e32 v74, v149, v74
	s_andn2_b32 s8, s8, 31
	v_max_f32_e32 v149, v155, v154
	v_max_f32_e32 v164, v159, v160
	v_max_f32_e32 v166, v148, v156
	v_max_f32_e32 v167, v161, v163
	v_max_f32_e32 v168, v162, v150
	v_max_f32_e32 v169, v147, v75
	v_max_f32_e32 v170, v146, v74
	v_or_b32_e32 v72, s8, v76
	v_min_f32_e32 v154, v155, v154
	v_min_f32_e32 v159, v159, v160
	v_min_f32_e32 v160, v153, v151
	v_min_f32_e32 v148, v148, v156
	s_movk_i32 s8, 0xff80
	v_max_f32_e32 v165, v153, v151
	v_max_f32_e32 v157, v149, v164
	v_max_f32_e32 v128, v167, v168
	v_max_f32_e32 v73, v169, v170
	v_min_f32_e32 v161, v161, v163
	v_min_f32_e32 v162, v162, v150
	v_min_f32_e32 v163, v146, v74
	v_max_f32_e32 v155, v154, v159
; #define CE_DESC(a, b) do { const float _x = (a), _y = (b); (a) = fmaxf(_x, _y); (b) = fminf(_x, _y); } while (0)
; #define CE_ASC(a, b) do { const float _x = (a), _y = (b); (a) = fminf(_x, _y); (b) = fmaxf(_x, _y); } while (0)
; DI void sort16_desc(float (&x)[16]) {
; #pragma unroll
;     for (int k = 2; k <= 16; k <<= 1)
; #pragma unroll
;         for (int j = k >> 1; j > 0; j >>= 1)
; #pragma unroll
;             for (int i = 0; i < 16; ++i) { const int l = i ^ j; if (l > i) { if ((i & k) == 0) CE_DESC(x[i], x[l]); else CE_ASC(x[i], x[l]); } }
; }
; DI void merge_top16(float (&a)[16], const float (&b)[16]) {
; #pragma unroll
;     for (int i = 0; i < 16; ++i) a[i] = fmaxf(a[i], b[15 - i]);
; #pragma unroll
;     for (int j = 8; j > 0; j >>= 1)
; #pragma unroll
;         for (int i = 0; i < 16; ++i) { const int l = i ^ j; if (l > i) CE_DESC(a[i], a[l]); }
; }
; DI void top16_of64(float (&x)[64], float (&t)[16]) {
;     float g[4][16];
; #pragma unroll
;     for (int q = 0; q < 4; ++q) {
; #pragma unroll
;         for (int i = 0; i < 16; ++i) g[q][i] = x[q * 16 + i];
;         sort16_desc(g[q]); }
;     merge_top16(g[0], g[1]); merge_top16(g[2], g[3]); merge_top16(g[0], g[2]);
; #pragma unroll
;     for (int i = 0; i < 16; ++i) t[i] = g[0][i];
; }
; DI void route_block(const Frame& F, int t0, int t1) {
;     ...
;                 for (int i = 0; i < 16; ++i) { const unsigned key = (unsigned)(kb * 32 + (i & 3) + 8 * (i >> 2)) + 4u * (unsigned)hh;
;                     x[kb * 16 + i] = __uint_as_float((__float_as_uint(acc[kb][i]) & ~127u) | key); }
	v_max_f32_e32 v151, v160, v148
	v_min_f32_e32 v156, v149, v164
	v_min_f32_e32 v154, v154, v159
	v_min_f32_e32 v150, v160, v148
	v_min_f32_e32 v149, v167, v168
	v_min_f32_e32 v146, v169, v170
	v_and_or_b32 v159, v0, s8, v77
	v_and_or_b32 v160, v1, s8, v80
	v_and_or_b32 v168, v32, s8, v95
	v_and_or_b32 v169, v33, s8, v96
	v_min_f32_e32 v75, v147, v75
	v_max_f32_e32 v147, v161, v162
	v_min_f32_e32 v148, v161, v162
	v_and_or_b32 v161, v2, s8, v81
	v_and_or_b32 v162, v3, s8, v82
	v_and_or_b32 v170, v34, s8, v97
	v_and_or_b32 v171, v35, s8, v98
	v_and_or_b32 v173, v37, s8, v100
	v_and_or_b32 v35, v16, s8, v127
	v_and_or_b32 v37, v17, s8, v130
	v_max_f32_e32 v16, v160, v160
	v_max_f32_e32 v17, v159, v159
	v_max_f32_e32 v159, v169, v169
	v_max_f32_e32 v160, v168, v168
	v_max_f32_e32 v74, v75, v163
	v_min_f32_e32 v75, v75, v163
	v_and_or_b32 v163, v4, s8, v83
	v_and_or_b32 v164, v5, s8, v84
	v_and_or_b32 v172, v36, s8, v99
	v_and_or_b32 v48, v48, s8, v111
	v_and_or_b32 v49, v49, s8, v112
	v_and_or_b32 v33, v18, s8, v131
	v_and_or_b32 v36, v19, s8, v132
	v_max_f32_e32 v18, v17, v16
	v_min_f32_e32 v16, v17, v16
	v_max_f32_e32 v17, v162, v162
	v_max_f32_e32 v19, v161, v161
	v_max_f32_e32 v161, v160, v159
	v_min_f32_e32 v159, v160, v159
	v_max_f32_e32 v160, v171, v171
	v_max_f32_e32 v162, v170, v170
	v_max_f32_e32 v152, v165, v166
	v_min_f32_e32 v153, v165, v166
	v_and_or_b32 v165, v6, s8, v85
	v_and_or_b32 v166, v11, s8, v90
	v_and_or_b32 v175, v39, s8, v102
	v_and_or_b32 v50, v50, s8, v113
	v_and_or_b32 v51, v51, s8, v114
	v_and_or_b32 v32, v20, s8, v133
	v_and_or_b32 v11, v22, s8, v135
	v_min_f32_e32 v20, v19, v17
	v_max_f32_e32 v17, v19, v17
	v_max_f32_e32 v19, v164, v164
	v_max_f32_e32 v22, v163, v163
	v_min_f32_e32 v163, v162, v160
	v_max_f32_e32 v160, v162, v160
	v_max_f32_e32 v162, v173, v173
	v_max_f32_e32 v164, v172, v172
	v_max_f32_e32 v49, v49, v49
	v_max_f32_e32 v48, v48, v48
	v_and_or_b32 v52, v52, s8, v115
	v_and_or_b32 v53, v53, s8, v116
	v_and_or_b32 v34, v21, s8, v134
	v_and_or_b32 v21, v23, s8, v136
	v_max_f32_e32 v23, v22, v19
	v_min_f32_e32 v19, v22, v19
	v_max_f32_e32 v22, v165, v165
	v_max_f32_e32 v165, v164, v162
	v_min_f32_e32 v162, v164, v162
	v_max_f32_e32 v164, v175, v175
	v_max_f32_e32 v175, v48, v49
	v_min_f32_e32 v48, v48, v49
	v_max_f32_e32 v49, v51, v51
	v_max_f32_e32 v50, v50, v50
	v_and_or_b32 v7, v7, s8, v86
	v_and_or_b32 v8, v8, s8, v87
	v_and_or_b32 v9, v9, s8, v88
	v_and_or_b32 v54, v54, s8, v117
	v_and_or_b32 v55, v55, s8, v118
	v_min_f32_e32 v51, v50, v49
	v_max_f32_e32 v49, v50, v49
	v_max_f32_e32 v50, v53, v53
	v_max_f32_e32 v52, v52, v52
	v_and_or_b32 v10, v10, s8, v89
	v_and_or_b32 v174, v38, s8, v101
	v_and_or_b32 v40, v40, s8, v103
	v_and_or_b32 v41, v41, s8, v104
	v_and_or_b32 v56, v56, s8, v119
	v_and_or_b32 v57, v57, s8, v120
	v_max_f32_e32 v7, v7, v7
	v_max_f32_e32 v9, v9, v9
	v_max_f32_e32 v8, v8, v8
	v_max_f32_e32 v53, v52, v50
	v_min_f32_e32 v50, v52, v50
	v_max_f32_e32 v52, v55, v55
	v_max_f32_e32 v54, v54, v54
	v_and_or_b32 v167, v12, s8, v91
	v_and_or_b32 v13, v13, s8, v92
	v_and_or_b32 v42, v42, s8, v105
	v_and_or_b32 v43, v43, s8, v106
	v_and_or_b32 v58, v58, s8, v121
	v_and_or_b32 v59, v59, s8, v122
	v_and_or_b32 v5, v24, s8, v137
	v_min_f32_e32 v24, v22, v7
	v_max_f32_e32 v7, v22, v7
	v_max_f32_e32 v22, v8, v9
	v_min_f32_e32 v8, v8, v9
	v_max_f32_e32 v9, v166, v166
	v_max_f32_e32 v10, v10, v10
	v_max_f32_e32 v166, v174, v174
	v_max_f32_e32 v41, v41, v41
	v_max_f32_e32 v40, v40, v40
	v_min_f32_e32 v55, v54, v52
	v_max_f32_e32 v52, v54, v52
	v_max_f32_e32 v54, v57, v57
	v_max_f32_e32 v56, v56, v56
	v_and_or_b32 v44, v44, s8, v107
	v_and_or_b32 v45, v45, s8, v108
	v_and_or_b32 v60, v60, s8, v123
	v_and_or_b32 v61, v61, s8, v124
	v_and_or_b32 v12, v25, s8, v138
	v_min_f32_e32 v25, v10, v9
	v_max_f32_e32 v9, v10, v9
	v_max_f32_e32 v10, v13, v13
	v_max_f32_e32 v13, v167, v167
	v_min_f32_e32 v167, v166, v164
	v_max_f32_e32 v164, v166, v164
	v_max_f32_e32 v166, v40, v41
	v_min_f32_e32 v40, v40, v41
	v_max_f32_e32 v41, v43, v43
	v_max_f32_e32 v42, v42, v42
	v_max_f32_e32 v57, v56, v54
	v_min_f32_e32 v54, v56, v54
	v_max_f32_e32 v56, v59, v59
	v_max_f32_e32 v58, v58, v58
	v_and_or_b32 v14, v14, s8, v93
	v_and_or_b32 v15, v15, s8, v94
	v_and_or_b32 v46, v46, s8, v109
	v_and_or_b32 v47, v47, s8, v110
	v_and_or_b32 v62, v62, s8, v125
	v_and_or_b32 v63, v63, s8, v126
	v_and_or_b32 v3, v26, s8, v139
	v_and_or_b32 v6, v27, s8, v140
	v_and_or_b32 v1, v28, s8, v141
	v_and_or_b32 v4, v29, s8, v142
	v_and_or_b32 v0, v30, s8, v143
	v_and_or_b32 v2, v31, s8, v144
	v_min_f32_e32 v43, v42, v41
	v_max_f32_e32 v41, v42, v41
	v_max_f32_e32 v42, v45, v45
	v_max_f32_e32 v44, v44, v44
	v_min_f32_e32 v59, v58, v56
	v_max_f32_e32 v56, v58, v56
	v_max_f32_e32 v58, v61, v61
	v_max_f32_e32 v60, v60, v60
	v_max_f32_e32 v26, v13, v10
	v_min_f32_e32 v10, v13, v10
	v_max_f32_e32 v13, v15, v15
	v_max_f32_e32 v14, v14, v14
	v_max_f32_e32 v45, v44, v42
	v_min_f32_e32 v42, v44, v42
	v_max_f32_e32 v44, v47, v47
	v_max_f32_e32 v46, v46, v46
	v_max_f32_e32 v61, v60, v58
	v_min_f32_e32 v58, v60, v58
	v_max_f32_e32 v60, v63, v63
	v_max_f32_e32 v62, v62, v62
	v_max_f32_e32 v37, v37, v37
	v_max_f32_e32 v35, v35, v35
	v_max_f32_e32 v36, v36, v36
	v_max_f32_e32 v33, v33, v33
	v_max_f32_e32 v34, v34, v34
	v_max_f32_e32 v32, v32, v32
	v_max_f32_e32 v21, v21, v21
	v_max_f32_e32 v11, v11, v11
	v_max_f32_e32 v12, v12, v12
	v_max_f32_e32 v5, v5, v5
	v_max_f32_e32 v6, v6, v6
	v_max_f32_e32 v3, v3, v3
	v_max_f32_e32 v4, v4, v4
	v_max_f32_e32 v1, v1, v1
	v_max_f32_e32 v2, v2, v2
	v_max_f32_e32 v0, v0, v0
	v_min_f32_e32 v15, v14, v13
; #define CE_DESC(a, b) do { const float _x = (a), _y = (b); (a) = fmaxf(_x, _y); (b) = fminf(_x, _y); } while (0)
; #define CE_ASC(a, b) do { const float _x = (a), _y = (b); (a) = fminf(_x, _y); (b) = fmaxf(_x, _y); } while (0)
; DI void sort16_desc(float (&x)[16]) {
; #pragma unroll
;     for (int k = 2; k <= 16; k <<= 1)
; #pragma unroll
;         for (int j = k >> 1; j > 0; j >>= 1)
; #pragma unroll
;             for (int i = 0; i < 16; ++i) { const int l = i ^ j; if (l > i) { if ((i & k) == 0) CE_DESC(x[i], x[l]); else CE_ASC(x[i], x[l]); } }
; }
; DI void merge_top16(float (&a)[16], const float (&b)[16]) {
; #pragma unroll
;     for (int i = 0; i < 16; ++i) a[i] = fmaxf(a[i], b[15 - i]);
; #pragma unroll
;     for (int j = 8; j > 0; j >>= 1)
; #pragma unroll
;         for (int i = 0; i < 16; ++i) { const int l = i ^ j; if (l > i) CE_DESC(a[i], a[l]); }
; }
; DI void top16_of64(float (&x)[64], float (&t)[16]) {
;     float g[4][16];
; #pragma unroll
;     for (int q = 0; q < 4; ++q) {
; #pragma unroll
;         for (int i = 0; i < 16; ++i) g[q][i] = x[q * 16 + i];
;         sort16_desc(g[q]); }
;     merge_top16(g[0], g[1]); merge_top16(g[2], g[3]); merge_top16(g[0], g[2]);
; #pragma unroll
;     for (int i = 0; i < 16; ++i) t[i] = g[0][i];
; }
	v_max_f32_e32 v13, v14, v13
	v_min_f32_e32 v47, v46, v44
	v_max_f32_e32 v44, v46, v44
	v_min_f32_e32 v63, v62, v60
	v_max_f32_e32 v60, v62, v60
	v_max_f32_e32 v183, v35, v37
	v_min_f32_e32 v35, v35, v37
	v_min_f32_e32 v37, v33, v36
	v_max_f32_e32 v33, v33, v36
	v_max_f32_e32 v36, v32, v34
	v_min_f32_e32 v32, v32, v34
	v_min_f32_e32 v34, v11, v21
	v_max_f32_e32 v11, v11, v21
	v_max_f32_e32 v21, v5, v12
	v_min_f32_e32 v5, v5, v12
	v_min_f32_e32 v12, v3, v6
	v_max_f32_e32 v3, v3, v6
	v_max_f32_e32 v6, v1, v4
	v_min_f32_e32 v1, v1, v4
	v_min_f32_e32 v4, v0, v2
	v_max_f32_e32 v0, v0, v2
	v_max_f32_e32 v14, v18, v20
	v_min_f32_e32 v18, v18, v20
	v_max_f32_e32 v20, v16, v17
	v_min_f32_e32 v16, v16, v17
	v_min_f32_e32 v17, v23, v24
	v_max_f32_e32 v23, v23, v24
	v_min_f32_e32 v24, v19, v7
	v_max_f32_e32 v7, v19, v7
	v_max_f32_e32 v19, v22, v25
	v_min_f32_e32 v22, v22, v25
	v_max_f32_e32 v25, v8, v9
	v_min_f32_e32 v8, v8, v9
	v_min_f32_e32 v9, v26, v15
	v_max_f32_e32 v15, v26, v15
	v_min_f32_e32 v26, v10, v13
	v_max_f32_e32 v10, v10, v13
	v_max_f32_e32 v46, v161, v163
	v_min_f32_e32 v161, v161, v163
	v_max_f32_e32 v163, v159, v160
	v_min_f32_e32 v159, v159, v160
	v_min_f32_e32 v160, v165, v167
	v_max_f32_e32 v165, v165, v167
	v_min_f32_e32 v167, v162, v164
	v_max_f32_e32 v162, v162, v164
	v_max_f32_e32 v164, v166, v43
	v_min_f32_e32 v43, v166, v43
	v_max_f32_e32 v166, v40, v41
	v_min_f32_e32 v40, v40, v41
	v_min_f32_e32 v41, v45, v47
	v_max_f32_e32 v45, v45, v47
	v_min_f32_e32 v47, v42, v44
	v_max_f32_e32 v42, v42, v44
	v_max_f32_e32 v62, v175, v51
	v_min_f32_e32 v51, v175, v51
	v_max_f32_e32 v175, v48, v49
	v_min_f32_e32 v48, v48, v49
	v_min_f32_e32 v49, v53, v55
	v_max_f32_e32 v53, v53, v55
	v_min_f32_e32 v55, v50, v52
	v_max_f32_e32 v50, v50, v52
	v_max_f32_e32 v52, v57, v59
	v_min_f32_e32 v57, v57, v59
	v_max_f32_e32 v59, v54, v56
	v_min_f32_e32 v54, v54, v56
	v_min_f32_e32 v56, v61, v63
	v_max_f32_e32 v61, v61, v63
	v_min_f32_e32 v63, v58, v60
	v_max_f32_e32 v58, v58, v60
	v_max_f32_e32 v2, v183, v37
	v_min_f32_e32 v37, v183, v37
	v_max_f32_e32 v183, v35, v33
	v_min_f32_e32 v33, v35, v33
	v_min_f32_e32 v35, v36, v34
	v_max_f32_e32 v34, v36, v34
	v_min_f32_e32 v36, v32, v11
	v_max_f32_e32 v11, v32, v11
	v_max_f32_e32 v32, v21, v12
	v_min_f32_e32 v12, v21, v12
	v_max_f32_e32 v21, v5, v3
	v_min_f32_e32 v3, v5, v3
	v_min_f32_e32 v5, v6, v4
	v_max_f32_e32 v4, v6, v4
	v_min_f32_e32 v6, v1, v0
	v_max_f32_e32 v0, v1, v0
	v_max_f32_e32 v13, v14, v20
	v_min_f32_e32 v14, v14, v20
	v_max_f32_e32 v20, v18, v16
	v_min_f32_e32 v16, v18, v16
	v_min_f32_e32 v18, v17, v24
	v_max_f32_e32 v17, v17, v24
	v_min_f32_e32 v24, v23, v7
	v_max_f32_e32 v7, v23, v7
	v_max_f32_e32 v23, v19, v25
	v_min_f32_e32 v19, v19, v25
	v_max_f32_e32 v25, v22, v8
	v_min_f32_e32 v8, v22, v8
	v_min_f32_e32 v22, v9, v26
	v_max_f32_e32 v9, v9, v26
	v_min_f32_e32 v26, v15, v10
	v_max_f32_e32 v10, v15, v10
	v_max_f32_e32 v44, v46, v163
	v_min_f32_e32 v46, v46, v163
	v_max_f32_e32 v163, v161, v159
	v_min_f32_e32 v159, v161, v159
	v_min_f32_e32 v161, v160, v167
	v_max_f32_e32 v160, v160, v167
	v_min_f32_e32 v167, v165, v162
	v_max_f32_e32 v162, v165, v162
	v_max_f32_e32 v165, v164, v166
	v_min_f32_e32 v164, v164, v166
	v_max_f32_e32 v166, v43, v40
	v_min_f32_e32 v40, v43, v40
	v_min_f32_e32 v43, v41, v47
	v_max_f32_e32 v41, v41, v47
	v_min_f32_e32 v47, v45, v42
	v_max_f32_e32 v42, v45, v42
	v_max_f32_e32 v60, v62, v175
	v_min_f32_e32 v62, v62, v175
	v_max_f32_e32 v175, v51, v48
	v_min_f32_e32 v48, v51, v48
	v_min_f32_e32 v51, v49, v55
	v_max_f32_e32 v49, v49, v55
	v_min_f32_e32 v55, v53, v50
	v_max_f32_e32 v50, v53, v50
	v_max_f32_e32 v53, v52, v59
	v_min_f32_e32 v52, v52, v59
	v_max_f32_e32 v59, v57, v54
	v_min_f32_e32 v54, v57, v54
	v_min_f32_e32 v57, v56, v63
	v_max_f32_e32 v56, v56, v63
	v_min_f32_e32 v63, v61, v58
	v_max_f32_e32 v58, v61, v58
	v_max_f32_e32 v1, v2, v183
	v_min_f32_e32 v2, v2, v183
	v_max_f32_e32 v183, v37, v33
	v_min_f32_e32 v33, v37, v33
	v_min_f32_e32 v37, v35, v36
	v_max_f32_e32 v35, v35, v36
	v_min_f32_e32 v36, v34, v11
	v_max_f32_e32 v11, v34, v11
	v_max_f32_e32 v34, v32, v21
	v_min_f32_e32 v21, v32, v21
	v_max_f32_e32 v32, v12, v3
	v_min_f32_e32 v3, v12, v3
	v_min_f32_e32 v12, v5, v6
	v_max_f32_e32 v5, v5, v6
	v_min_f32_e32 v6, v4, v0
	v_max_f32_e32 v0, v4, v0
	v_max_f32_e32 v15, v13, v18
	v_min_f32_e32 v13, v13, v18
	v_max_f32_e32 v18, v14, v17
	v_min_f32_e32 v14, v14, v17
	v_max_f32_e32 v17, v20, v24
	v_min_f32_e32 v20, v20, v24
	v_max_f32_e32 v24, v16, v7
	v_min_f32_e32 v7, v16, v7
	v_min_f32_e32 v16, v23, v22
	v_max_f32_e32 v22, v23, v22
	v_min_f32_e32 v23, v19, v9
	v_max_f32_e32 v9, v19, v9
	v_min_f32_e32 v19, v25, v26
	v_max_f32_e32 v25, v25, v26
	v_min_f32_e32 v26, v8, v10
	v_max_f32_e32 v8, v8, v10
	v_max_f32_e32 v45, v44, v161
	v_min_f32_e32 v44, v44, v161
	v_max_f32_e32 v161, v46, v160
	v_min_f32_e32 v46, v46, v160
	v_max_f32_e32 v160, v163, v167
	v_min_f32_e32 v163, v163, v167
	v_max_f32_e32 v167, v159, v162
	v_min_f32_e32 v159, v159, v162
	v_min_f32_e32 v162, v165, v43
	v_max_f32_e32 v43, v165, v43
	v_min_f32_e32 v165, v164, v41
	v_max_f32_e32 v41, v164, v41
	v_min_f32_e32 v164, v166, v47
	v_max_f32_e32 v47, v166, v47
	v_min_f32_e32 v166, v40, v42
	v_max_f32_e32 v40, v40, v42
	v_max_f32_e32 v61, v60, v51
	v_min_f32_e32 v51, v60, v51
	v_max_f32_e32 v60, v62, v49
	v_min_f32_e32 v49, v62, v49
	v_max_f32_e32 v62, v175, v55
	v_min_f32_e32 v55, v175, v55
	v_max_f32_e32 v175, v48, v50
	v_min_f32_e32 v48, v48, v50
	v_min_f32_e32 v50, v53, v57
	v_max_f32_e32 v53, v53, v57
	v_min_f32_e32 v57, v52, v56
	v_max_f32_e32 v52, v52, v56
	v_min_f32_e32 v56, v59, v63
; #define CE_DESC(a, b) do { const float _x = (a), _y = (b); (a) = fmaxf(_x, _y); (b) = fminf(_x, _y); } while (0)
; #define CE_ASC(a, b) do { const float _x = (a), _y = (b); (a) = fminf(_x, _y); (b) = fmaxf(_x, _y); } while (0)
; DI void sort16_desc(float (&x)[16]) {
; #pragma unroll
;     for (int k = 2; k <= 16; k <<= 1)
; #pragma unroll
;         for (int j = k >> 1; j > 0; j >>= 1)
; #pragma unroll
;             for (int i = 0; i < 16; ++i) { const int l = i ^ j; if (l > i) { if ((i & k) == 0) CE_DESC(x[i], x[l]); else CE_ASC(x[i], x[l]); } }
; }
; DI void merge_top16(float (&a)[16], const float (&b)[16]) {
; #pragma unroll
;     for (int i = 0; i < 16; ++i) a[i] = fmaxf(a[i], b[15 - i]);
; #pragma unroll
;     for (int j = 8; j > 0; j >>= 1)
; #pragma unroll
;         for (int i = 0; i < 16; ++i) { const int l = i ^ j; if (l > i) CE_DESC(a[i], a[l]); }
; }
; DI void top16_of64(float (&x)[64], float (&t)[16]) {
;     float g[4][16];
; #pragma unroll
;     for (int q = 0; q < 4; ++q) {
; #pragma unroll
;         for (int i = 0; i < 16; ++i) g[q][i] = x[q * 16 + i];
;         sort16_desc(g[q]); }
;     merge_top16(g[0], g[1]); merge_top16(g[2], g[3]); merge_top16(g[0], g[2]);
; #pragma unroll
;     for (int i = 0; i < 16; ++i) t[i] = g[0][i];
; }
	v_max_f32_e32 v59, v59, v63
	v_min_f32_e32 v63, v54, v58
	v_max_f32_e32 v54, v54, v58
	v_max_f32_e32 v4, v1, v37
	v_min_f32_e32 v1, v1, v37
	v_max_f32_e32 v37, v2, v35
	v_min_f32_e32 v2, v2, v35
	v_max_f32_e32 v35, v183, v36
	v_min_f32_e32 v36, v183, v36
	v_max_f32_e32 v183, v33, v11
	v_min_f32_e32 v11, v33, v11
	v_min_f32_e32 v33, v34, v12
	v_max_f32_e32 v12, v34, v12
	v_min_f32_e32 v34, v21, v5
	v_max_f32_e32 v5, v21, v5
	v_min_f32_e32 v21, v32, v6
	v_max_f32_e32 v6, v32, v6
	v_min_f32_e32 v32, v3, v0
	v_max_f32_e32 v0, v3, v0
	v_max_f32_e32 v10, v15, v17
	v_min_f32_e32 v15, v15, v17
	v_max_f32_e32 v17, v18, v24
	v_min_f32_e32 v18, v18, v24
	v_max_f32_e32 v24, v13, v20
	v_min_f32_e32 v13, v13, v20
	v_max_f32_e32 v20, v14, v7
	v_min_f32_e32 v7, v14, v7
	v_min_f32_e32 v14, v16, v19
	v_max_f32_e32 v16, v16, v19
	v_min_f32_e32 v19, v23, v26
	v_max_f32_e32 v23, v23, v26
	v_min_f32_e32 v26, v22, v25
	v_max_f32_e32 v22, v22, v25
	v_min_f32_e32 v25, v9, v8
	v_max_f32_e32 v8, v9, v8
	v_max_f32_e32 v42, v45, v160
	v_min_f32_e32 v45, v45, v160
	v_max_f32_e32 v160, v161, v167
	v_min_f32_e32 v161, v161, v167
	v_max_f32_e32 v167, v44, v163
	v_min_f32_e32 v44, v44, v163
	v_max_f32_e32 v163, v46, v159
	v_min_f32_e32 v46, v46, v159
	v_min_f32_e32 v159, v162, v164
	v_max_f32_e32 v162, v162, v164
	v_min_f32_e32 v164, v165, v166
	v_max_f32_e32 v165, v165, v166
	v_min_f32_e32 v166, v43, v47
	v_max_f32_e32 v43, v43, v47
	v_min_f32_e32 v47, v41, v40
	v_max_f32_e32 v40, v41, v40
	v_max_f32_e32 v58, v61, v62
	v_min_f32_e32 v61, v61, v62
	v_max_f32_e32 v62, v60, v175
	v_min_f32_e32 v60, v60, v175
	v_max_f32_e32 v175, v51, v55
	v_min_f32_e32 v51, v51, v55
	v_max_f32_e32 v55, v49, v48
	v_min_f32_e32 v48, v49, v48
	v_min_f32_e32 v49, v50, v56
	v_max_f32_e32 v50, v50, v56
	v_min_f32_e32 v56, v57, v63
	v_max_f32_e32 v57, v57, v63
	v_min_f32_e32 v63, v53, v59
	v_max_f32_e32 v53, v53, v59
	v_min_f32_e32 v59, v52, v54
	v_max_f32_e32 v52, v52, v54
	v_max_f32_e32 v3, v4, v35
	v_min_f32_e32 v4, v4, v35
	v_max_f32_e32 v35, v37, v183
	v_min_f32_e32 v37, v37, v183
	v_max_f32_e32 v183, v1, v36
	v_min_f32_e32 v1, v1, v36
	v_max_f32_e32 v36, v2, v11
	v_min_f32_e32 v2, v2, v11
	v_min_f32_e32 v11, v33, v21
	v_max_f32_e32 v21, v33, v21
	v_min_f32_e32 v33, v34, v32
	v_max_f32_e32 v32, v34, v32
	v_min_f32_e32 v34, v12, v6
	v_max_f32_e32 v6, v12, v6
	v_min_f32_e32 v12, v5, v0
	v_max_f32_e32 v0, v5, v0
	v_max_f32_e32 v9, v10, v17
	v_min_f32_e32 v10, v10, v17
	v_max_f32_e32 v17, v15, v18
	v_min_f32_e32 v15, v15, v18
	v_max_f32_e32 v18, v24, v20
	v_min_f32_e32 v20, v24, v20
	v_max_f32_e32 v24, v13, v7
	v_min_f32_e32 v7, v13, v7
	v_min_f32_e32 v13, v14, v19
	v_max_f32_e32 v14, v14, v19
	v_min_f32_e32 v19, v16, v23
	v_max_f32_e32 v16, v16, v23
	v_min_f32_e32 v23, v26, v25
	v_max_f32_e32 v25, v26, v25
	v_min_f32_e32 v26, v22, v8
	v_max_f32_e32 v8, v22, v8
	v_max_f32_e32 v41, v42, v160
	v_min_f32_e32 v42, v42, v160
	v_max_f32_e32 v160, v45, v161
	v_min_f32_e32 v45, v45, v161
	v_max_f32_e32 v161, v167, v163
	v_min_f32_e32 v163, v167, v163
	v_max_f32_e32 v167, v44, v46
	v_min_f32_e32 v44, v44, v46
	v_min_f32_e32 v46, v159, v164
	v_max_f32_e32 v159, v159, v164
	v_min_f32_e32 v164, v162, v165
	v_max_f32_e32 v162, v162, v165
	v_min_f32_e32 v165, v166, v47
	v_max_f32_e32 v47, v166, v47
	v_min_f32_e32 v166, v43, v40
	v_max_f32_e32 v40, v43, v40
	v_max_f32_e32 v54, v58, v62
	v_min_f32_e32 v58, v58, v62
	v_max_f32_e32 v62, v61, v60
	v_min_f32_e32 v60, v61, v60
	v_max_f32_e32 v61, v175, v55
	v_min_f32_e32 v55, v175, v55
	v_max_f32_e32 v175, v51, v48
	v_min_f32_e32 v48, v51, v48
	v_min_f32_e32 v51, v49, v56
	v_max_f32_e32 v49, v49, v56
	v_min_f32_e32 v56, v50, v57
	v_max_f32_e32 v50, v50, v57
	v_min_f32_e32 v57, v63, v59
	v_max_f32_e32 v59, v63, v59
	v_min_f32_e32 v63, v53, v52
	v_max_f32_e32 v52, v53, v52
	v_max_f32_e32 v5, v3, v35
	v_min_f32_e32 v3, v3, v35
	v_max_f32_e32 v35, v4, v37
	v_min_f32_e32 v4, v4, v37
	v_max_f32_e32 v37, v183, v36
	v_min_f32_e32 v36, v183, v36
	v_max_f32_e32 v183, v1, v2
	v_min_f32_e32 v1, v1, v2
	v_min_f32_e32 v2, v11, v33
	v_max_f32_e32 v11, v11, v33
	v_min_f32_e32 v33, v21, v32
	v_max_f32_e32 v21, v21, v32
	v_min_f32_e32 v32, v34, v12
	v_max_f32_e32 v12, v34, v12
	v_min_f32_e32 v34, v6, v0
	v_max_f32_e32 v0, v6, v0
	v_max_f32_e32 v22, v9, v13
	v_min_f32_e32 v9, v9, v13
	v_max_f32_e32 v13, v10, v14
	v_min_f32_e32 v10, v10, v14
	v_max_f32_e32 v14, v17, v19
	v_min_f32_e32 v17, v17, v19
	v_max_f32_e32 v19, v15, v16
	v_min_f32_e32 v15, v15, v16
	v_max_f32_e32 v16, v18, v23
	v_min_f32_e32 v18, v18, v23
	v_max_f32_e32 v23, v20, v25
	v_min_f32_e32 v20, v20, v25
	v_max_f32_e32 v25, v24, v26
	v_min_f32_e32 v24, v24, v26
	v_max_f32_e32 v26, v7, v8
	v_min_f32_e32 v7, v7, v8
	v_max_f32_e32 v43, v41, v46
	v_min_f32_e32 v41, v41, v46
	v_max_f32_e32 v46, v42, v159
	v_min_f32_e32 v42, v42, v159
	v_max_f32_e32 v159, v160, v164
	v_min_f32_e32 v160, v160, v164
	v_max_f32_e32 v164, v45, v162
	v_min_f32_e32 v45, v45, v162
	v_max_f32_e32 v162, v161, v165
	v_min_f32_e32 v161, v161, v165
	v_max_f32_e32 v165, v163, v47
	v_min_f32_e32 v47, v163, v47
	v_max_f32_e32 v163, v167, v166
	v_min_f32_e32 v166, v167, v166
	v_max_f32_e32 v167, v44, v40
	v_min_f32_e32 v40, v44, v40
	v_max_f32_e32 v53, v54, v51
	v_min_f32_e32 v51, v54, v51
	v_max_f32_e32 v54, v58, v49
	v_min_f32_e32 v49, v58, v49
	v_max_f32_e32 v58, v62, v56
	v_min_f32_e32 v56, v62, v56
	v_max_f32_e32 v62, v60, v50
	v_min_f32_e32 v50, v60, v50
	v_max_f32_e32 v60, v61, v57
	v_min_f32_e32 v57, v61, v57
	v_max_f32_e32 v61, v55, v59
	v_min_f32_e32 v55, v55, v59
	v_max_f32_e32 v59, v175, v63
	v_min_f32_e32 v63, v175, v63
	v_max_f32_e32 v175, v48, v52
; #define CE_DESC(a, b) do { const float _x = (a), _y = (b); (a) = fmaxf(_x, _y); (b) = fminf(_x, _y); } while (0)
; #define CE_ASC(a, b) do { const float _x = (a), _y = (b); (a) = fminf(_x, _y); (b) = fmaxf(_x, _y); } while (0)
; DI void sort16_desc(float (&x)[16]) {
; #pragma unroll
;     for (int k = 2; k <= 16; k <<= 1)
; #pragma unroll
;         for (int j = k >> 1; j > 0; j >>= 1)
; #pragma unroll
;             for (int i = 0; i < 16; ++i) { const int l = i ^ j; if (l > i) { if ((i & k) == 0) CE_DESC(x[i], x[l]); else CE_ASC(x[i], x[l]); } }
; }
; DI void merge_top16(float (&a)[16], const float (&b)[16]) {
; #pragma unroll
;     for (int i = 0; i < 16; ++i) a[i] = fmaxf(a[i], b[15 - i]);
; #pragma unroll
;     for (int j = 8; j > 0; j >>= 1)
; #pragma unroll
;         for (int i = 0; i < 16; ++i) { const int l = i ^ j; if (l > i) CE_DESC(a[i], a[l]); }
; }
; DI void top16_of64(float (&x)[64], float (&t)[16]) {
;     float g[4][16];
; #pragma unroll
;     for (int q = 0; q < 4; ++q) {
; #pragma unroll
;         for (int i = 0; i < 16; ++i) g[q][i] = x[q * 16 + i];
;         sort16_desc(g[q]); }
;     merge_top16(g[0], g[1]); merge_top16(g[2], g[3]); merge_top16(g[0], g[2]);
; #pragma unroll
;     for (int i = 0; i < 16; ++i) t[i] = g[0][i];
; }
	v_min_f32_e32 v48, v48, v52
	v_max_f32_e32 v6, v5, v2
	v_min_f32_e32 v2, v5, v2
	v_max_f32_e32 v5, v3, v11
	v_min_f32_e32 v3, v3, v11
	v_max_f32_e32 v11, v35, v33
	v_min_f32_e32 v33, v35, v33
	v_max_f32_e32 v35, v4, v21
	v_min_f32_e32 v4, v4, v21
	v_max_f32_e32 v21, v37, v32
	v_min_f32_e32 v32, v37, v32
	v_max_f32_e32 v37, v36, v12
	v_min_f32_e32 v12, v36, v12
	v_max_f32_e32 v36, v183, v34
	v_min_f32_e32 v34, v183, v34
	v_max_f32_e32 v183, v1, v0
	v_min_f32_e32 v0, v1, v0
	v_max_f32_e32 v8, v22, v16
	v_min_f32_e32 v16, v22, v16
	v_max_f32_e32 v27, v13, v23
	v_min_f32_e32 v28, v13, v23
	v_max_f32_e32 v22, v14, v25
	v_min_f32_e32 v23, v14, v25
	v_max_f32_e32 v14, v19, v26
	v_min_f32_e32 v19, v19, v26
	v_max_f32_e32 v25, v9, v18
	v_min_f32_e32 v26, v9, v18
	v_max_f32_e32 v29, v10, v20
	v_min_f32_e32 v20, v10, v20
	v_max_f32_e32 v9, v17, v24
	v_min_f32_e32 v10, v17, v24
	v_max_f32_e32 v30, v15, v7
	v_min_f32_e32 v31, v15, v7
	v_max_f32_e32 v44, v43, v162
	v_min_f32_e32 v43, v43, v162
	v_max_f32_e32 v162, v46, v165
	v_min_f32_e32 v46, v46, v165
	v_max_f32_e32 v165, v159, v163
	v_min_f32_e32 v159, v159, v163
	v_max_f32_e32 v163, v164, v167
	v_min_f32_e32 v164, v164, v167
	v_max_f32_e32 v167, v41, v161
	v_min_f32_e32 v41, v41, v161
	v_max_f32_e32 v161, v42, v47
	v_min_f32_e32 v42, v42, v47
	v_max_f32_e32 v47, v160, v166
	v_min_f32_e32 v160, v160, v166
	v_max_f32_e32 v166, v45, v40
	v_min_f32_e32 v40, v45, v40
	v_max_f32_e32 v52, v53, v60
	v_min_f32_e32 v53, v53, v60
	v_max_f32_e32 v60, v54, v61
	v_min_f32_e32 v54, v54, v61
	v_max_f32_e32 v61, v58, v59
	v_min_f32_e32 v58, v58, v59
	v_max_f32_e32 v59, v62, v175
	v_min_f32_e32 v62, v62, v175
	v_max_f32_e32 v175, v51, v57
	v_min_f32_e32 v51, v51, v57
	v_max_f32_e32 v57, v49, v55
	v_min_f32_e32 v49, v49, v55
	v_max_f32_e32 v55, v56, v63
	v_min_f32_e32 v56, v56, v63
	v_max_f32_e32 v63, v50, v48
	v_min_f32_e32 v48, v50, v48
	v_max_f32_e32 v1, v6, v21
	v_min_f32_e32 v6, v6, v21
	v_max_f32_e32 v21, v5, v37
	v_min_f32_e32 v5, v5, v37
	v_max_f32_e32 v37, v11, v36
	v_min_f32_e32 v11, v11, v36
	v_max_f32_e32 v36, v35, v183
	v_min_f32_e32 v35, v35, v183
	v_max_f32_e32 v183, v2, v32
	v_min_f32_e32 v2, v2, v32
	v_max_f32_e32 v32, v3, v12
	v_min_f32_e32 v3, v3, v12
	v_max_f32_e32 v12, v33, v34
	v_min_f32_e32 v33, v33, v34
	v_max_f32_e32 v34, v4, v0
	v_min_f32_e32 v0, v4, v0
	v_max_f32_e32 v13, v8, v22
	v_min_f32_e32 v7, v8, v22
	v_max_f32_e32 v22, v27, v14
	v_min_f32_e32 v17, v27, v14
	v_max_f32_e32 v14, v16, v23
	v_min_f32_e32 v8, v16, v23
	v_max_f32_e32 v23, v28, v19
	v_min_f32_e32 v18, v28, v19
	v_max_f32_e32 v15, v25, v9
	v_min_f32_e32 v9, v25, v9
	v_max_f32_e32 v24, v29, v30
	v_min_f32_e32 v19, v29, v30
	v_max_f32_e32 v16, v26, v10
	v_min_f32_e32 v10, v26, v10
	v_max_f32_e32 v25, v20, v31
	v_min_f32_e32 v20, v20, v31
	v_max_f32_e32 v45, v44, v165
	v_min_f32_e32 v44, v44, v165
	v_max_f32_e32 v165, v162, v163
	v_min_f32_e32 v162, v162, v163
	v_max_f32_e32 v163, v43, v159
	v_min_f32_e32 v43, v43, v159
	v_max_f32_e32 v159, v46, v164
	v_min_f32_e32 v46, v46, v164
	v_max_f32_e32 v164, v167, v47
	v_min_f32_e32 v47, v167, v47
	v_max_f32_e32 v167, v161, v166
	v_min_f32_e32 v161, v161, v166
	v_max_f32_e32 v166, v41, v160
	v_min_f32_e32 v41, v41, v160
	v_max_f32_e32 v160, v42, v40
	v_min_f32_e32 v40, v42, v40
	v_max_f32_e32 v50, v52, v61
	v_min_f32_e32 v52, v52, v61
	v_max_f32_e32 v61, v60, v59
	v_min_f32_e32 v59, v60, v59
	v_max_f32_e32 v60, v53, v58
	v_min_f32_e32 v53, v53, v58
	v_max_f32_e32 v58, v54, v62
	v_min_f32_e32 v54, v54, v62
	v_max_f32_e32 v62, v175, v55
	v_min_f32_e32 v55, v175, v55
	v_max_f32_e32 v175, v57, v63
	v_min_f32_e32 v57, v57, v63
	v_max_f32_e32 v63, v51, v56
	v_min_f32_e32 v51, v51, v56
	v_max_f32_e32 v56, v49, v48
	v_min_f32_e32 v48, v49, v48
	v_max_f32_e32 v4, v1, v37
	v_min_f32_e32 v1, v1, v37
	v_max_f32_e32 v37, v21, v36
	v_min_f32_e32 v21, v21, v36
	v_max_f32_e32 v36, v6, v11
	v_min_f32_e32 v6, v6, v11
	v_max_f32_e32 v11, v5, v35
	v_min_f32_e32 v5, v5, v35
	v_max_f32_e32 v35, v183, v12
	v_min_f32_e32 v12, v183, v12
	v_max_f32_e32 v183, v32, v34
	v_min_f32_e32 v32, v32, v34
	v_max_f32_e32 v34, v2, v33
	v_min_f32_e32 v2, v2, v33
	v_max_f32_e32 v33, v3, v0
	v_min_f32_e32 v0, v3, v0
	v_min_f32_e32 v39, v13, v22
	v_min_f32_e32 v38, v7, v17
	v_min_f32_e32 v31, v14, v23
	v_min_f32_e32 v30, v8, v18
	v_min_f32_e32 v29, v15, v24
	v_min_f32_e32 v28, v9, v19
	v_min_f32_e32 v27, v16, v25
	v_min_f32_e32 v26, v10, v20
	v_min_f32_e32 v42, v45, v165
	v_min_f32_e32 v168, v44, v162
	v_min_f32_e32 v169, v163, v159
	v_min_f32_e32 v170, v43, v46
	v_min_f32_e32 v171, v164, v167
	v_min_f32_e32 v172, v47, v161
	v_min_f32_e32 v173, v166, v160
	v_min_f32_e32 v174, v41, v40
	v_min_f32_e32 v49, v50, v61
	v_min_f32_e32 v176, v52, v59
	v_min_f32_e32 v177, v60, v58
	v_min_f32_e32 v178, v53, v54
	v_min_f32_e32 v179, v62, v175
	v_min_f32_e32 v180, v55, v57
	v_min_f32_e32 v181, v63, v56
	v_min_f32_e32 v182, v51, v48
	v_min_f32_e32 v3, v4, v37
	v_min_f32_e32 v184, v1, v21
	v_min_f32_e32 v185, v36, v11
	v_min_f32_e32 v186, v6, v5
	v_min_f32_e32 v187, v35, v183
	v_min_f32_e32 v188, v12, v32
	v_min_f32_e32 v189, v34, v33
	v_min_f32_e32 v190, v2, v0
	v_max3_f32 v13, v13, v22, v174
	v_max3_f32 v22, v39, v41, v40
	v_max3_f32 v7, v7, v17, v173
	v_max3_f32 v17, v38, v166, v160
	v_max3_f32 v14, v14, v23, v172
	v_max3_f32 v23, v31, v47, v161
	v_max3_f32 v8, v8, v18, v171
	v_max3_f32 v18, v30, v164, v167
	v_max3_f32 v15, v15, v24, v170
	v_max3_f32 v24, v29, v43, v46
	v_max3_f32 v9, v9, v19, v169
	v_max3_f32 v19, v28, v163, v159
	v_max3_f32 v16, v16, v25, v168
	v_max3_f32 v25, v27, v44, v162
	v_max3_f32 v10, v10, v20, v42
; #define CE_DESC(a, b) do { const float _x = (a), _y = (b); (a) = fmaxf(_x, _y); (b) = fminf(_x, _y); } while (0)
; DI void merge_top16(float (&a)[16], const float (&b)[16]) {
; #pragma unroll
;     for (int i = 0; i < 16; ++i) a[i] = fmaxf(a[i], b[15 - i]);
; #pragma unroll
;     for (int j = 8; j > 0; j >>= 1)
; #pragma unroll
;         for (int i = 0; i < 16; ++i) { const int l = i ^ j; if (l > i) CE_DESC(a[i], a[l]); }
; }
; DI void top16_of64(float (&x)[64], float (&t)[16]) {
;     float g[4][16];
; #pragma unroll
;     for (int q = 0; q < 4; ++q) {
; #pragma unroll
;         for (int i = 0; i < 16; ++i) g[q][i] = x[q * 16 + i];
;         sort16_desc(g[q]); }
;     merge_top16(g[0], g[1]); merge_top16(g[2], g[3]); merge_top16(g[0], g[2]);
; #pragma unroll
;     for (int i = 0; i < 16; ++i) t[i] = g[0][i];
; }
; DI void route_block(const Frame& F, int t0, int t1) {
;     ...
;             for (int i = 0; i < 16; ++i) pb[i] = __shfl_xor(t[i], 32);
;             merge_top16(t, pb);
	v_max3_f32 v20, v26, v45, v165
	v_max3_f32 v40, v50, v61, v190
	v_max3_f32 v0, v49, v2, v0
	v_max3_f32 v2, v52, v59, v189
	v_max3_f32 v33, v176, v34, v33
	v_max3_f32 v34, v60, v58, v188
	v_max3_f32 v12, v177, v12, v32
	v_max3_f32 v32, v53, v54, v187
	v_max3_f32 v35, v178, v35, v183
	v_max3_f32 v41, v62, v175, v186
	v_max3_f32 v5, v179, v6, v5
	v_max3_f32 v6, v55, v57, v185
	v_max3_f32 v11, v180, v36, v11
	v_max3_f32 v36, v63, v56, v184
	v_max3_f32 v1, v181, v1, v21
	v_max3_f32 v3, v51, v48, v3
	v_max3_f32 v4, v182, v4, v37
	v_max_f32_e32 v26, v13, v15
	v_min_f32_e32 v13, v13, v15
	v_max_f32_e32 v15, v22, v24
	v_min_f32_e32 v22, v22, v24
	v_max_f32_e32 v24, v7, v9
	v_min_f32_e32 v7, v7, v9
	v_max_f32_e32 v9, v17, v19
	v_min_f32_e32 v17, v17, v19
	v_max_f32_e32 v19, v14, v16
	v_min_f32_e32 v14, v14, v16
	v_max_f32_e32 v16, v23, v25
	v_min_f32_e32 v23, v23, v25
	v_max_f32_e32 v25, v8, v10
	v_min_f32_e32 v8, v8, v10
	v_max_f32_e32 v10, v18, v20
	v_min_f32_e32 v18, v18, v20
	v_max_f32_e32 v21, v40, v41
	v_min_f32_e32 v37, v40, v41
	v_max_f32_e32 v40, v0, v5
	v_min_f32_e32 v0, v0, v5
	v_max_f32_e32 v5, v2, v6
	v_min_f32_e32 v2, v2, v6
	v_max_f32_e32 v6, v33, v11
	v_min_f32_e32 v11, v33, v11
	v_max_f32_e32 v33, v34, v36
	v_min_f32_e32 v34, v34, v36
	v_max_f32_e32 v36, v12, v1
	v_min_f32_e32 v1, v12, v1
	v_max_f32_e32 v12, v32, v3
	v_min_f32_e32 v3, v32, v3
	v_max_f32_e32 v32, v35, v4
	v_min_f32_e32 v4, v35, v4
	v_max_f32_e32 v20, v26, v19
	v_min_f32_e32 v19, v26, v19
	v_max_f32_e32 v26, v15, v16
	v_min_f32_e32 v15, v15, v16
	v_max_f32_e32 v16, v24, v25
	v_min_f32_e32 v24, v24, v25
	v_max_f32_e32 v25, v9, v10
	v_min_f32_e32 v9, v9, v10
	v_max_f32_e32 v10, v13, v14
	v_min_f32_e32 v13, v13, v14
	v_max_f32_e32 v14, v22, v23
	v_min_f32_e32 v22, v22, v23
	v_max_f32_e32 v23, v7, v8
	v_min_f32_e32 v7, v7, v8
	v_max_f32_e32 v8, v17, v18
	v_min_f32_e32 v17, v17, v18
	v_max_f32_e32 v35, v21, v33
	v_min_f32_e32 v21, v21, v33
	v_max_f32_e32 v33, v40, v36
	v_min_f32_e32 v36, v40, v36
	v_max_f32_e32 v40, v5, v12
	v_min_f32_e32 v5, v5, v12
	v_max_f32_e32 v12, v6, v32
	v_min_f32_e32 v6, v6, v32
	v_max_f32_e32 v32, v37, v34
	v_min_f32_e32 v34, v37, v34
	v_max_f32_e32 v37, v0, v1
	v_min_f32_e32 v0, v0, v1
	v_max_f32_e32 v1, v2, v3
	v_min_f32_e32 v2, v2, v3
	v_max_f32_e32 v3, v11, v4
	v_min_f32_e32 v4, v11, v4
	v_max_f32_e32 v18, v20, v16
	v_min_f32_e32 v16, v20, v16
	v_max_f32_e32 v20, v26, v25
	v_min_f32_e32 v25, v26, v25
	v_max_f32_e32 v26, v19, v24
	v_min_f32_e32 v19, v19, v24
	v_max_f32_e32 v24, v15, v9
	v_min_f32_e32 v9, v15, v9
	v_max_f32_e32 v15, v10, v23
	v_min_f32_e32 v10, v10, v23
	v_max_f32_e32 v23, v14, v8
	v_min_f32_e32 v8, v14, v8
	v_max_f32_e32 v14, v13, v7
	v_min_f32_e32 v7, v13, v7
	v_max_f32_e32 v13, v22, v17
	v_min_f32_e32 v17, v22, v17
	v_max_f32_e32 v11, v35, v40
	v_min_f32_e32 v35, v35, v40
	v_max_f32_e32 v40, v33, v12
	v_min_f32_e32 v12, v33, v12
	v_max_f32_e32 v33, v21, v5
	v_min_f32_e32 v5, v21, v5
	v_max_f32_e32 v21, v36, v6
	v_min_f32_e32 v6, v36, v6
	v_max_f32_e32 v36, v32, v1
	v_min_f32_e32 v1, v32, v1
	v_max_f32_e32 v32, v37, v3
	v_min_f32_e32 v3, v37, v3
	v_max_f32_e32 v37, v34, v2
	v_min_f32_e32 v2, v34, v2
	v_max_f32_e32 v34, v0, v4
	v_min_f32_e32 v0, v0, v4
	v_min_f32_e32 v22, v18, v20
	v_min_f32_e32 v27, v16, v25
	v_min_f32_e32 v28, v26, v24
	v_min_f32_e32 v29, v19, v9
	v_min_f32_e32 v30, v15, v23
	v_min_f32_e32 v31, v10, v8
	v_min_f32_e32 v38, v14, v13
	v_min_f32_e32 v39, v7, v17
	v_min_f32_e32 v4, v11, v40
	v_min_f32_e32 v41, v35, v12
	v_min_f32_e32 v42, v33, v21
	v_min_f32_e32 v43, v5, v6
	v_min_f32_e32 v44, v36, v32
	v_min_f32_e32 v45, v1, v3
	v_min_f32_e32 v46, v37, v34
	v_min_f32_e32 v47, v2, v0
	v_max3_f32 v18, v18, v20, v47
	v_max3_f32 v0, v22, v2, v0
	v_max3_f32 v2, v16, v25, v46
	v_max3_f32 v16, v27, v37, v34
	v_max3_f32 v20, v26, v24, v45
	v_max3_f32 v1, v28, v1, v3
	v_max3_f32 v3, v19, v9, v44
	v_max3_f32 v9, v29, v36, v32
	v_max3_f32 v15, v15, v23, v43
	v_max3_f32 v5, v30, v5, v6
	v_max3_f32 v6, v10, v8, v42
	v_max3_f32 v8, v31, v33, v21
	v_max3_f32 v10, v14, v13, v41
	v_max3_f32 v12, v38, v35, v12
	v_max3_f32 v4, v7, v17, v4
	v_max3_f32 v7, v39, v11, v40
	v_max_f32_e32 v11, v18, v15
	v_min_f32_e32 v13, v18, v15
	v_max_f32_e32 v14, v0, v5
	v_min_f32_e32 v0, v0, v5
	v_max_f32_e32 v5, v2, v6
	v_min_f32_e32 v2, v2, v6
	v_max_f32_e32 v6, v16, v8
	v_min_f32_e32 v8, v16, v8
	v_max_f32_e32 v15, v20, v10
	v_min_f32_e32 v10, v20, v10
	v_max_f32_e32 v16, v1, v12
	v_min_f32_e32 v1, v1, v12
	v_max_f32_e32 v12, v3, v4
	v_min_f32_e32 v3, v3, v4
	v_max_f32_e32 v4, v9, v7
	v_min_f32_e32 v7, v9, v7
	v_max_f32_e32 v9, v11, v15
	v_min_f32_e32 v11, v11, v15
	v_max_f32_e32 v15, v14, v16
	v_min_f32_e32 v14, v14, v16
	v_max_f32_e32 v16, v5, v12
	v_min_f32_e32 v5, v5, v12
	v_max_f32_e32 v12, v6, v4
	v_min_f32_e32 v4, v6, v4
	v_max_f32_e32 v6, v13, v10
	v_min_f32_e32 v10, v13, v10
	v_max_f32_e32 v13, v0, v1
	v_min_f32_e32 v0, v0, v1
	v_max_f32_e32 v1, v2, v3
	v_min_f32_e32 v2, v2, v3
	v_max_f32_e32 v3, v8, v7
	v_min_f32_e32 v7, v8, v7
	v_max_f32_e32 v8, v9, v16
	v_min_f32_e32 v9, v9, v16
	v_max_f32_e32 v16, v15, v12
	v_min_f32_e32 v12, v15, v12
	v_max_f32_e32 v15, v11, v5
	v_min_f32_e32 v5, v11, v5
	v_max_f32_e32 v11, v14, v4
	v_min_f32_e32 v4, v14, v4
	v_max_f32_e32 v14, v6, v1
	v_min_f32_e32 v1, v6, v1
	v_max_f32_e32 v6, v13, v3
	v_min_f32_e32 v3, v13, v3
	v_max_f32_e32 v13, v10, v2
	v_min_f32_e32 v2, v10, v2
	v_max_f32_e32 v10, v0, v7
	v_min_f32_e32 v0, v0, v7
	v_max_f32_e32 v7, v8, v16
	v_min_f32_e32 v8, v8, v16
	v_max_f32_e32 v16, v9, v12
	v_min_f32_e32 v9, v9, v12
	v_max_f32_e32 v12, v15, v11
	v_min_f32_e32 v11, v15, v11
	v_max_f32_e32 v15, v5, v4
	v_min_f32_e32 v4, v5, v4
	v_max_f32_e32 v5, v14, v6
	v_min_f32_e32 v6, v14, v6
	v_max_f32_e32 v14, v1, v3
	v_min_f32_e32 v1, v1, v3
	v_max_f32_e32 v3, v13, v10
	v_min_f32_e32 v10, v13, v10
	v_max_f32_e32 v13, v2, v0
	v_min_f32_e32 v0, v2, v0
	ds_bpermute_b32 v27, v78, v0
	ds_bpermute_b32 v29, v78, v13
	ds_bpermute_b32 v31, v78, v10
	ds_bpermute_b32 v30, v78, v3
	ds_bpermute_b32 v2, v78, v7
	ds_bpermute_b32 v17, v78, v8
	ds_bpermute_b32 v18, v78, v16
	ds_bpermute_b32 v19, v78, v9
	ds_bpermute_b32 v20, v78, v12
	ds_bpermute_b32 v21, v78, v11
	ds_bpermute_b32 v22, v78, v15
	ds_bpermute_b32 v23, v78, v4
	ds_bpermute_b32 v24, v78, v5
	ds_bpermute_b32 v25, v78, v6
	ds_bpermute_b32 v26, v78, v14
	ds_bpermute_b32 v28, v78, v1
	s_waitcnt lgkmcnt(14)
; DI void route_block(const Frame& F, int t0, int t1) {
;     ...
;             merge_top16(t, pb);
; #pragma unroll
;             for (int i = 0; i < 16; ++i) tv[p][i] = t[i];
;         }
; #pragma unroll
;         for (int w = 0; w < 8; ++w) { unsigned pk = 0;
; #pragma unroll
;             for (int b = 0; b < 4; ++b) { const int i = w * 4 + b; pk |= (__float_as_uint(i < 16 ? tv[0][i] : tv[1][i - 16]) & 127u) << (8 * b); }
;             kl[w * 64 + lane] = pk; }
;     ...
;         if (valid) {
	v_max_f32_e32 v27, v27, v27
	v_max_f32_e32 v7, v7, v27
	v_max_f32_e32 v27, v29, v29
	v_max_f32_e32 v8, v8, v27
	s_waitcnt lgkmcnt(13)
	v_max_f32_e32 v27, v31, v31
	v_max_f32_e32 v16, v16, v27
	s_waitcnt lgkmcnt(12)
	v_max_f32_e32 v27, v30, v30
	v_max_f32_e32 v9, v9, v27
	s_waitcnt lgkmcnt(0)
	v_max_f32_e32 v27, v28, v28
	v_max_f32_e32 v26, v26, v26
	v_max_f32_e32 v25, v25, v25
	v_max_f32_e32 v24, v24, v24
	v_max_f32_e32 v23, v23, v23
	v_max_f32_e32 v22, v22, v22
	v_max_f32_e32 v21, v21, v21
	v_max_f32_e32 v20, v20, v20
	v_max_f32_e32 v19, v19, v19
	v_max_f32_e32 v18, v18, v18
	v_max_f32_e32 v17, v17, v17
	v_max_f32_e32 v2, v2, v2
	v_max_f32_e32 v12, v12, v27
	v_max_f32_e32 v11, v11, v26
	v_max_f32_e32 v15, v15, v25
	v_max_f32_e32 v4, v4, v24
	v_max_f32_e32 v5, v5, v23
	v_max_f32_e32 v6, v6, v22
	v_max_f32_e32 v14, v14, v21
	v_max_f32_e32 v1, v1, v20
	v_max_f32_e32 v3, v3, v19
	v_max_f32_e32 v10, v10, v18
	v_max_f32_e32 v13, v13, v17
	v_max_f32_e32 v0, v0, v2
	v_max_f32_e32 v2, v7, v5
	v_min_f32_e32 v5, v7, v5
	v_max_f32_e32 v7, v8, v6
	v_min_f32_e32 v6, v8, v6
	v_max_f32_e32 v8, v16, v14
	v_min_f32_e32 v14, v16, v14
	v_max_f32_e32 v16, v9, v1
	v_min_f32_e32 v1, v9, v1
	v_max_f32_e32 v9, v12, v3
	v_min_f32_e32 v3, v12, v3
	v_max_f32_e32 v12, v11, v10
	v_min_f32_e32 v10, v11, v10
	v_max_f32_e32 v11, v15, v13
	v_min_f32_e32 v13, v15, v13
	v_max_f32_e32 v15, v4, v0
	v_min_f32_e32 v0, v4, v0
	v_max_f32_e32 v4, v2, v9
	v_min_f32_e32 v2, v2, v9
	v_max_f32_e32 v9, v7, v12
	v_min_f32_e32 v7, v7, v12
	v_max_f32_e32 v12, v8, v11
	v_min_f32_e32 v8, v8, v11
	v_max_f32_e32 v11, v16, v15
	v_min_f32_e32 v15, v16, v15
	v_max_f32_e32 v16, v5, v3
	v_min_f32_e32 v3, v5, v3
	v_max_f32_e32 v5, v6, v10
	v_min_f32_e32 v6, v6, v10
	v_max_f32_e32 v10, v14, v13
	v_min_f32_e32 v13, v14, v13
	v_max_f32_e32 v14, v1, v0
	v_min_f32_e32 v0, v1, v0
	v_max_f32_e32 v1, v4, v12
	v_min_f32_e32 v4, v4, v12
	v_max_f32_e32 v12, v9, v11
	v_min_f32_e32 v9, v9, v11
	v_max_f32_e32 v17, v2, v8
	v_min_f32_e32 v2, v2, v8
	v_max_f32_e32 v8, v7, v15
	v_max_f32_e32 v18, v16, v10
	v_min_f32_e32 v16, v16, v10
	v_min_f32_e32 v20, v5, v14
	v_min_f32_e32 v7, v7, v15
	v_max_f32_e32 v19, v5, v14
	v_max_f32_e32 v21, v3, v13
	v_min_f32_e32 v22, v3, v13
	v_max_f32_e32 v15, v1, v12
	v_min_f32_e32 v14, v1, v12
	v_max_f32_e32 v13, v4, v9
	v_min_f32_e32 v12, v4, v9
	v_max_f32_e32 v11, v17, v8
	v_min_f32_e32 v10, v17, v8
	v_max_f32_e32 v5, v16, v20
	v_min_f32_e32 v4, v16, v20
	v_and_b32_e32 v16, 0x7f, v157
	v_lshlrev_b32_e32 v17, 8, v156
	s_movk_i32 s8, 0x7f00
	v_max_f32_e32 v23, v6, v0
	v_min_f32_e32 v0, v6, v0
	v_max_f32_e32 v9, v2, v7
	v_min_f32_e32 v8, v2, v7
	v_max_f32_e32 v7, v18, v19
	v_min_f32_e32 v6, v18, v19
	v_and_or_b32 v16, v17, s8, v16
	v_lshlrev_b32_e32 v17, 16, v155
	v_lshlrev_b32_e32 v18, 24, v154
	v_and_b32_e32 v17, 0x7f0000, v17
	v_and_b32_e32 v18, 0x7f000000, v18
	v_or3_b32 v16, v16, v17, v18
	v_and_b32_e32 v17, 0x7f, v152
	v_lshlrev_b32_e32 v18, 8, v153
	v_and_or_b32 v17, v18, s8, v17
	v_lshlrev_b32_e32 v18, 16, v151
	v_lshlrev_b32_e32 v19, 24, v150
	v_and_b32_e32 v18, 0x7f0000, v18
	v_and_b32_e32 v19, 0x7f000000, v19
	v_or3_b32 v17, v17, v18, v19
	ds_write2st64_b32 v79, v16, v17 offset1:1
	v_and_b32_e32 v16, 0x7f, v128
	v_lshlrev_b32_e32 v17, 8, v149
	v_and_or_b32 v16, v17, s8, v16
	v_lshlrev_b32_e32 v17, 16, v147
	v_lshlrev_b32_e32 v18, 24, v148
	v_and_b32_e32 v17, 0x7f0000, v17
	v_and_b32_e32 v18, 0x7f000000, v18
	v_or3_b32 v16, v16, v17, v18
	v_and_b32_e32 v17, 0x7f, v73
	v_lshlrev_b32_e32 v18, 8, v146
	v_and_or_b32 v17, v18, s8, v17
	v_lshlrev_b32_e32 v18, 16, v74
	v_lshlrev_b32_e32 v19, 24, v75
	v_and_b32_e32 v18, 0x7f0000, v18
	v_and_b32_e32 v19, 0x7f000000, v19
	v_or3_b32 v17, v17, v18, v19
	ds_write2st64_b32 v79, v16, v17 offset0:2 offset1:3
	v_and_b32_e32 v16, 0x7f, v15
	v_lshlrev_b32_e32 v17, 8, v14
	v_and_or_b32 v16, v17, s8, v16
	v_lshlrev_b32_e32 v17, 16, v13
	v_lshlrev_b32_e32 v18, 24, v12
	v_and_b32_e32 v17, 0x7f0000, v17
	v_and_b32_e32 v18, 0x7f000000, v18
	v_or3_b32 v16, v16, v17, v18
	v_and_b32_e32 v17, 0x7f, v11
	v_lshlrev_b32_e32 v18, 8, v10
	v_and_or_b32 v17, v18, s8, v17
	v_lshlrev_b32_e32 v18, 16, v9
	v_lshlrev_b32_e32 v19, 24, v8
	v_and_b32_e32 v18, 0x7f0000, v18
	v_and_b32_e32 v19, 0x7f000000, v19
	v_or3_b32 v17, v17, v18, v19
	ds_write2st64_b32 v79, v16, v17 offset0:4 offset1:5
	v_and_b32_e32 v16, 0x7f, v7
	v_lshlrev_b32_e32 v17, 8, v6
	v_and_or_b32 v16, v17, s8, v16
	v_lshlrev_b32_e32 v17, 16, v5
	v_lshlrev_b32_e32 v18, 24, v4
	v_max_f32_e32 v3, v21, v23
	v_min_f32_e32 v2, v21, v23
	v_and_b32_e32 v17, 0x7f0000, v17
	v_and_b32_e32 v18, 0x7f000000, v18
	v_max_f32_e32 v1, v22, v0
	v_min_f32_e32 v0, v22, v0
	v_or3_b32 v16, v16, v17, v18
	v_and_b32_e32 v17, 0x7f, v3
	v_lshlrev_b32_e32 v18, 8, v2
	v_and_or_b32 v17, v18, s8, v17
	v_lshlrev_b32_e32 v18, 16, v1
	v_lshlrev_b32_e32 v19, 24, v0
	v_and_b32_e32 v18, 0x7f0000, v18
	v_and_b32_e32 v19, 0x7f000000, v19
	v_or3_b32 v17, v17, v18, v19
	ds_write2st64_b32 v79, v16, v17 offset0:6 offset1:7
	s_waitcnt lgkmcnt(0)
	v_add_u32_e32 v158, s0, v72
	v_cmp_gt_i32_e32 vcc, s13, v158
	s_and_saveexec_b64 s[8:9], vcc
	s_cbranch_execz .LBB0_911
; #define CE_DESC(a, b) do { const float _x = (a), _y = (b); (a) = fmaxf(_x, _y); (b) = fminf(_x, _y); } while (0)
; #define CE_ASC(a, b) do { const float _x = (a), _y = (b); (a) = fminf(_x, _y); (b) = fmaxf(_x, _y); } while (0)
; DI void sort16_desc(float (&x)[16]) {
; #pragma unroll
;     for (int k = 2; k <= 16; k <<= 1)
; #pragma unroll
;         for (int j = k >> 1; j > 0; j >>= 1)
; #pragma unroll
;             for (int i = 0; i < 16; ++i) { const int l = i ^ j; if (l > i) { if ((i & k) == 0) CE_DESC(x[i], x[l]); else CE_ASC(x[i], x[l]); } }
; }
; DI void route_block(const Frame& F, int t0, int t1) {
;     ...
;         float x[64];
; #pragma unroll
;         for (int i = 0; i < 64; ++i) x[i] = NEG;
; #pragma unroll
;         for (int i = 0; i < 16; ++i)
; #pragma unroll
;             for (int j = 0; j < 16; ++j) if ((i + 1) * (j + 1) <= 16) {
;                 const float sa = __uint_as_float(__float_as_uint(tv[0][i]) & ~127u), sb = __uint_as_float(__float_as_uint(tv[1][j]) & ~127u);
;                 x[cand_off(i) + j] = __uint_as_float((__float_as_uint(sa + sb) & ~255u) | (unsigned)(i * 16 + j)); }
	v_and_b32_e32 v16, 0xffffff80, v157
	v_and_b32_e32 v0, 0xffffff80, v0
	v_and_b32_e32 v15, 0xffffff80, v15
	v_and_b32_e32 v14, 0xffffff80, v14
	s_movk_i32 s10, 0xff00
	v_and_b32_e32 v13, 0xffffff80, v13
	v_and_b32_e32 v12, 0xffffff80, v12
	v_and_b32_e32 v11, 0xffffff80, v11
	v_and_b32_e32 v10, 0xffffff80, v10
	v_and_b32_e32 v9, 0xffffff80, v9
	v_and_b32_e32 v8, 0xffffff80, v8
	v_and_b32_e32 v7, 0xffffff80, v7
	v_and_b32_e32 v6, 0xffffff80, v6
	v_and_b32_e32 v5, 0xffffff80, v5
	v_and_b32_e32 v4, 0xffffff80, v4
	v_and_b32_e32 v3, 0xffffff80, v3
	v_and_b32_e32 v2, 0xffffff80, v2
	v_and_b32_e32 v1, 0xffffff80, v1
	v_add_f32_e32 v0, v16, v0
	v_add_f32_e32 v17, v16, v15
	v_add_f32_e32 v18, v16, v14
	v_add_f32_e32 v19, v16, v13
	v_add_f32_e32 v20, v16, v12
	v_add_f32_e32 v21, v16, v11
	v_add_f32_e32 v22, v16, v10
	v_add_f32_e32 v23, v16, v9
	v_add_f32_e32 v24, v16, v8
	v_add_f32_e32 v7, v16, v7
	v_add_f32_e32 v6, v16, v6
	v_add_f32_e32 v5, v16, v5
	v_add_f32_e32 v4, v16, v4
	v_add_f32_e32 v3, v16, v3
	v_add_f32_e32 v2, v16, v2
	v_add_f32_e32 v1, v16, v1
	v_and_or_b32 v16, v0, s10, 15
	v_and_b32_e32 v0, 0xffffff80, v156
	v_and_or_b32 v25, v1, s10, 14
	v_add_f32_e32 v1, v0, v15
	v_and_or_b32 v26, v1, s10, 16
	v_add_f32_e32 v1, v0, v14
	v_and_or_b32 v27, v1, s10, 17
	v_add_f32_e32 v1, v0, v13
	v_and_or_b32 v28, v1, s10, 18
	v_add_f32_e32 v1, v0, v12
	v_and_or_b32 v29, v1, s10, 19
	v_add_f32_e32 v1, v0, v11
	v_and_or_b32 v30, v1, s10, 20
	v_add_f32_e32 v1, v0, v10
	v_and_or_b32 v10, v1, s10, 21
	v_add_f32_e32 v1, v0, v9
	v_add_f32_e32 v0, v0, v8
	v_and_or_b32 v8, v0, s10, 23
	v_and_b32_e32 v0, 0xffffff80, v155
	v_and_or_b32 v9, v1, s10, 22
	v_add_f32_e32 v1, v0, v15
	v_and_or_b32 v31, v1, s10, 32
	v_add_f32_e32 v1, v0, v14
	v_and_or_b32 v32, v1, s10, 33
	v_add_f32_e32 v1, v0, v13
	v_and_or_b32 v33, v1, s10, 34
	v_add_f32_e32 v1, v0, v12
	v_add_f32_e32 v0, v0, v11
	v_and_or_b32 v11, v0, s10, 36
	v_and_b32_e32 v0, 0xffffff80, v154
	v_and_or_b32 v34, v1, s10, 35
	v_add_f32_e32 v1, v0, v15
	v_and_or_b32 v35, v1, s10, 48
	v_add_f32_e32 v1, v0, v14
	v_and_or_b32 v36, v1, s10, 49
	v_add_f32_e32 v1, v0, v13
	v_add_f32_e32 v0, v0, v12
	v_and_or_b32 v12, v0, s10, 51
	v_and_b32_e32 v0, 0xffffff80, v152
	v_and_or_b32 v37, v1, s10, 50
	v_add_f32_e32 v1, v0, v15
	v_and_or_b32 v38, v1, s10, 64
	v_add_f32_e32 v1, v0, v14
	v_add_f32_e32 v0, v0, v13
	v_and_b32_e32 v0, 0xffffff00, v0
	v_and_b32_e32 v1, 0xffffff00, v1
	v_or_b32_e32 v13, 0x42, v0
	v_and_b32_e32 v0, 0xffffff80, v153
	v_or_b32_e32 v39, 0x41, v1
	v_add_f32_e32 v1, v0, v15
	v_add_f32_e32 v0, v0, v14
	v_and_b32_e32 v0, 0xffffff00, v0
	v_and_b32_e32 v1, 0xffffff00, v1
	v_or_b32_e32 v41, 0x51, v0
	v_and_b32_e32 v0, 0xffffff80, v151
	v_or_b32_e32 v40, 0x50, v1
	v_add_f32_e32 v1, v0, v15
	v_add_f32_e32 v0, v0, v14
	v_and_b32_e32 v0, 0xffffff00, v0
	v_and_b32_e32 v1, 0xffffff00, v1
	v_or_b32_e32 v43, 0x61, v0
	v_and_b32_e32 v0, 0xffffff80, v150
	v_or_b32_e32 v42, 0x60, v1
	v_add_f32_e32 v1, v0, v15
	v_add_f32_e32 v0, v0, v14
	v_and_b32_e32 v0, 0xffffff00, v0
	v_or_b32_e32 v14, 0x71, v0
	v_and_b32_e32 v0, 0xffffff80, v128
	v_add_f32_e32 v0, v0, v15
	v_and_b32_e32 v0, 0xffffff00, v0
	v_or_b32_e32 v45, 0x80, v0
	v_and_b32_e32 v0, 0xffffff80, v149
	v_add_f32_e32 v0, v0, v15
	v_and_b32_e32 v0, 0xffffff00, v0
	v_or_b32_e32 v46, 0x90, v0
	v_and_b32_e32 v0, 0xffffff80, v147
	v_add_f32_e32 v0, v0, v15
	v_and_b32_e32 v0, 0xffffff00, v0
	v_or_b32_e32 v47, 0xa0, v0
	v_and_b32_e32 v0, 0xffffff80, v148
	v_add_f32_e32 v0, v0, v15
	v_and_b32_e32 v0, 0xffffff00, v0
	v_or_b32_e32 v48, 0xb0, v0
	v_and_b32_e32 v0, 0xffffff80, v73
	v_add_f32_e32 v0, v0, v15
	v_and_b32_e32 v0, 0xffffff00, v0
	v_or_b32_e32 v49, 0xc0, v0
	v_and_b32_e32 v0, 0xffffff80, v146
	v_and_b32_e32 v1, 0xffffff00, v1
	v_add_f32_e32 v0, v0, v15
	v_max_f32_e32 v38, v38, v38
	v_max_f32_e32 v12, v12, v12
	v_or_b32_e32 v44, 0x70, v1
	v_and_b32_e32 v0, 0xffffff00, v0
	v_and_b32_e32 v1, 0xffffff80, v75
	v_max_f32_e32 v27, v27, v27
	v_max_f32_e32 v26, v26, v26
	v_max_f32_e32 v75, v12, v38
	v_min_f32_e32 v12, v12, v38
	v_max_f32_e32 v13, v13, v13
	v_max_f32_e32 v38, v39, v39
	v_and_b32_e32 v17, 0xffffff00, v17
	v_and_or_b32 v18, v18, s10, 1
	v_or_b32_e32 v50, 0xd0, v0
	v_and_b32_e32 v0, 0xffffff80, v74
	v_max_f32_e32 v58, v26, v27
	v_min_f32_e32 v26, v26, v27
	v_max_f32_e32 v27, v29, v29
	v_max_f32_e32 v28, v28, v28
	v_min_f32_e32 v39, v38, v13
	v_max_f32_e32 v13, v38, v13
	v_max_f32_e32 v38, v41, v41
	v_max_f32_e32 v40, v40, v40
	v_and_or_b32 v19, v19, s10, 2
	v_and_or_b32 v20, v20, s10, 3
	v_add_f32_e32 v0, v0, v15
	v_add_f32_e32 v1, v1, v15
	v_max_f32_e32 v15, v18, v18
	v_max_f32_e32 v17, v17, v17
	v_min_f32_e32 v29, v28, v27
	v_max_f32_e32 v27, v28, v27
	v_max_f32_e32 v10, v10, v10
	v_max_f32_e32 v28, v30, v30
	v_max_f32_e32 v8, v8, v8
	v_max_f32_e32 v9, v9, v9
	v_max_f32_e32 v41, v40, v38
	v_min_f32_e32 v38, v40, v38
	v_max_f32_e32 v40, v43, v43
	v_max_f32_e32 v42, v42, v42
	v_and_or_b32 v21, v21, s10, 4
	v_and_or_b32 v22, v22, s10, 5
	v_max_f32_e32 v18, v17, v15
	v_min_f32_e32 v15, v17, v15
	v_max_f32_e32 v17, v20, v20
	v_max_f32_e32 v19, v19, v19
	v_max_f32_e32 v30, v28, v10
	v_min_f32_e32 v10, v28, v10
	v_min_f32_e32 v28, v9, v8
	v_max_f32_e32 v8, v9, v8
	v_max_f32_e32 v9, v32, v32
	v_max_f32_e32 v31, v31, v31
	v_min_f32_e32 v43, v42, v40
	v_max_f32_e32 v40, v42, v40
	v_max_f32_e32 v14, v14, v14
	v_max_f32_e32 v42, v44, v44
	v_and_or_b32 v23, v23, s10, 6
	v_and_or_b32 v24, v24, s10, 7
	v_and_or_b32 v7, v7, s10, 8
	v_and_or_b32 v6, v6, s10, 9
	v_and_or_b32 v5, v5, s10, 10
	v_and_or_b32 v4, v4, s10, 11
	v_and_or_b32 v3, v3, s10, 12
	v_and_or_b32 v2, v2, s10, 13
; #define CE_DESC(a, b) do { const float _x = (a), _y = (b); (a) = fmaxf(_x, _y); (b) = fminf(_x, _y); } while (0)
; #define CE_ASC(a, b) do { const float _x = (a), _y = (b); (a) = fminf(_x, _y); (b) = fmaxf(_x, _y); } while (0)
; DI void sort16_desc(float (&x)[16]) {
; #pragma unroll
;     for (int k = 2; k <= 16; k <<= 1)
; #pragma unroll
;         for (int j = k >> 1; j > 0; j >>= 1)
; #pragma unroll
;             for (int i = 0; i < 16; ++i) { const int l = i ^ j; if (l > i) { if ((i & k) == 0) CE_DESC(x[i], x[l]); else CE_ASC(x[i], x[l]); } }
; }
; DI void merge_top16(float (&a)[16], const float (&b)[16]) {
; #pragma unroll
;     for (int i = 0; i < 16; ++i) a[i] = fmaxf(a[i], b[15 - i]);
; #pragma unroll
;     for (int j = 8; j > 0; j >>= 1)
; #pragma unroll
;         for (int i = 0; i < 16; ++i) { const int l = i ^ j; if (l > i) CE_DESC(a[i], a[l]); }
; }
; DI void top16_of64(float (&x)[64], float (&t)[16]) {
;     float g[4][16];
; #pragma unroll
;     for (int q = 0; q < 4; ++q) {
; #pragma unroll
;         for (int i = 0; i < 16; ++i) g[q][i] = x[q * 16 + i];
;         sort16_desc(g[q]); }
;     merge_top16(g[0], g[1]); merge_top16(g[2], g[3]); merge_top16(g[0], g[2]);
; #pragma unroll
;     for (int i = 0; i < 16; ++i) t[i] = g[0][i];
; }
	v_and_b32_e32 v0, 0xffffff00, v0
	v_and_b32_e32 v1, 0xffffff00, v1
	v_min_f32_e32 v20, v19, v17
	v_max_f32_e32 v17, v19, v17
	v_max_f32_e32 v19, v22, v22
	v_max_f32_e32 v21, v21, v21
	v_max_f32_e32 v32, v31, v9
	v_min_f32_e32 v9, v31, v9
	v_max_f32_e32 v31, v34, v34
	v_max_f32_e32 v33, v33, v33
	v_max_f32_e32 v44, v42, v14
	v_min_f32_e32 v14, v42, v14
	v_max_f32_e32 v42, v46, v46
	v_max_f32_e32 v45, v45, v45
	v_or_b32_e32 v0, 0xe0, v0
	v_or_b32_e32 v1, 0xf0, v1
	v_max_f32_e32 v22, v21, v19
	v_min_f32_e32 v19, v21, v19
	v_max_f32_e32 v21, v24, v24
	v_max_f32_e32 v23, v23, v23
	v_max_f32_e32 v6, v6, v6
	v_max_f32_e32 v7, v7, v7
	v_max_f32_e32 v4, v4, v4
	v_max_f32_e32 v5, v5, v5
	v_max_f32_e32 v2, v2, v2
	v_max_f32_e32 v3, v3, v3
	v_min_f32_e32 v34, v33, v31
	v_max_f32_e32 v31, v33, v31
	v_max_f32_e32 v33, v35, v35
	v_max_f32_e32 v11, v11, v11
	v_min_f32_e32 v46, v45, v42
	v_max_f32_e32 v42, v45, v42
	v_max_f32_e32 v45, v48, v48
	v_max_f32_e32 v47, v47, v47
	v_min_f32_e32 v24, v23, v21
	v_max_f32_e32 v21, v23, v21
	v_max_f32_e32 v23, v7, v6
	v_min_f32_e32 v6, v7, v6
	v_min_f32_e32 v7, v5, v4
	v_max_f32_e32 v4, v5, v4
	v_max_f32_e32 v5, v3, v2
	v_min_f32_e32 v2, v3, v2
	v_max_f32_e32 v3, v16, v16
	v_max_f32_e32 v16, v25, v25
	v_max_f32_e32 v35, v11, v33
	v_min_f32_e32 v11, v11, v33
	v_max_f32_e32 v33, v37, v37
	v_max_f32_e32 v36, v36, v36
	v_max_f32_e32 v48, v47, v45
	v_min_f32_e32 v45, v47, v45
	v_max_f32_e32 v47, v50, v50
	v_max_f32_e32 v49, v49, v49
	v_max_f32_e32 v1, v1, v1
	v_max_f32_e32 v0, v0, v0
	v_min_f32_e32 v25, v16, v3
	v_max_f32_e32 v3, v16, v3
	v_min_f32_e32 v37, v36, v33
	v_max_f32_e32 v33, v36, v33
	v_min_f32_e32 v50, v49, v47
	v_max_f32_e32 v47, v49, v47
	v_max_f32_e32 v152, v0, v1
	v_min_f32_e32 v0, v0, v1
	v_max_f32_e32 v16, v18, v20
	v_min_f32_e32 v18, v18, v20
	v_max_f32_e32 v20, v15, v17
	v_min_f32_e32 v15, v15, v17
	v_min_f32_e32 v17, v22, v24
	v_max_f32_e32 v22, v22, v24
	v_min_f32_e32 v24, v19, v21
	v_max_f32_e32 v19, v19, v21
	v_max_f32_e32 v21, v23, v7
	v_min_f32_e32 v7, v23, v7
	v_max_f32_e32 v23, v6, v4
	v_min_f32_e32 v4, v6, v4
	v_min_f32_e32 v6, v5, v25
	v_max_f32_e32 v5, v5, v25
	v_min_f32_e32 v25, v2, v3
	v_max_f32_e32 v2, v2, v3
	v_max_f32_e32 v36, v58, v29
	v_min_f32_e32 v29, v58, v29
	v_max_f32_e32 v58, v26, v27
	v_min_f32_e32 v26, v26, v27
	v_min_f32_e32 v27, v30, v28
	v_max_f32_e32 v28, v30, v28
	v_min_f32_e32 v30, v10, v8
	v_max_f32_e32 v8, v10, v8
	v_max_f32_e32 v10, v32, v34
	v_min_f32_e32 v32, v32, v34
	v_max_f32_e32 v34, v9, v31
	v_min_f32_e32 v9, v9, v31
	v_min_f32_e32 v31, v35, v37
	v_max_f32_e32 v35, v35, v37
	v_min_f32_e32 v37, v11, v33
	v_max_f32_e32 v11, v11, v33
	v_max_f32_e32 v49, v75, v39
	v_min_f32_e32 v39, v75, v39
	v_max_f32_e32 v75, v12, v13
	v_min_f32_e32 v12, v12, v13
	v_min_f32_e32 v13, v41, v43
	v_max_f32_e32 v41, v41, v43
	v_min_f32_e32 v43, v38, v40
	v_max_f32_e32 v38, v38, v40
	v_max_f32_e32 v40, v44, v46
	v_min_f32_e32 v44, v44, v46
	v_max_f32_e32 v46, v14, v42
	v_min_f32_e32 v14, v14, v42
	v_min_f32_e32 v42, v48, v50
	v_max_f32_e32 v48, v48, v50
	v_min_f32_e32 v50, v45, v47
	v_max_f32_e32 v45, v45, v47
	v_max_f32_e32 v1, 0xff61b1e6, v152
	v_min_f32_e32 v152, 0xff61b1e6, v152
	v_max_f32_e32 v153, 0xff61b1e6, v0
	v_min_f32_e32 v0, 0xff61b1e6, v0
	v_max_f32_e32 v3, v16, v20
	v_min_f32_e32 v16, v16, v20
	v_max_f32_e32 v20, v18, v15
	v_min_f32_e32 v15, v18, v15
	v_min_f32_e32 v18, v17, v24
	v_max_f32_e32 v17, v17, v24
	v_min_f32_e32 v24, v22, v19
	v_max_f32_e32 v19, v22, v19
	v_max_f32_e32 v22, v21, v23
	v_min_f32_e32 v21, v21, v23
	v_max_f32_e32 v23, v7, v4
	v_min_f32_e32 v4, v7, v4
	v_min_f32_e32 v7, v6, v25
	v_max_f32_e32 v6, v6, v25
	v_min_f32_e32 v25, v5, v2
	v_max_f32_e32 v2, v5, v2
	v_max_f32_e32 v33, v36, v58
	v_min_f32_e32 v36, v36, v58
	v_max_f32_e32 v58, v29, v26
	v_min_f32_e32 v26, v29, v26
	v_min_f32_e32 v29, v27, v30
	v_max_f32_e32 v27, v27, v30
	v_min_f32_e32 v30, v28, v8
	v_max_f32_e32 v8, v28, v8
	v_max_f32_e32 v28, v10, v34
	v_min_f32_e32 v10, v10, v34
	v_max_f32_e32 v34, v32, v9
	v_min_f32_e32 v9, v32, v9
	v_min_f32_e32 v32, v31, v37
	v_max_f32_e32 v31, v31, v37
	v_min_f32_e32 v37, v35, v11
	v_max_f32_e32 v11, v35, v11
	v_max_f32_e32 v47, v49, v75
	v_min_f32_e32 v49, v49, v75
	v_max_f32_e32 v75, v39, v12
	v_min_f32_e32 v12, v39, v12
	v_min_f32_e32 v39, v13, v43
	v_max_f32_e32 v13, v13, v43
	v_min_f32_e32 v43, v41, v38
	v_max_f32_e32 v38, v41, v38
	v_max_f32_e32 v41, v40, v46
	v_min_f32_e32 v40, v40, v46
	v_max_f32_e32 v46, v44, v14
	v_min_f32_e32 v14, v44, v14
	v_min_f32_e32 v44, v42, v50
	v_max_f32_e32 v42, v42, v50
	v_min_f32_e32 v50, v48, v45
	v_max_f32_e32 v45, v48, v45
	v_max_f32_e32 v154, v1, v153
	v_min_f32_e32 v1, v1, v153
	v_max_f32_e32 v153, v152, v0
	v_min_f32_e32 v0, v152, v0
	v_max_f32_e32 v5, v3, v18
	v_min_f32_e32 v3, v3, v18
	v_max_f32_e32 v18, v16, v17
	v_min_f32_e32 v16, v16, v17
	v_max_f32_e32 v17, v20, v24
	v_min_f32_e32 v20, v20, v24
	v_max_f32_e32 v24, v15, v19
	v_min_f32_e32 v15, v15, v19
	v_min_f32_e32 v19, v22, v7
	v_max_f32_e32 v7, v22, v7
	v_min_f32_e32 v22, v21, v6
	v_max_f32_e32 v6, v21, v6
	v_min_f32_e32 v21, v23, v25
	v_max_f32_e32 v23, v23, v25
	v_min_f32_e32 v25, v4, v2
	v_max_f32_e32 v2, v4, v2
	v_max_f32_e32 v35, v33, v29
	v_min_f32_e32 v29, v33, v29
	v_max_f32_e32 v33, v36, v27
	v_min_f32_e32 v27, v36, v27
	v_max_f32_e32 v36, v58, v30
	v_min_f32_e32 v30, v58, v30
	v_max_f32_e32 v58, v26, v8
	v_min_f32_e32 v8, v26, v8
	v_min_f32_e32 v26, v28, v32
	v_max_f32_e32 v28, v28, v32
	v_min_f32_e32 v32, v10, v31
	v_max_f32_e32 v10, v10, v31
	v_min_f32_e32 v31, v34, v37
	v_max_f32_e32 v34, v34, v37
	v_min_f32_e32 v37, v9, v11
; #define CE_DESC(a, b) do { const float _x = (a), _y = (b); (a) = fmaxf(_x, _y); (b) = fminf(_x, _y); } while (0)
; #define CE_ASC(a, b) do { const float _x = (a), _y = (b); (a) = fminf(_x, _y); (b) = fmaxf(_x, _y); } while (0)
; DI void sort16_desc(float (&x)[16]) {
; #pragma unroll
;     for (int k = 2; k <= 16; k <<= 1)
; #pragma unroll
;         for (int j = k >> 1; j > 0; j >>= 1)
; #pragma unroll
;             for (int i = 0; i < 16; ++i) { const int l = i ^ j; if (l > i) { if ((i & k) == 0) CE_DESC(x[i], x[l]); else CE_ASC(x[i], x[l]); } }
; }
; DI void merge_top16(float (&a)[16], const float (&b)[16]) {
; #pragma unroll
;     for (int i = 0; i < 16; ++i) a[i] = fmaxf(a[i], b[15 - i]);
; #pragma unroll
;     for (int j = 8; j > 0; j >>= 1)
; #pragma unroll
;         for (int i = 0; i < 16; ++i) { const int l = i ^ j; if (l > i) CE_DESC(a[i], a[l]); }
; }
; DI void top16_of64(float (&x)[64], float (&t)[16]) {
;     float g[4][16];
; #pragma unroll
;     for (int q = 0; q < 4; ++q) {
; #pragma unroll
;         for (int i = 0; i < 16; ++i) g[q][i] = x[q * 16 + i];
;         sort16_desc(g[q]); }
;     merge_top16(g[0], g[1]); merge_top16(g[2], g[3]); merge_top16(g[0], g[2]);
; #pragma unroll
;     for (int i = 0; i < 16; ++i) t[i] = g[0][i];
; }
	v_max_f32_e32 v9, v9, v11
	v_max_f32_e32 v48, v47, v39
	v_min_f32_e32 v39, v47, v39
	v_max_f32_e32 v47, v49, v13
	v_min_f32_e32 v13, v49, v13
	v_max_f32_e32 v49, v75, v43
	v_min_f32_e32 v43, v75, v43
	v_max_f32_e32 v75, v12, v38
	v_min_f32_e32 v12, v12, v38
	v_min_f32_e32 v38, v41, v44
	v_max_f32_e32 v41, v41, v44
	v_min_f32_e32 v44, v40, v42
	v_max_f32_e32 v40, v40, v42
	v_min_f32_e32 v42, v46, v50
	v_max_f32_e32 v46, v46, v50
	v_min_f32_e32 v50, v14, v45
	v_max_f32_e32 v14, v14, v45
	v_max_f32_e32 v152, 0xff61b1e6, v154
	v_min_f32_e32 v154, 0xff61b1e6, v154
	v_max_f32_e32 v155, 0xff61b1e6, v1
	v_min_f32_e32 v1, 0xff61b1e6, v1
	v_max_f32_e32 v156, 0xff61b1e6, v153
	v_min_f32_e32 v153, 0xff61b1e6, v153
	v_max_f32_e32 v157, 0xff61b1e6, v0
	v_min_f32_e32 v0, 0xff61b1e6, v0
	v_max_f32_e32 v4, v5, v17
	v_min_f32_e32 v5, v5, v17
	v_max_f32_e32 v17, v18, v24
	v_min_f32_e32 v18, v18, v24
	v_max_f32_e32 v24, v3, v20
	v_min_f32_e32 v3, v3, v20
	v_max_f32_e32 v20, v16, v15
	v_min_f32_e32 v15, v16, v15
	v_min_f32_e32 v16, v19, v21
	v_max_f32_e32 v19, v19, v21
	v_min_f32_e32 v21, v22, v25
	v_max_f32_e32 v22, v22, v25
	v_min_f32_e32 v25, v7, v23
	v_max_f32_e32 v7, v7, v23
	v_min_f32_e32 v23, v6, v2
	v_max_f32_e32 v2, v6, v2
	v_max_f32_e32 v11, v35, v36
	v_min_f32_e32 v35, v35, v36
	v_max_f32_e32 v36, v33, v58
	v_min_f32_e32 v33, v33, v58
	v_max_f32_e32 v58, v29, v30
	v_min_f32_e32 v29, v29, v30
	v_max_f32_e32 v30, v27, v8
	v_min_f32_e32 v8, v27, v8
	v_min_f32_e32 v27, v26, v31
	v_max_f32_e32 v26, v26, v31
	v_min_f32_e32 v31, v32, v37
	v_max_f32_e32 v32, v32, v37
	v_min_f32_e32 v37, v28, v34
	v_max_f32_e32 v28, v28, v34
	v_min_f32_e32 v34, v10, v9
	v_max_f32_e32 v9, v10, v9
	v_max_f32_e32 v45, v48, v49
	v_min_f32_e32 v48, v48, v49
	v_max_f32_e32 v49, v47, v75
	v_min_f32_e32 v47, v47, v75
	v_max_f32_e32 v75, v39, v43
	v_min_f32_e32 v39, v39, v43
	v_max_f32_e32 v43, v13, v12
	v_min_f32_e32 v12, v13, v12
	v_min_f32_e32 v13, v38, v42
	v_max_f32_e32 v38, v38, v42
	v_min_f32_e32 v42, v44, v50
	v_max_f32_e32 v44, v44, v50
	v_min_f32_e32 v50, v41, v46
	v_max_f32_e32 v41, v41, v46
	v_min_f32_e32 v46, v40, v14
	v_max_f32_e32 v14, v40, v14
	v_max_f32_e32 v158, v152, v156
	v_min_f32_e32 v152, v152, v156
	v_max_f32_e32 v156, v155, v157
	v_min_f32_e32 v155, v155, v157
	v_max_f32_e32 v157, v154, v153
	v_min_f32_e32 v153, v154, v153
	v_max_f32_e32 v154, v1, v0
	v_min_f32_e32 v0, v1, v0
	v_max_f32_e32 v6, v4, v17
	v_min_f32_e32 v4, v4, v17
	v_max_f32_e32 v17, v5, v18
	v_min_f32_e32 v5, v5, v18
	v_max_f32_e32 v18, v24, v20
	v_min_f32_e32 v20, v24, v20
	v_max_f32_e32 v24, v3, v15
	v_min_f32_e32 v3, v3, v15
	v_min_f32_e32 v15, v16, v21
	v_max_f32_e32 v16, v16, v21
	v_min_f32_e32 v21, v19, v22
	v_max_f32_e32 v19, v19, v22
	v_min_f32_e32 v22, v25, v23
	v_max_f32_e32 v23, v25, v23
	v_min_f32_e32 v25, v7, v2
	v_max_f32_e32 v2, v7, v2
	v_max_f32_e32 v10, v11, v36
	v_min_f32_e32 v11, v11, v36
	v_max_f32_e32 v36, v35, v33
	v_min_f32_e32 v33, v35, v33
	v_max_f32_e32 v35, v58, v30
	v_min_f32_e32 v30, v58, v30
	v_max_f32_e32 v58, v29, v8
	v_min_f32_e32 v8, v29, v8
	v_min_f32_e32 v29, v27, v31
	v_max_f32_e32 v27, v27, v31
	v_min_f32_e32 v31, v26, v32
	v_max_f32_e32 v26, v26, v32
	v_min_f32_e32 v32, v37, v34
	v_max_f32_e32 v34, v37, v34
	v_min_f32_e32 v37, v28, v9
	v_max_f32_e32 v9, v28, v9
	v_max_f32_e32 v40, v45, v49
	v_min_f32_e32 v45, v45, v49
	v_max_f32_e32 v49, v48, v47
	v_min_f32_e32 v47, v48, v47
	v_max_f32_e32 v48, v75, v43
	v_min_f32_e32 v43, v75, v43
	v_max_f32_e32 v75, v39, v12
	v_min_f32_e32 v12, v39, v12
	v_min_f32_e32 v39, v13, v42
	v_max_f32_e32 v13, v13, v42
	v_min_f32_e32 v42, v38, v44
	v_max_f32_e32 v38, v38, v44
	v_min_f32_e32 v44, v50, v46
	v_max_f32_e32 v46, v50, v46
	v_min_f32_e32 v50, v41, v14
	v_max_f32_e32 v14, v41, v14
	v_max_f32_e32 v1, v158, v156
	v_min_f32_e32 v156, v158, v156
	v_max_f32_e32 v158, v152, v155
	v_min_f32_e32 v152, v152, v155
	v_max_f32_e32 v155, v157, v154
	v_min_f32_e32 v154, v157, v154
	v_max_f32_e32 v157, v153, v0
	v_min_f32_e32 v0, v153, v0
	v_max_f32_e32 v7, v6, v15
	v_min_f32_e32 v6, v6, v15
	v_max_f32_e32 v15, v4, v16
	v_min_f32_e32 v4, v4, v16
	v_max_f32_e32 v16, v17, v21
	v_min_f32_e32 v17, v17, v21
	v_max_f32_e32 v21, v5, v19
	v_min_f32_e32 v5, v5, v19
	v_max_f32_e32 v19, v18, v22
	v_min_f32_e32 v18, v18, v22
	v_max_f32_e32 v22, v20, v23
	v_min_f32_e32 v20, v20, v23
	v_max_f32_e32 v23, v24, v25
	v_min_f32_e32 v24, v24, v25
	v_max_f32_e32 v25, v3, v2
	v_min_f32_e32 v2, v3, v2
	v_max_f32_e32 v28, v10, v29
	v_min_f32_e32 v10, v10, v29
	v_max_f32_e32 v29, v11, v27
	v_min_f32_e32 v11, v11, v27
	v_max_f32_e32 v27, v36, v31
	v_min_f32_e32 v31, v36, v31
	v_max_f32_e32 v36, v33, v26
	v_min_f32_e32 v26, v33, v26
	v_max_f32_e32 v33, v35, v32
	v_min_f32_e32 v32, v35, v32
	v_max_f32_e32 v35, v30, v34
	v_min_f32_e32 v30, v30, v34
	v_max_f32_e32 v34, v58, v37
	v_min_f32_e32 v37, v58, v37
	v_max_f32_e32 v58, v8, v9
	v_min_f32_e32 v8, v8, v9
	v_max_f32_e32 v41, v40, v39
	v_min_f32_e32 v39, v40, v39
	v_max_f32_e32 v40, v45, v13
	v_min_f32_e32 v13, v45, v13
	v_max_f32_e32 v45, v49, v42
	v_min_f32_e32 v42, v49, v42
	v_max_f32_e32 v49, v47, v38
	v_min_f32_e32 v38, v47, v38
	v_max_f32_e32 v47, v48, v44
	v_min_f32_e32 v44, v48, v44
	v_max_f32_e32 v48, v43, v46
	v_min_f32_e32 v43, v43, v46
	v_max_f32_e32 v46, v75, v50
	v_min_f32_e32 v50, v75, v50
	v_max_f32_e32 v75, v12, v14
	v_min_f32_e32 v12, v12, v14
	v_max_f32_e32 v153, 0xff61b1e6, v1
	v_min_f32_e32 v1, 0xff61b1e6, v1
	v_max_f32_e32 v159, 0xff61b1e6, v156
	v_min_f32_e32 v156, 0xff61b1e6, v156
	v_max_f32_e32 v160, 0xff61b1e6, v158
	v_min_f32_e32 v158, 0xff61b1e6, v158
	v_max_f32_e32 v161, 0xff61b1e6, v152
; #define CE_DESC(a, b) do { const float _x = (a), _y = (b); (a) = fmaxf(_x, _y); (b) = fminf(_x, _y); } while (0)
; #define CE_ASC(a, b) do { const float _x = (a), _y = (b); (a) = fminf(_x, _y); (b) = fmaxf(_x, _y); } while (0)
; DI void sort16_desc(float (&x)[16]) {
; #pragma unroll
;     for (int k = 2; k <= 16; k <<= 1)
; #pragma unroll
;         for (int j = k >> 1; j > 0; j >>= 1)
; #pragma unroll
;             for (int i = 0; i < 16; ++i) { const int l = i ^ j; if (l > i) { if ((i & k) == 0) CE_DESC(x[i], x[l]); else CE_ASC(x[i], x[l]); } }
; }
; DI void merge_top16(float (&a)[16], const float (&b)[16]) {
; #pragma unroll
;     for (int i = 0; i < 16; ++i) a[i] = fmaxf(a[i], b[15 - i]);
; #pragma unroll
;     for (int j = 8; j > 0; j >>= 1)
; #pragma unroll
;         for (int i = 0; i < 16; ++i) { const int l = i ^ j; if (l > i) CE_DESC(a[i], a[l]); }
; }
; DI void top16_of64(float (&x)[64], float (&t)[16]) {
;     float g[4][16];
; #pragma unroll
;     for (int q = 0; q < 4; ++q) {
; #pragma unroll
;         for (int i = 0; i < 16; ++i) g[q][i] = x[q * 16 + i];
;         sort16_desc(g[q]); }
;     merge_top16(g[0], g[1]); merge_top16(g[2], g[3]); merge_top16(g[0], g[2]);
; #pragma unroll
;     for (int i = 0; i < 16; ++i) t[i] = g[0][i];
; }
	v_min_f32_e32 v152, 0xff61b1e6, v152
	v_max_f32_e32 v162, 0xff61b1e6, v155
	v_min_f32_e32 v155, 0xff61b1e6, v155
	v_max_f32_e32 v163, 0xff61b1e6, v154
	v_min_f32_e32 v154, 0xff61b1e6, v154
	v_max_f32_e32 v164, 0xff61b1e6, v157
	v_min_f32_e32 v157, 0xff61b1e6, v157
	v_max_f32_e32 v165, 0xff61b1e6, v0
	v_min_f32_e32 v0, 0xff61b1e6, v0
	v_max_f32_e32 v3, v7, v19
	v_min_f32_e32 v7, v7, v19
	v_max_f32_e32 v19, v15, v22
	v_min_f32_e32 v15, v15, v22
	v_max_f32_e32 v22, v16, v23
	v_min_f32_e32 v16, v16, v23
	v_max_f32_e32 v23, v21, v25
	v_min_f32_e32 v21, v21, v25
	v_max_f32_e32 v25, v6, v18
	v_min_f32_e32 v6, v6, v18
	v_max_f32_e32 v18, v4, v20
	v_min_f32_e32 v4, v4, v20
	v_max_f32_e32 v20, v17, v24
	v_min_f32_e32 v17, v17, v24
	v_max_f32_e32 v24, v5, v2
	v_min_f32_e32 v2, v5, v2
	v_max_f32_e32 v9, v28, v33
	v_min_f32_e32 v28, v28, v33
	v_max_f32_e32 v33, v29, v35
	v_min_f32_e32 v29, v29, v35
	v_max_f32_e32 v35, v27, v34
	v_min_f32_e32 v27, v27, v34
	v_max_f32_e32 v34, v36, v58
	v_min_f32_e32 v36, v36, v58
	v_max_f32_e32 v58, v10, v32
	v_min_f32_e32 v10, v10, v32
	v_max_f32_e32 v32, v11, v30
	v_min_f32_e32 v11, v11, v30
	v_max_f32_e32 v30, v31, v37
	v_min_f32_e32 v31, v31, v37
	v_max_f32_e32 v37, v26, v8
	v_min_f32_e32 v8, v26, v8
	v_max_f32_e32 v14, v41, v47
	v_min_f32_e32 v41, v41, v47
	v_max_f32_e32 v47, v40, v48
	v_min_f32_e32 v40, v40, v48
	v_max_f32_e32 v48, v45, v46
	v_min_f32_e32 v45, v45, v46
	v_max_f32_e32 v46, v49, v75
	v_min_f32_e32 v49, v49, v75
	v_max_f32_e32 v75, v39, v44
	v_min_f32_e32 v39, v39, v44
	v_max_f32_e32 v44, v13, v43
	v_min_f32_e32 v13, v13, v43
	v_max_f32_e32 v43, v42, v50
	v_min_f32_e32 v42, v42, v50
	v_max_f32_e32 v50, v38, v12
	v_min_f32_e32 v12, v38, v12
	v_max_f32_e32 v166, v153, v162
	v_min_f32_e32 v153, v153, v162
	v_max_f32_e32 v162, v159, v163
	v_min_f32_e32 v159, v159, v163
	v_max_f32_e32 v163, v160, v164
	v_min_f32_e32 v160, v160, v164
	v_max_f32_e32 v164, v161, v165
	v_min_f32_e32 v161, v161, v165
	v_max_f32_e32 v165, v1, v155
	v_min_f32_e32 v1, v1, v155
	v_max_f32_e32 v155, v156, v154
	v_min_f32_e32 v154, v156, v154
	v_max_f32_e32 v156, v158, v157
	v_min_f32_e32 v157, v158, v157
	v_max_f32_e32 v158, v152, v0
	v_min_f32_e32 v0, v152, v0
	v_max_f32_e32 v5, v3, v22
	v_min_f32_e32 v3, v3, v22
	v_max_f32_e32 v22, v19, v23
	v_min_f32_e32 v19, v19, v23
	v_max_f32_e32 v23, v7, v16
	v_min_f32_e32 v7, v7, v16
	v_max_f32_e32 v16, v15, v21
	v_min_f32_e32 v15, v15, v21
	v_max_f32_e32 v21, v25, v20
	v_min_f32_e32 v20, v25, v20
	v_max_f32_e32 v25, v18, v24
	v_min_f32_e32 v18, v18, v24
	v_max_f32_e32 v24, v6, v17
	v_min_f32_e32 v6, v6, v17
	v_max_f32_e32 v17, v4, v2
	v_min_f32_e32 v2, v4, v2
	v_max_f32_e32 v26, v9, v35
	v_min_f32_e32 v9, v9, v35
	v_max_f32_e32 v35, v33, v34
	v_min_f32_e32 v33, v33, v34
	v_max_f32_e32 v34, v28, v27
	v_min_f32_e32 v27, v28, v27
	v_max_f32_e32 v28, v29, v36
	v_min_f32_e32 v29, v29, v36
	v_max_f32_e32 v36, v58, v30
	v_min_f32_e32 v30, v58, v30
	v_max_f32_e32 v58, v32, v37
	v_min_f32_e32 v32, v32, v37
	v_max_f32_e32 v37, v10, v31
	v_min_f32_e32 v10, v10, v31
	v_max_f32_e32 v31, v11, v8
	v_min_f32_e32 v8, v11, v8
	v_max_f32_e32 v38, v14, v48
	v_min_f32_e32 v14, v14, v48
	v_max_f32_e32 v48, v47, v46
	v_min_f32_e32 v46, v47, v46
	v_max_f32_e32 v47, v41, v45
	v_min_f32_e32 v41, v41, v45
	v_max_f32_e32 v45, v40, v49
	v_min_f32_e32 v40, v40, v49
	v_max_f32_e32 v49, v75, v43
	v_min_f32_e32 v43, v75, v43
	v_max_f32_e32 v75, v44, v50
	v_min_f32_e32 v44, v44, v50
	v_max_f32_e32 v50, v39, v42
	v_min_f32_e32 v39, v39, v42
	v_max_f32_e32 v42, v13, v12
	v_min_f32_e32 v12, v13, v12
	v_max_f32_e32 v152, v166, v163
	v_min_f32_e32 v163, v166, v163
	v_max_f32_e32 v166, v162, v164
	v_min_f32_e32 v162, v162, v164
	v_max_f32_e32 v164, v153, v160
	v_min_f32_e32 v153, v153, v160
	v_max_f32_e32 v160, v159, v161
	v_min_f32_e32 v159, v159, v161
	v_max_f32_e32 v161, v165, v156
	v_min_f32_e32 v156, v165, v156
	v_max_f32_e32 v165, v155, v158
	v_min_f32_e32 v155, v155, v158
	v_max_f32_e32 v158, v1, v157
	v_min_f32_e32 v1, v1, v157
	v_max_f32_e32 v157, v154, v0
	v_min_f32_e32 v0, v154, v0
	v_min_f32_e32 v4, v5, v22
	v_min_f32_e32 v51, v3, v19
	v_min_f32_e32 v52, v23, v16
	v_min_f32_e32 v53, v7, v15
	v_min_f32_e32 v54, v21, v25
	v_min_f32_e32 v55, v20, v18
	v_min_f32_e32 v56, v24, v17
	v_min_f32_e32 v57, v6, v2
	v_min_f32_e32 v11, v26, v35
	v_min_f32_e32 v59, v9, v33
	v_min_f32_e32 v60, v34, v28
	v_min_f32_e32 v61, v27, v29
	v_min_f32_e32 v62, v36, v58
	v_min_f32_e32 v63, v30, v32
	v_min_f32_e32 v73, v37, v31
	v_min_f32_e32 v74, v10, v8
	v_min_f32_e32 v13, v38, v48
	v_min_f32_e32 v128, v14, v46
	v_min_f32_e32 v146, v47, v45
	v_min_f32_e32 v147, v41, v40
	v_min_f32_e32 v148, v49, v75
	v_min_f32_e32 v149, v43, v44
	v_min_f32_e32 v150, v50, v42
	v_min_f32_e32 v151, v39, v12
	v_min_f32_e32 v154, v152, v166
	v_min_f32_e32 v167, v163, v162
	v_min_f32_e32 v168, v164, v160
	v_min_f32_e32 v169, v153, v159
	v_min_f32_e32 v170, v161, v165
	v_min_f32_e32 v171, v156, v155
	v_min_f32_e32 v172, v158, v157
	v_min_f32_e32 v173, v1, v0
	v_max3_f32 v5, v5, v22, v74
	v_max3_f32 v4, v4, v10, v8
	v_max3_f32 v3, v3, v19, v73
	v_max3_f32 v8, v51, v37, v31
	v_max3_f32 v10, v23, v16, v63
	v_max3_f32 v16, v52, v30, v32
	v_max3_f32 v7, v7, v15, v62
	v_max3_f32 v15, v53, v36, v58
	v_max3_f32 v19, v21, v25, v61
	v_max3_f32 v21, v54, v27, v29
	v_max3_f32 v18, v20, v18, v60
	v_max3_f32 v20, v55, v34, v28
	v_max3_f32 v17, v24, v17, v59
	v_max3_f32 v9, v56, v9, v33
	v_max3_f32 v2, v6, v2, v11
	v_max3_f32 v6, v57, v26, v35
	v_max3_f32 v29, v38, v48, v173
	v_max3_f32 v0, v13, v1, v0
	v_max3_f32 v1, v14, v46, v172
	v_max3_f32 v13, v128, v158, v157
; #define CE_DESC(a, b) do { const float _x = (a), _y = (b); (a) = fmaxf(_x, _y); (b) = fminf(_x, _y); } while (0)
; DI void merge_top16(float (&a)[16], const float (&b)[16]) {
; #pragma unroll
;     for (int i = 0; i < 16; ++i) a[i] = fmaxf(a[i], b[15 - i]);
; #pragma unroll
;     for (int j = 8; j > 0; j >>= 1)
; #pragma unroll
;         for (int i = 0; i < 16; ++i) { const int l = i ^ j; if (l > i) CE_DESC(a[i], a[l]); }
; }
; DI void top16_of64(float (&x)[64], float (&t)[16]) {
;     float g[4][16];
; #pragma unroll
;     for (int q = 0; q < 4; ++q) {
; #pragma unroll
;         for (int i = 0; i < 16; ++i) g[q][i] = x[q * 16 + i];
;         sort16_desc(g[q]); }
;     merge_top16(g[0], g[1]); merge_top16(g[2], g[3]); merge_top16(g[0], g[2]);
; #pragma unroll
;     for (int i = 0; i < 16; ++i) t[i] = g[0][i];
; }
; DI void route_block(const Frame& F, int t0, int t1) {
;     ...
;         if (valid) {
;             if (hh == 0) {
; #pragma unroll
;                 for (int q = 0; q < 2; ++q) *(u32x4*)(RI + tl * 128 + h * 16 + q * 8) = (u32x4){(unsigned)eidx[q * 8] | ((unsigned)eidx[q * 8 + 1] << 16), (unsigned)eidx[q * 8 + 2] | ((unsigned)eidx[q * 8 + 3] << 16), (unsigned)eidx[q * 8 + 4] | ((unsigned)eidx[q * 8 + 5] << 16), (unsigned)eidx[q * 8 + 6] | ((unsigned)eidx[q * 8 + 7] << 16)};
;             } else {
	v_max3_f32 v14, v47, v45, v171
	v_max3_f32 v30, v146, v156, v155
	v_max3_f32 v31, v41, v40, v170
	v_max3_f32 v32, v147, v161, v165
	v_max3_f32 v33, v49, v75, v169
	v_max3_f32 v34, v148, v153, v159
	v_max3_f32 v35, v43, v44, v168
	v_max3_f32 v36, v149, v164, v160
	v_max3_f32 v37, v50, v42, v167
	v_max3_f32 v38, v150, v163, v162
	v_max3_f32 v12, v39, v12, v154
	v_max3_f32 v39, v151, v152, v166
	v_max_f32_e32 v11, v5, v19
	v_min_f32_e32 v5, v5, v19
	v_max_f32_e32 v19, v4, v21
	v_min_f32_e32 v4, v4, v21
	v_max_f32_e32 v21, v3, v18
	v_min_f32_e32 v3, v3, v18
	v_max_f32_e32 v18, v8, v20
	v_min_f32_e32 v8, v8, v20
	v_max_f32_e32 v20, v10, v17
	v_min_f32_e32 v10, v10, v17
	v_max_f32_e32 v17, v16, v9
	v_min_f32_e32 v9, v16, v9
	v_max_f32_e32 v16, v7, v2
	v_min_f32_e32 v2, v7, v2
	v_max_f32_e32 v7, v15, v6
	v_min_f32_e32 v6, v15, v6
	v_max_f32_e32 v40, v29, v33
	v_min_f32_e32 v29, v29, v33
	v_max_f32_e32 v33, v0, v34
	v_min_f32_e32 v0, v0, v34
	v_max_f32_e32 v34, v1, v35
	v_min_f32_e32 v1, v1, v35
	v_max_f32_e32 v35, v13, v36
	v_min_f32_e32 v13, v13, v36
	v_max_f32_e32 v36, v14, v37
	v_min_f32_e32 v14, v14, v37
	v_max_f32_e32 v37, v30, v38
	v_min_f32_e32 v30, v30, v38
	v_max_f32_e32 v38, v31, v12
	v_min_f32_e32 v12, v31, v12
	v_max_f32_e32 v31, v32, v39
	v_min_f32_e32 v32, v32, v39
	v_max_f32_e32 v15, v11, v20
	v_min_f32_e32 v11, v11, v20
	v_max_f32_e32 v20, v19, v17
	v_min_f32_e32 v17, v19, v17
	v_max_f32_e32 v19, v21, v16
	v_min_f32_e32 v16, v21, v16
	v_max_f32_e32 v21, v18, v7
	v_min_f32_e32 v7, v18, v7
	v_max_f32_e32 v18, v5, v10
	v_min_f32_e32 v5, v5, v10
	v_max_f32_e32 v10, v4, v9
	v_min_f32_e32 v4, v4, v9
	v_max_f32_e32 v9, v3, v2
	v_min_f32_e32 v2, v3, v2
	v_max_f32_e32 v3, v8, v6
	v_min_f32_e32 v6, v8, v6
	v_max_f32_e32 v39, v40, v36
	v_min_f32_e32 v36, v40, v36
	v_max_f32_e32 v40, v33, v37
	v_min_f32_e32 v33, v33, v37
	v_max_f32_e32 v37, v34, v38
	v_min_f32_e32 v34, v34, v38
	v_max_f32_e32 v38, v35, v31
	v_min_f32_e32 v31, v35, v31
	v_max_f32_e32 v35, v29, v14
	v_min_f32_e32 v14, v29, v14
	v_max_f32_e32 v29, v0, v30
	v_min_f32_e32 v0, v0, v30
	v_max_f32_e32 v30, v1, v12
	v_min_f32_e32 v1, v1, v12
	v_max_f32_e32 v12, v13, v32
	v_min_f32_e32 v13, v13, v32
	v_max_f32_e32 v8, v15, v19
	v_min_f32_e32 v15, v15, v19
	v_max_f32_e32 v19, v20, v21
	v_min_f32_e32 v20, v20, v21
	v_max_f32_e32 v21, v11, v16
	v_min_f32_e32 v11, v11, v16
	v_max_f32_e32 v16, v17, v7
	v_min_f32_e32 v7, v17, v7
	v_max_f32_e32 v17, v18, v9
	v_min_f32_e32 v9, v18, v9
	v_max_f32_e32 v18, v10, v3
	v_min_f32_e32 v3, v10, v3
	v_max_f32_e32 v10, v5, v2
	v_min_f32_e32 v2, v5, v2
	v_max_f32_e32 v5, v4, v6
	v_min_f32_e32 v4, v4, v6
	v_max_f32_e32 v32, v39, v37
	v_min_f32_e32 v37, v39, v37
	v_max_f32_e32 v39, v40, v38
	v_min_f32_e32 v38, v40, v38
	v_max_f32_e32 v40, v36, v34
	v_min_f32_e32 v34, v36, v34
	v_max_f32_e32 v36, v33, v31
	v_min_f32_e32 v31, v33, v31
	v_max_f32_e32 v33, v35, v30
	v_min_f32_e32 v30, v35, v30
	v_max_f32_e32 v35, v29, v12
	v_min_f32_e32 v12, v29, v12
	v_max_f32_e32 v29, v14, v1
	v_min_f32_e32 v1, v14, v1
	v_max_f32_e32 v14, v0, v13
	v_min_f32_e32 v0, v0, v13
	v_min_f32_e32 v6, v8, v19
	v_min_f32_e32 v22, v15, v20
	v_min_f32_e32 v23, v21, v16
	v_min_f32_e32 v24, v11, v7
	v_min_f32_e32 v25, v17, v18
	v_min_f32_e32 v26, v9, v3
	v_min_f32_e32 v27, v10, v5
	v_min_f32_e32 v28, v2, v4
	v_min_f32_e32 v13, v32, v39
	v_min_f32_e32 v41, v37, v38
	v_min_f32_e32 v42, v40, v36
	v_min_f32_e32 v43, v34, v31
	v_min_f32_e32 v44, v33, v35
	v_min_f32_e32 v45, v30, v12
	v_min_f32_e32 v46, v29, v14
	v_min_f32_e32 v47, v1, v0
	v_max3_f32 v8, v8, v19, v47
	v_max3_f32 v0, v6, v1, v0
	v_max3_f32 v1, v15, v20, v46
	v_max3_f32 v6, v22, v29, v14
	v_max3_f32 v14, v21, v16, v45
	v_max3_f32 v12, v23, v30, v12
	v_max3_f32 v7, v11, v7, v44
	v_max3_f32 v11, v24, v33, v35
	v_max3_f32 v15, v17, v18, v43
	v_max3_f32 v16, v25, v34, v31
	v_max3_f32 v3, v9, v3, v42
	v_max3_f32 v9, v26, v40, v36
	v_max3_f32 v5, v10, v5, v41
	v_max3_f32 v10, v27, v37, v38
	v_max3_f32 v2, v2, v4, v13
	v_max3_f32 v4, v28, v32, v39
	v_max_f32_e32 v13, v8, v15
	v_min_f32_e32 v8, v8, v15
	v_max_f32_e32 v15, v0, v16
	v_min_f32_e32 v0, v0, v16
	v_max_f32_e32 v16, v1, v3
	v_min_f32_e32 v1, v1, v3
	v_max_f32_e32 v3, v6, v9
	v_min_f32_e32 v6, v6, v9
	v_max_f32_e32 v9, v14, v5
	v_min_f32_e32 v5, v14, v5
	v_max_f32_e32 v14, v12, v10
	v_min_f32_e32 v10, v12, v10
	v_max_f32_e32 v12, v7, v2
	v_min_f32_e32 v2, v7, v2
	v_max_f32_e32 v7, v11, v4
	v_min_f32_e32 v4, v11, v4
	v_max_f32_e32 v11, v13, v9
	v_min_f32_e32 v9, v13, v9
	v_max_f32_e32 v13, v15, v14
	v_min_f32_e32 v14, v15, v14
	v_max_f32_e32 v15, v16, v12
	v_min_f32_e32 v12, v16, v12
	v_max_f32_e32 v16, v3, v7
	v_min_f32_e32 v3, v3, v7
	v_max_f32_e32 v7, v8, v5
	v_min_f32_e32 v5, v8, v5
	v_max_f32_e32 v8, v0, v10
	v_min_f32_e32 v0, v0, v10
	v_max_f32_e32 v10, v1, v2
	v_min_f32_e32 v1, v1, v2
	v_max_f32_e32 v2, v6, v4
	v_min_f32_e32 v4, v6, v4
	v_max_f32_e32 v6, v11, v15
	v_min_f32_e32 v11, v11, v15
	v_max_f32_e32 v15, v13, v16
	v_max_f32_e32 v19, v7, v10
	v_min_f32_e32 v20, v7, v10
	v_max_f32_e32 v7, v8, v2
	v_min_f32_e32 v2, v8, v2
	v_max_f32_e32 v21, v5, v1
	v_min_f32_e32 v1, v5, v1
	v_max_f32_e32 v22, v0, v4
	v_min_f32_e32 v0, v0, v4
	v_min_f32_e32 v13, v13, v16
	v_max_f32_e32 v18, v9, v12
	v_min_f32_e32 v9, v9, v12
	v_max_f32_e32 v12, v14, v3
	v_min_f32_e32 v3, v14, v3
	v_max_f32_e32 v17, v6, v15
	v_min_f32_e32 v15, v6, v15
	v_max_f32_e32 v8, v20, v2
	v_min_f32_e32 v6, v20, v2
	v_max_f32_e32 v4, v1, v0
	v_min_f32_e32 v2, v1, v0
	v_lshlrev_b32_e32 v0, 7, v72
	v_max_f32_e32 v16, v11, v13
	v_min_f32_e32 v14, v11, v13
	v_max_f32_e32 v13, v18, v12
	v_min_f32_e32 v11, v18, v12
	v_max_f32_e32 v12, v9, v3
	v_min_f32_e32 v10, v9, v3
	v_max_f32_e32 v9, v19, v7
	v_min_f32_e32 v7, v19, v7
	v_max_f32_e32 v5, v21, v22
	v_min_f32_e32 v3, v21, v22
	v_ashrrev_i32_e32 v1, 31, v0
	s_and_saveexec_b64 s[10:11], s[36:37]
	s_xor_b64 s[10:11], exec, s[10:11]
	s_cbranch_execz .LBB0_919
; DI void route_block(const Frame& F, int t0, int t1) {
;     ...
;         int eidx[16]; float ev[16]; float den = 0.f;
;         const float mx = __uint_as_float(__float_as_uint(c[0]) & ~255u);
; #pragma unroll
;         for (int i = 0; i < 16; ++i) {
;             const unsigned bits = __float_as_uint(c[i]); const int pos = bits & 255u, ia = pos >> 4, ib = 16 + (pos & 15);
;             const unsigned wa = kl[(ia >> 2) * 64 + lane], wb = kl[(ib >> 2) * 64 + lane];
;             const int ka = (wa >> (8 * (ia & 3))) & 127, kb2 = (wb >> (8 * (ib & 3))) & 127;
;             eidx[i] = ka * 128 + kb2;
;             ev[i] = __expf(__uint_as_float(bits & ~255u) - mx); den += ev[i]; }
;         const float inv = 1.0f / den;
;         if (valid) {
;             if (hh == 0) {
; #pragma unroll
;                 for (int q = 0; q < 2; ++q) *(u32x4*)(RI + tl * 128 + h * 16 + q * 8) = (u32x4){(unsigned)eidx[q * 8] | ((unsigned)eidx[q * 8 + 1] << 16), (unsigned)eidx[q * 8 + 2] | ((unsigned)eidx[q * 8 + 3] << 16), (unsigned)eidx[q * 8 + 4] | ((unsigned)eidx[q * 8 + 5] << 16), (unsigned)eidx[q * 8 + 6] | ((unsigned)eidx[q * 8 + 7] << 16)};
;             } else {
; #pragma unroll
;                 for (int q = 0; q < 4; ++q) *(f32x4*)(RGl + tl * 128 + h * 16 + q * 4) = (f32x4){ev[q * 4] * inv, ev[q * 4 + 1] * inv, ev[q * 4 + 2] * inv, ev[q * 4 + 3] * inv};
	v_and_b32_e32 v20, 0xffffff00, v17
	v_and_b32_e32 v15, 0xffffff00, v15
	v_sub_f32_e32 v15, v15, v20
	v_sub_f32_e32 v17, v20, v20
	v_mul_f32_e32 v15, 0x3fb8aa3b, v15
	v_mul_f32_e32 v17, 0x3fb8aa3b, v17
	v_exp_f32_e32 v19, v15
	v_and_b32_e32 v15, 0xffffff00, v16
	v_exp_f32_e32 v18, v17
	v_sub_f32_e32 v15, v15, v20
	v_and_b32_e32 v14, 0xffffff00, v14
	v_mul_f32_e32 v15, 0x3fb8aa3b, v15
	v_sub_f32_e32 v14, v14, v20
	v_exp_f32_e32 v16, v15
	v_mul_f32_e32 v14, 0x3fb8aa3b, v14
	v_exp_f32_e32 v17, v14
	v_and_b32_e32 v11, 0xffffff00, v11
	v_add_f32_e32 v14, 0, v18
	v_and_b32_e32 v13, 0xffffff00, v13
	v_sub_f32_e32 v11, v11, v20
	v_add_f32_e32 v14, v19, v14
	v_sub_f32_e32 v13, v13, v20
	v_mul_f32_e32 v11, 0x3fb8aa3b, v11
	v_add_f32_e32 v14, v16, v14
	v_mul_f32_e32 v13, 0x3fb8aa3b, v13
	v_exp_f32_e32 v15, v11
	v_and_b32_e32 v11, 0xffffff00, v12
	v_add_f32_e32 v21, v17, v14
	v_exp_f32_e32 v14, v13
	v_sub_f32_e32 v11, v11, v20
	v_and_b32_e32 v10, 0xffffff00, v10
	v_mul_f32_e32 v11, 0x3fb8aa3b, v11
	v_sub_f32_e32 v10, v10, v20
	v_exp_f32_e32 v12, v11
	v_mul_f32_e32 v10, 0x3fb8aa3b, v10
	v_exp_f32_e32 v13, v10
	v_and_b32_e32 v7, 0xffffff00, v7
	v_add_f32_e32 v10, v14, v21
	v_and_b32_e32 v9, 0xffffff00, v9
	v_sub_f32_e32 v7, v7, v20
	v_add_f32_e32 v10, v15, v10
	v_sub_f32_e32 v9, v9, v20
	v_mul_f32_e32 v7, 0x3fb8aa3b, v7
	v_add_f32_e32 v10, v12, v10
	v_mul_f32_e32 v9, 0x3fb8aa3b, v9
	v_exp_f32_e32 v11, v7
	v_and_b32_e32 v7, 0xffffff00, v8
	v_add_f32_e32 v21, v13, v10
	v_exp_f32_e32 v10, v9
	v_sub_f32_e32 v7, v7, v20
	v_and_b32_e32 v6, 0xffffff00, v6
	v_mul_f32_e32 v7, 0x3fb8aa3b, v7
	v_sub_f32_e32 v6, v6, v20
	v_exp_f32_e32 v8, v7
	v_mul_f32_e32 v6, 0x3fb8aa3b, v6
	v_exp_f32_e32 v9, v6
	v_add_f32_e32 v6, v10, v21
	v_and_b32_e32 v5, 0xffffff00, v5
	v_add_f32_e32 v6, v11, v6
	v_sub_f32_e32 v5, v5, v20
	v_and_b32_e32 v3, 0xffffff00, v3
	v_add_f32_e32 v6, v8, v6
	v_mul_f32_e32 v5, 0x3fb8aa3b, v5
	v_and_b32_e32 v4, 0xffffff00, v4
	v_sub_f32_e32 v3, v3, v20
	v_add_f32_e32 v21, v9, v6
	v_exp_f32_e32 v6, v5
	v_sub_f32_e32 v4, v4, v20
	v_mul_f32_e32 v3, 0x3fb8aa3b, v3
	v_and_b32_e32 v2, 0xffffff00, v2
	v_mul_f32_e32 v4, 0x3fb8aa3b, v4
	v_exp_f32_e32 v7, v3
	v_sub_f32_e32 v2, v2, v20
	v_exp_f32_e32 v4, v4
	v_mul_f32_e32 v2, 0x3fb8aa3b, v2
	v_exp_f32_e32 v5, v2
	v_add_f32_e32 v2, v6, v21
	v_add_f32_e32 v2, v7, v2
	v_add_f32_e32 v2, v4, v2
	v_add_f32_e32 v2, v5, v2
	v_div_scale_f32 v3, s[16:17], v2, v2, 1.0
	v_rcp_f32_e32 v20, v3
	s_nop 0
	v_fma_f32 v21, -v3, v20, 1.0
	v_fmac_f32_e32 v20, v21, v20
	v_div_scale_f32 v21, vcc, 1.0, v2, 1.0
	v_mul_f32_e32 v22, v21, v20
	v_fma_f32 v23, -v3, v22, v21
	v_fmac_f32_e32 v22, v23, v20
	v_fma_f32 v3, -v3, v22, v21
	v_div_fmas_f32 v3, v3, v20, v22
	v_div_fixup_f32 v20, v3, v2, 1.0
	v_lshl_add_u64 v[22:23], v[0:1], 2, s[4:5]
	v_pk_mul_f32 v[2:3], v[16:17], v[20:21] op_sel_hi:[1,0]
	v_pk_mul_f32 v[0:1], v[18:19], v[20:21] op_sel_hi:[1,0]
	global_store_dwordx4 v[22:23], v[0:3], off
	s_nop 1
	v_pk_mul_f32 v[2:3], v[12:13], v[20:21] op_sel_hi:[1,0]
	v_pk_mul_f32 v[0:1], v[14:15], v[20:21] op_sel_hi:[1,0]
	global_store_dwordx4 v[22:23], v[0:3], off offset:16
	s_nop 1
	v_pk_mul_f32 v[2:3], v[8:9], v[20:21] op_sel_hi:[1,0]
	v_pk_mul_f32 v[0:1], v[10:11], v[20:21] op_sel_hi:[1,0]
	global_store_dwordx4 v[22:23], v[0:3], off offset:32
	s_nop 1
	v_pk_mul_f32 v[2:3], v[4:5], v[20:21] op_sel_hi:[1,0]
	v_pk_mul_f32 v[0:1], v[6:7], v[20:21] op_sel_hi:[1,0]
	global_store_dwordx4 v[22:23], v[0:3], off offset:48
